# prep phase wave sums: v_mov 0 + v_mov_dpp row_bcast + v_add replaced by one v_add_f32_dpp (instruction selection)
# speedup vs baseline: 1.0055x; 1.0026x over previous
; #define LAS __attribute__((address_space(3)))
; __device__ __forceinline__ void prep_phase(const Ctx& F, const float* mu, const float* w0, const float* a0, const float* k_k, const float* k_a, const float* r_k) {
;     ...
;         float muj[8];
;         { const f32x4 m0 = *(const f32x4*)(mu + 1536 + j0), m1 = *(const f32x4*)(mu + 1540 + j0); muj[0] = m0.x; muj[1] = m0.y; muj[2] = m0.z; muj[3] = m0.w; muj[4] = m1.x; muj[5] = m1.y; muj[6] = m1.z; muj[7] = m1.w; }
; #pragma unroll
;         for (int i = 0; i < 2; ++i) { const int tt = (F.tid >> 5) + 16 * i; const int tok = t0 + tt;
;             const u32x4 pc = *(const u32x4*)(PRW + (size_t)tok * PRWW + 1536 + j0);
;             u32x4 pp = {0u, 0u, 0u, 0u}; if ((tok & (SEQ - 1)) != 0) pp = *(const u32x4*)(PRW + (size_t)(tok - 1) * PRWW + 1536 + j0);
;             float x[8] = {bflo(pc.x), bfhi(pc.x), bflo(pc.y), bfhi(pc.y), bflo(pc.z), bfhi(pc.z), bflo(pc.w), bfhi(pc.w)};
;             const float xp[8] = {bflo(pp.x), bfhi(pp.x), bflo(pp.y), bfhi(pp.y), bflo(pp.z), bfhi(pp.z), bflo(pp.w), bfhi(pp.w)};
; #pragma unroll
;             for (int e = 0; e < 8; ++e) { const float xs = x[e] + (xp[e] - x[e]) * muj[e]; const float y = typ == 0 ? 2.f * xs : xs; const float sg = __builtin_amdgcn_rcpf(1.f + __expf(-y));
;                 x[e] = typ == 0 ? 2.f * sg - 1.f : (typ == 1 ? xs : sg); }
;             u32x4 o; o.x = pk2(x[0], x[1]); o.y = pk2(x[2], x[3]); o.z = pk2(x[4], x[5]); o.w = pk2(x[6], x[7]);
;             *(LAS u32x4*)(act + tt * AP + j0) = o; }
;         __syncthreads();
; #pragma unroll
;         for (int nt = 0; nt < 2; ++nt) {
;             f32x16 aD, aA, aG;
; #pragma unroll
;             for (int r = 0; r < 16; ++r) { aD[r] = 0.f; aA[r] = 0.f; aG[r] = 0.f; }
;             const unsigned n = head * 64 + nt * 32 + j; const unsigned wo = n * 64 + 8 * hi, wg = n * 128 + 8 * hi; const unsigned ao = j * AP + 8 * hi;
; #pragma unroll
;             for (int ks = 0; ks < 4; ++ks) {
;                 aD = MFMA32(*(const bf16x8*)(LWD + wo + ks * 16), *(const LAS bf16x8*)(act + ao + ks * 16), aD);
;                 aA = MFMA32(*(const bf16x8*)(LWA + wo + ks * 16), *(const LAS bf16x8*)(act + ao + (64 + ks * 16)), aA); }
; #pragma unroll
;             for (int ks = 0; ks < 8; ++ks)
;                 aG = MFMA32(*(const bf16x8*)(LWG + wg + ks * 16), *(const LAS bf16x8*)(act + ao + (128 + ks * 16)), aG);
.LBB0_528:
	s_or_b64 exec, exec, s[26:27]
	s_waitcnt vmcnt(0)
	v_cvt_f32_f16_e32 v18, v14
	v_cvt_f32_f16_e32 v20, v6
	v_cvt_f32_f16_sdwa v19, v14 dst_sel:DWORD dst_unused:UNUSED_PAD src0_sel:WORD_1
	v_cvt_f32_f16_sdwa v6, v6 dst_sel:DWORD dst_unused:UNUSED_PAD src0_sel:WORD_1
	v_add_u32_e32 v251, 0x4000, v165
	v_sub_f32_e32 v18, v20, v18
	v_fma_mix_f32 v10, v10, v18, v14 op_sel_hi:[0,0,1]
	v_add_f32_e32 v18, v10, v10
	v_cndmask_b32_e64 v18, v18, v10, s[10:11]
	v_mul_f32_e32 v18, 0xbfb8aa3b, v18
	v_exp_f32_e32 v18, v18
	v_sub_f32_e32 v6, v6, v19
	v_fma_mix_f32 v6, v11, v6, v14 op_sel:[0,0,1] op_sel_hi:[0,0,1]
	v_cvt_f32_f16_e32 v14, v7
	v_add_f32_e32 v18, 1.0, v18
	v_rcp_f32_e32 v18, v18
	v_add_u32_e32 v252, 0xc000, v165
	s_ashr_i32 s26, s33, 31
	s_lshr_b32 s26, s26, 25
	v_fma_f32 v20, v18, 2.0, -1.0
	v_cndmask_b32_e64 v10, v18, v10, s[4:5]
	v_cndmask_b32_e64 v18, v20, v10, s[10:11]
	v_add_f32_e32 v10, v6, v6
	v_cndmask_b32_e64 v10, v10, v6, s[10:11]
	v_mul_f32_e32 v10, 0xbfb8aa3b, v10
	v_exp_f32_e32 v10, v10
	s_add_i32 s26, s33, s26
	s_ashr_i32 s26, s26, 7
	s_lshl_b32 s26, s26, 3
	v_add_f32_e32 v10, 1.0, v10
	v_rcp_f32_e32 v10, v10
	s_add_i32 s26, s26, s86
	s_ashr_i32 s27, s26, 31
	v_fma_f32 v11, v10, 2.0, -1.0
	v_cndmask_b32_e64 v6, v10, v6, s[4:5]
	v_cndmask_b32_e64 v19, v11, v6, s[10:11]
	v_cvt_f32_f16_sdwa v11, v15 dst_sel:DWORD dst_unused:UNUSED_PAD src0_sel:WORD_1
	v_cvt_f32_f16_e32 v10, v15
	v_cvt_f32_f16_sdwa v15, v7 dst_sel:DWORD dst_unused:UNUSED_PAD src0_sel:WORD_1
	v_pk_add_f32 v[6:7], v[14:15], v[10:11] neg_lo:[0,1] neg_hi:[0,1]
	s_nop 0
	v_pk_fma_f32 v[6:7], v[12:13], v[6:7], v[10:11]
	s_nop 0
	v_add_f32_e32 v10, v6, v6
	v_add_f32_e32 v11, v7, v7
	v_cndmask_b32_e64 v10, v10, v6, s[10:11]
	v_cndmask_b32_e64 v11, v11, v7, s[10:11]
	v_mul_f32_e32 v10, 0xbfb8aa3b, v10
	v_mul_f32_e32 v11, 0xbfb8aa3b, v11
	v_exp_f32_e32 v10, v10
	v_exp_f32_e32 v11, v11
	v_add_f32_e32 v10, 1.0, v10
	v_add_f32_e32 v11, 1.0, v11
	v_rcp_f32_e32 v10, v10
	v_rcp_f32_e32 v11, v11
	v_cndmask_b32_e64 v6, v10, v6, s[4:5]
	v_pk_fma_f32 v[12:13], v[10:11], 2.0, -1.0 op_sel_hi:[1,0,0]
	v_cndmask_b32_e64 v7, v11, v7, s[4:5]
	v_cndmask_b32_e64 v13, v13, v7, s[10:11]
	v_cndmask_b32_e64 v12, v12, v6, s[10:11]
	v_cvt_f32_f16_sdwa v7, v16 dst_sel:DWORD dst_unused:UNUSED_PAD src0_sel:WORD_1
	v_cvt_f32_f16_e32 v6, v16
	v_cvt_f32_f16_sdwa v11, v8 dst_sel:DWORD dst_unused:UNUSED_PAD src0_sel:WORD_1
	v_cvt_f32_f16_e32 v10, v8
	v_pk_add_f32 v[10:11], v[10:11], v[6:7] neg_lo:[0,1] neg_hi:[0,1]
	s_nop 0
	v_pk_fma_f32 v[2:3], v[2:3], v[10:11], v[6:7]
	s_nop 0
	v_add_f32_e32 v6, v2, v2
	v_add_f32_e32 v7, v3, v3
	v_cndmask_b32_e64 v6, v6, v2, s[10:11]
	v_cndmask_b32_e64 v7, v7, v3, s[10:11]
	v_mul_f32_e32 v6, 0xbfb8aa3b, v6
	v_mul_f32_e32 v7, 0xbfb8aa3b, v7
	v_exp_f32_e32 v6, v6
	v_exp_f32_e32 v7, v7
	v_add_f32_e32 v6, 1.0, v6
	v_add_f32_e32 v7, 1.0, v7
	v_rcp_f32_e32 v6, v6
	v_rcp_f32_e32 v7, v7
	v_cndmask_b32_e64 v2, v6, v2, s[4:5]
	v_pk_fma_f32 v[10:11], v[6:7], 2.0, -1.0 op_sel_hi:[1,0,0]
	v_cndmask_b32_e64 v3, v7, v3, s[4:5]
	v_cndmask_b32_e64 v8, v11, v3, s[10:11]
	v_cndmask_b32_e64 v10, v10, v2, s[10:11]
	v_cvt_f32_f16_sdwa v3, v17 dst_sel:DWORD dst_unused:UNUSED_PAD src0_sel:WORD_1
	v_cvt_f32_f16_e32 v2, v17
	v_cvt_f32_f16_sdwa v7, v9 dst_sel:DWORD dst_unused:UNUSED_PAD src0_sel:WORD_1
	v_cvt_f32_f16_e32 v6, v9
	v_pk_add_f32 v[6:7], v[6:7], v[2:3] neg_lo:[0,1] neg_hi:[0,1]
	s_nop 0
	v_pk_fma_f32 v[2:3], v[4:5], v[6:7], v[2:3]
	s_nop 0
	v_add_f32_e32 v4, v2, v2
	v_add_f32_e32 v5, v3, v3
	v_cndmask_b32_e64 v4, v4, v2, s[10:11]
	v_cndmask_b32_e64 v5, v5, v3, s[10:11]
	v_mul_f32_e32 v4, 0xbfb8aa3b, v4
	v_mul_f32_e32 v5, 0xbfb8aa3b, v5
	v_exp_f32_e32 v4, v4
	v_exp_f32_e32 v5, v5
	v_add_f32_e32 v4, 1.0, v4
	v_add_f32_e32 v5, 1.0, v5
	v_rcp_f32_e32 v4, v4
	v_rcp_f32_e32 v5, v5
	v_cndmask_b32_e64 v2, v4, v2, s[4:5]
	v_pk_fma_f32 v[6:7], v[4:5], 2.0, -1.0 op_sel_hi:[1,0,0]
	v_cndmask_b32_e64 v3, v5, v3, s[4:5]
	v_cndmask_b32_e64 v5, v7, v3, s[10:11]
	v_cndmask_b32_e64 v6, v6, v2, s[10:11]
	v_cvt_pk_f16_f32 v2, v18, v19
	v_cvt_pk_f16_f32 v3, v12, v13
	v_cvt_pk_f16_f32 v4, v10, v8
	v_cvt_pk_f16_f32 v5, v6, v5
	ds_write_b128 v227, v[2:5] offset:8448
	s_waitcnt lgkmcnt(0)
	s_barrier
	global_load_dwordx4 v[18:21], v[142:143], off
	global_load_dwordx4 v[34:37], v[144:145], off
	ds_read_b128 v[74:77], v159 offset:128
	global_load_dwordx4 v[94:97], v[142:143], off offset:32
	ds_read_b128 v[78:81], v159
	ds_read_b128 v[70:73], v159 offset:32
	global_load_dwordx4 v[134:137], v[144:145], off offset:96
	global_load_dwordx4 v[2:5], v[146:147], off
	global_load_dwordx4 v[22:25], v[146:147], off offset:32
	ds_read_b128 v[50:53], v159 offset:224
	ds_read_b128 v[98:101], v159 offset:256
	ds_read_b128 v[102:105], v159 offset:288
	ds_read_b128 v[110:113], v159 offset:320
	ds_read_b128 v[114:117], v159 offset:352
	ds_read_b128 v[106:109], v159 offset:384
	ds_read_b128 v[90:93], v159 offset:416
	ds_read_b128 v[86:89], v159 offset:448
	global_load_dwordx4 v[118:121], v[144:145], off offset:32
	global_load_dwordx4 v[126:129], v[144:145], off offset:64
	global_load_dwordx4 v[122:125], v[142:143], off offset:64
	global_load_dwordx4 v[130:133], v[142:143], off offset:96
	ds_read_b128 v[82:85], v159 offset:480
	ds_read_b128 v[66:69], v159 offset:160
	ds_read_b128 v[58:61], v159 offset:192
	ds_read_b128 v[62:65], v159 offset:64
	ds_read_b128 v[54:57], v159 offset:96
	s_waitcnt vmcnt(8) lgkmcnt(14)
	v_mfma_f32_32x32x16_f16 v[34:49], v[34:37], v[74:77], 0
	s_waitcnt vmcnt(5) lgkmcnt(11)
	v_mfma_f32_32x32x16_f16 v[2:17], v[2:5], v[98:101], 0
	s_waitcnt vmcnt(4) lgkmcnt(10)
; #define LAS __attribute__((address_space(3)))
; #define MFMA32(a, b, c) __builtin_amdgcn_mfma_f32_32x32x16_f16(H8(a), H8(b), (c), 0, 0, 0)
; __device__ __forceinline__ u32x2 pack4(f32x4 v) { u32x2 o; o.x = pk2(v.x, v.y); o.y = pk2(v.z, v.w); return o; }
; __device__ __forceinline__ void prep_phase(const Ctx& F, const float* mu, const float* w0, const float* a0, const float* k_k, const float* k_a, const float* r_k) {
;     ...
;         for (int nt = 0; nt < 2; ++nt) {
;             f32x16 aD, aA, aG;
; #pragma unroll
;             for (int r = 0; r < 16; ++r) { aD[r] = 0.f; aA[r] = 0.f; aG[r] = 0.f; }
;             const unsigned n = head * 64 + nt * 32 + j; const unsigned wo = n * 64 + 8 * hi, wg = n * 128 + 8 * hi; const unsigned ao = j * AP + 8 * hi;
; #pragma unroll
;             for (int ks = 0; ks < 4; ++ks) {
;                 aD = MFMA32(*(const bf16x8*)(LWD + wo + ks * 16), *(const LAS bf16x8*)(act + ao + ks * 16), aD);
;                 aA = MFMA32(*(const bf16x8*)(LWA + wo + ks * 16), *(const LAS bf16x8*)(act + ao + (64 + ks * 16)), aA); }
; #pragma unroll
;             for (int ks = 0; ks < 8; ++ks)
;                 aG = MFMA32(*(const bf16x8*)(LWG + wg + ks * 16), *(const LAS bf16x8*)(act + ao + (128 + ks * 16)), aG);
;             LAS bf16* ob = outs + j * OP + head * 64 + nt * 32 + 4 * hi;
; #pragma unroll
;             for (int q = 0; q < 4; ++q) {
;                 *(LAS u32x2*)(ob + 8 * q) = pack4((f32x4){aD[4 * q], aD[4 * q + 1], aD[4 * q + 2], aD[4 * q + 3]});
;                 *(LAS u32x2*)(ob + 32 * OP + 8 * q) = pack4((f32x4){aA[4 * q], aA[4 * q + 1], aA[4 * q + 2], aA[4 * q + 3]});
;                 *(LAS u32x2*)(ob + 64 * OP + 8 * q) = pack4((f32x4){aG[4 * q], aG[4 * q + 1], aG[4 * q + 2], aG[4 * q + 3]}); }
;         }
;         __syncthreads();
	v_mfma_f32_32x32x16_f16 v[2:17], v[22:25], v[102:105], v[2:17]
	global_load_dwordx4 v[22:25], v[146:147], off offset:64
	s_waitcnt vmcnt(4) lgkmcnt(3)
	v_mfma_f32_32x32x16_f16 v[34:49], v[118:121], v[66:69], v[34:49]
	s_waitcnt vmcnt(3) lgkmcnt(2)
	v_mfma_f32_32x32x16_f16 v[34:49], v[126:129], v[58:61], v[34:49]
	v_mfma_f32_32x32x16_f16 v[34:49], v[134:137], v[50:53], v[34:49]
	global_load_dwordx4 v[118:121], v[146:147], off offset:96
	global_load_dwordx4 v[126:129], v[146:147], off offset:128
	global_load_dwordx4 v[134:137], v[146:147], off offset:160
	s_waitcnt vmcnt(3)
	v_mfma_f32_32x32x16_f16 v[2:17], v[22:25], v[110:113], v[2:17]
	global_load_dwordx4 v[22:25], v[146:147], off offset:192
	s_waitcnt vmcnt(3)
	v_mfma_f32_32x32x16_f16 v[2:17], v[118:121], v[114:117], v[2:17]
	global_load_dwordx4 v[118:121], v[146:147], off offset:224
	s_waitcnt vmcnt(3)
	v_mfma_f32_32x32x16_f16 v[2:17], v[126:129], v[106:109], v[2:17]
	s_waitcnt vmcnt(2)
	v_mfma_f32_32x32x16_f16 v[2:17], v[134:137], v[90:93], v[2:17]
	s_waitcnt vmcnt(1)
	v_mfma_f32_32x32x16_f16 v[2:17], v[22:25], v[86:89], v[2:17]
	s_waitcnt vmcnt(0)
	v_mfma_f32_32x32x16_f16 v[2:17], v[118:121], v[82:85], v[2:17]
	s_nop 11
	v_cvt_pk_f16_f32 v2, v2, v3
	v_mfma_f32_32x32x16_f16 v[18:33], v[18:21], v[78:81], 0
	v_cvt_pk_f16_f32 v3, v4, v5
	ds_write_b64 v166, v[2:3]
	v_cvt_pk_f16_f32 v4, v42, v43
	v_cvt_pk_f16_f32 v5, v44, v45
	v_mfma_f32_32x32x16_f16 v[18:33], v[94:97], v[70:73], v[18:33]
	s_waitcnt lgkmcnt(2)
	v_mfma_f32_32x32x16_f16 v[18:33], v[122:125], v[62:65], v[18:33]
	s_waitcnt lgkmcnt(1)
	v_mfma_f32_32x32x16_f16 v[18:33], v[130:133], v[54:57], v[18:33]
	s_nop 11
	v_cvt_pk_f16_f32 v18, v18, v19
	v_cvt_pk_f16_f32 v19, v20, v21
	v_cvt_pk_f16_f32 v2, v22, v23
	v_cvt_pk_f16_f32 v3, v24, v25
	v_cvt_pk_f16_f32 v20, v34, v35
	v_cvt_pk_f16_f32 v21, v36, v37
	ds_write2_b64 v251, v[18:19], v[2:3] offset0:64 offset1:66
	v_cvt_pk_f16_f32 v2, v38, v39
	v_cvt_pk_f16_f32 v3, v40, v41
	ds_write2_b64 v252, v[20:21], v[2:3] offset0:128 offset1:130
	v_cvt_pk_f16_f32 v2, v6, v7
	v_cvt_pk_f16_f32 v3, v8, v9
	v_cvt_pk_f16_f32 v6, v10, v11
	v_cvt_pk_f16_f32 v7, v12, v13
	ds_write_b64 v167, v[2:3]
	v_cvt_pk_f16_f32 v2, v26, v27
	v_cvt_pk_f16_f32 v3, v28, v29
	ds_write_b64 v168, v[6:7]
	v_cvt_pk_f16_f32 v6, v30, v31
	v_cvt_pk_f16_f32 v7, v32, v33
	ds_write2_b64 v251, v[2:3], v[6:7] offset0:68 offset1:70
	v_cvt_pk_f16_f32 v2, v46, v47
	v_cvt_pk_f16_f32 v3, v48, v49
	ds_write2_b64 v252, v[4:5], v[2:3] offset0:132 offset1:134
	v_cvt_pk_f16_f32 v2, v14, v15
	v_cvt_pk_f16_f32 v3, v16, v17
	ds_write_b64 v169, v[2:3]
	global_load_dwordx4 v[22:25], v[148:149], off
	global_load_dwordx4 v[18:21], v[150:151], off
	global_load_dwordx4 v[134:137], v[148:149], off offset:32
	global_load_dwordx4 v[130:133], v[150:151], off offset:32
	global_load_dwordx4 v[126:129], v[148:149], off offset:64
	global_load_dwordx4 v[122:125], v[150:151], off offset:64
	global_load_dwordx4 v[118:121], v[148:149], off offset:96
	global_load_dwordx4 v[94:97], v[150:151], off offset:96
	global_load_dwordx4 v[2:5], v[152:153], off
	global_load_dwordx4 v[26:29], v[152:153], off offset:32
	global_load_dwordx4 v[30:33], v[152:153], off offset:64
	global_load_dwordx4 v[34:37], v[152:153], off offset:96
	global_load_dwordx4 v[38:41], v[152:153], off offset:128
	global_load_dwordx4 v[42:45], v[152:153], off offset:160
	global_load_dwordx4 v[46:49], v[152:153], off offset:192
	s_waitcnt vmcnt(6)
	v_mfma_f32_32x32x16_f16 v[2:17], v[2:5], v[98:101], 0
	s_waitcnt vmcnt(5)
	v_mfma_f32_32x32x16_f16 v[2:17], v[26:29], v[102:105], v[2:17]
	global_load_dwordx4 v[26:29], v[152:153], off offset:224
	s_waitcnt vmcnt(5)
	v_mfma_f32_32x32x16_f16 v[2:17], v[30:33], v[110:113], v[2:17]
	s_waitcnt vmcnt(4)
	v_mfma_f32_32x32x16_f16 v[2:17], v[34:37], v[114:117], v[2:17]
	s_waitcnt vmcnt(3)
	v_mfma_f32_32x32x16_f16 v[2:17], v[38:41], v[106:109], v[2:17]
	s_waitcnt vmcnt(2)
	v_mfma_f32_32x32x16_f16 v[2:17], v[42:45], v[90:93], v[2:17]
	s_waitcnt vmcnt(1)
	v_mfma_f32_32x32x16_f16 v[2:17], v[46:49], v[86:89], v[2:17]
	s_waitcnt vmcnt(0)
	v_mfma_f32_32x32x16_f16 v[2:17], v[26:29], v[82:85], v[2:17]
	v_mfma_f32_32x32x16_f16 v[34:49], v[22:25], v[78:81], 0
	s_nop 11
	v_cvt_pk_f16_f32 v2, v2, v3
	v_mfma_f32_32x32x16_f16 v[18:33], v[18:21], v[74:77], 0
	v_cvt_pk_f16_f32 v3, v4, v5
	ds_write_b64 v138, v[2:3]
	v_mfma_f32_32x32x16_f16 v[34:49], v[134:137], v[70:73], v[34:49]
	v_mfma_f32_32x32x16_f16 v[18:33], v[130:133], v[66:69], v[18:33]
	v_mfma_f32_32x32x16_f16 v[34:49], v[126:129], v[62:65], v[34:49]
	v_mfma_f32_32x32x16_f16 v[18:33], v[122:125], v[58:61], v[18:33]
	v_mfma_f32_32x32x16_f16 v[34:49], v[118:121], v[54:57], v[34:49]
	v_mfma_f32_32x32x16_f16 v[18:33], v[94:97], v[50:53], v[18:33]
	s_nop 10
	v_cvt_pk_f16_f32 v34, v34, v35
	v_cvt_pk_f16_f32 v35, v36, v37
	v_cvt_pk_f16_f32 v2, v38, v39
	v_cvt_pk_f16_f32 v3, v40, v41
	ds_write2_b64 v251, v[34:35], v[2:3] offset0:72 offset1:74
	v_cvt_pk_f16_f32 v18, v18, v19
	v_cvt_pk_f16_f32 v19, v20, v21
	v_cvt_pk_f16_f32 v2, v22, v23
	v_cvt_pk_f16_f32 v3, v24, v25
	ds_write2_b64 v252, v[18:19], v[2:3] offset0:136 offset1:138
	v_cvt_pk_f16_f32 v2, v6, v7
	v_cvt_pk_f16_f32 v3, v8, v9
	v_cvt_pk_f16_f32 v6, v10, v11
	v_cvt_pk_f16_f32 v7, v12, v13
	v_cvt_f32_f16_e32 v11, v250
	ds_write_b64 v172, v[2:3]
	v_cvt_pk_f16_f32 v2, v42, v43
	v_cvt_pk_f16_f32 v3, v44, v45
	ds_write_b64 v173, v[6:7]
	v_cvt_pk_f16_f32 v6, v46, v47
	v_cvt_pk_f16_f32 v7, v48, v49
	v_cvt_f32_f16_e32 v12, v249
	v_cvt_pk_f16_f32 v4, v26, v27
	v_cvt_pk_f16_f32 v5, v28, v29
	ds_write2_b64 v251, v[2:3], v[6:7] offset0:76 offset1:78
	v_cvt_pk_f16_f32 v2, v30, v31
	v_cvt_pk_f16_f32 v3, v32, v33
	ds_write2_b64 v252, v[4:5], v[2:3] offset0:140 offset1:142
	v_cvt_pk_f16_f32 v2, v14, v15
	v_cvt_pk_f16_f32 v3, v16, v17
	v_add_u32_e32 v4, 0x5c00, v229
	v_add_u32_e32 v6, 0x5400, v229
	ds_write_b64 v174, v[2:3]
	s_waitcnt lgkmcnt(0)
	s_barrier
; __device__ __forceinline__ bf16 f2bf(float f) { return (bf16)(pk2(f, 0.f) & 0xffffu); }
; __device__ __forceinline__ float wave_sum_d(float v) {
;     v = row16_sum(v);
;     v += __builtin_bit_cast(float, __builtin_amdgcn_update_dpp(0, __builtin_bit_cast(int, v), 0x142, 0xa, 0xf, false));
;     v += __builtin_bit_cast(float, __builtin_amdgcn_update_dpp(0, __builtin_bit_cast(int, v), 0x143, 0xc, 0xf, false));
;     return __builtin_bit_cast(float, __builtin_amdgcn_readlane(__builtin_bit_cast(int, v), 63));
; }
; __device__ __forceinline__ void prep_phase(const Ctx& F, const float* mu, const float* w0, const float* a0, const float* k_k, const float* k_a, const float* r_k) {
;     ...
;         for (int t = 0; t < 32; ++t) {
;             if (t + 6 < 32) { rin[t + 7] = PRL((t + 6) * PRWW); kin[t + 7] = PRL((t + 6) * PRWW + 512); vin[t + 7] = PRL((t + 6) * PRWW + 1024); }
;             asm volatile("" ::: "memory");
;             const float rc = bf2f(rin[t + 1]), kc = bf2f(kin[t + 1]), vc = bf2f(vin[t + 1]), rp = bf2f(rin[t]), kp = bf2f(kin[t]), vp = bf2f(vin[t]);
;             const float r = rc + (rp - rc) * mur, kx = kc + (kp - kc) * muk, vx = vc + (vp - vc) * muv;
;             const float ld = bf2f(outs[t * OP + c]), la = bf2f(outs[32 * OP + t * OP + c]), g = bf2f(outs[64 * OP + t * OP + c]);
;             const float een = -0.87504979f * __builtin_amdgcn_rcpf(1.f + __builtin_amdgcn_exp2f(w0n - 1.44269504f * ld));
;             const float omw = 1.f - __builtin_amdgcn_exp2f(een);
;             const float a = __builtin_amdgcn_rcpf(1.f + __builtin_amdgcn_exp2f(a0n - 1.44269504f * la));
;             const float kkv = kx * kkc; const float n2 = wave_sum_d(kkv * kkv); const float kk = kkv * __builtin_amdgcn_rsqf(fmaxf(n2, 1e-24f));
;             const float kmod = kx * (1.f + (a - 1.f) * kac); const float bb = kk * a;
;             float s_kr = kmod * r, s_bs = s_kr * rkc, s_br = bb * r;
;             wave_sum3(s_kr, s_bs, s_br, lane);
;             const float wr = (1.f - omw) * r - s_br * kk;
;             const unsigned o = ob0 + t * 128u;
;             ST16(SWR, o, f2bf(wr)); ST16(SC, o, f2bf(omw)); ST16(SK, o, f2bf(kmod)); ST16(SV, o, f2bf(vx)); ST16(SKK, o, f2bf(kk)); ST16(SB, o, f2bf(bb));
;             ST16(GG, gb0 + t * 1024u, f2bf(g));
;             if (lane == 0) *(f32x2*)(SCAL + ((size_t)bh * SEQ + pos0 + t) * 2) = (f32x2){s_kr, s_bs};
	v_add_u32_e32 v5, 0x5800, v229
	global_load_ushort v8, v6, s[12:13]
	global_load_ushort v7, v5, s[12:13]
	s_nop 0
	global_load_ushort v6, v4, s[12:13]
	v_sub_f32_e32 v4, v246, v11
	v_fma_mix_f32 v9, v161, v4, v250 op_sel_hi:[0,0,1]
	v_sub_f32_e32 v4, v247, v12
	v_fma_mix_f32 v13, v160, v4, v249 op_sel_hi:[0,0,1]
	ds_read_u16 v4, v176 offset:16896
	ds_read_u16 v5, v176 offset:50176
	ds_read_u16 v15, v177
	v_mul_f32_e32 v18, v1, v13
	v_lshl_or_b32 v2, s28, 7, v175
	s_waitcnt lgkmcnt(2)
	v_fma_mix_f32 v4, v4, s31, v170 op_sel_hi:[1,0,0]
	v_lshl_or_b32 v3, s26, 19, v2
	v_exp_f32_e32 v4, v4
	s_lshl_b64 s[26:27], s[26:27], 12
	s_or_b32 s26, s26, s28
	v_cvt_f32_f16_e32 v10, v245
	v_add_f32_e32 v4, 1.0, v4
	v_rcp_f32_e32 v4, v4
	v_add_u32_e32 v2, s38, v158
	v_sub_f32_e32 v14, v248, v10
	v_mul_f32_e32 v4, 0xbf600343, v4
	v_exp_f32_e32 v4, v4
	s_nop 0
	v_sub_f32_e32 v16, 1.0, v4
	s_waitcnt lgkmcnt(1)
	v_fma_mix_f32 v4, v5, s31, v171 op_sel_hi:[1,0,0]
	v_mov_b32_e32 v5, 0
	v_exp_f32_e32 v4, v4
	s_nop 0
	v_add_f32_e32 v4, 1.0, v4
	v_rcp_f32_e32 v17, v4
	v_mul_f32_e32 v4, v18, v18
	s_nop 1
	v_mov_b32_dpp v5, v4 quad_perm:[1,0,3,2] row_mask:0xf bank_mask:0xf
	v_fmac_f32_e32 v5, v18, v18
	s_nop 1
	v_add_f32_dpp v4, v5, v5 quad_perm:[2,3,0,1] row_mask:0xf bank_mask:0xf bound_ctrl:1
	s_nop 0
	s_nop 0
	v_add_f32_dpp v4, v4, v4 row_half_mirror row_mask:0xf bank_mask:0xf bound_ctrl:1
	s_nop 1
	v_add_f32_dpp v4, v4, v4 row_mirror row_mask:0xf bank_mask:0xf bound_ctrl:1
	s_nop 1
	v_add_f32_dpp v4, v4, v4 row_bcast:15 row_mask:0xa bank_mask:0xf
	s_nop 1
	v_add_f32_dpp v4, v4, v4 row_bcast:31 row_mask:0xc bank_mask:0xf
	s_nop 0
	v_readlane_b32 s28, v4, 63
	s_nop 1
	v_max_f32_e64 v4, s28, s28
	v_max_f32_e32 v4, 0x179abe15, v4
	v_rsq_f32_e32 v19, v4
	v_add_f32_e32 v4, -1.0, v17
	v_fma_f32 v21, v156, v4, 1.0
	v_mul_f32_e32 v4, v13, v21
	v_mul_f32_e32 v20, v18, v19
	v_mul_f32_e32 v5, v17, v20
	v_mul_f32_e32 v4, v9, v4
	v_mul_f32_e32 v22, v157, v4
	v_mul_f32_e32 v5, v9, v5
	v_cndmask_b32_e64 v23, v5, v4, s[6:7]
	v_cndmask_b32_e64 v4, v4, v5, s[6:7]
	v_cndmask_b32_e64 v5, 0, v22, s[6:7]
	v_cndmask_b32_e64 v22, v22, 0, s[6:7]
	v_add_f32_dpp v4, v4, v23 quad_perm:[1,0,3,2] row_mask:0xf bank_mask:0xf bound_ctrl:1
	s_nop 0
	v_add_f32_dpp v5, v22, v5 quad_perm:[1,0,3,2] row_mask:0xf bank_mask:0xf bound_ctrl:1
	v_cndmask_b32_e64 v22, v5, v4, s[8:9]
	v_cndmask_b32_e64 v4, v4, v5, s[8:9]
	s_nop 1
	v_add_f32_dpp v4, v4, v22 quad_perm:[2,3,0,1] row_mask:0xf bank_mask:0xf bound_ctrl:1
	v_and_b32_e32 v22, 64, v228
	v_add_u32_e32 v22, 64, v22
	v_add_f32_dpp v4, v4, v4 row_ror:4 row_mask:0xf bank_mask:0xf bound_ctrl:1
	s_nop 1
	v_add_f32_dpp v5, v4, v4 row_ror:8 row_mask:0xf bank_mask:0xf bound_ctrl:1
	v_xor_b32_e32 v4, 16, v228
	v_cmp_lt_i32_e32 vcc, v4, v22
	s_nop 1
	v_cndmask_b32_e32 v4, v228, v4, vcc
	v_lshlrev_b32_e32 v4, 2, v4
	ds_bpermute_b32 v23, v4, v5
	s_waitcnt lgkmcnt(0)
	v_add_f32_e32 v23, v5, v23
	v_xor_b32_e32 v5, 32, v228
	v_cmp_lt_i32_e32 vcc, v5, v22
	s_nop 1
	v_cndmask_b32_e32 v5, v228, v5, vcc
	v_lshlrev_b32_e32 v5, 2, v5
	ds_bpermute_b32 v22, v5, v23
	s_waitcnt lgkmcnt(0)
	v_add_f32_e32 v22, v23, v22
	s_nop 0
	v_readlane_b32 s28, v22, 1
	v_readlane_b32 s42, v22, 0
	v_readlane_b32 s43, v22, 2
	v_sub_f32_e32 v22, 1.0, v16
	v_mul_f32_e32 v23, s28, v20
	v_fma_mixlo_f16 v9, v9, v22, -v23
	global_store_short v3, v9, s[66:67]
	v_cvt_f16_f32_e32 v9, v16
	global_store_short v3, v9, s[14:15]
	v_fma_mixlo_f16 v9, v13, v21, 0
	global_store_short v3, v9, s[16:17]
	v_fma_mixlo_f16 v9, v164, v14, v245 op_sel_hi:[0,0,1]
	global_store_short v3, v9, s[18:19]
	v_fma_mixlo_f16 v9, v18, v19, 0
	global_store_short v3, v9, s[20:21]
	v_fma_mixlo_f16 v9, v17, v20, 0
	global_store_short v3, v9, s[22:23]
	global_store_short v2, v15, s[24:25]
	s_and_saveexec_b64 s[28:29], s[2:3]
	s_cbranch_execz .LBB0_530
	s_lshl_b64 s[44:45], s[26:27], 3
	s_add_u32 s44, s34, s44
	s_addc_u32 s45, s35, s45
	v_mov_b32_e32 v14, s42
	v_mov_b32_e32 v15, s43
	global_store_dwordx2 v139, v[14:15], s[44:45]
.LBB0_530:
	s_or_b64 exec, exec, s[28:29]
	v_add_u32_e32 v9, 0x6200, v229
	v_add_u32_e32 v13, 0x6600, v229
	v_add_u32_e32 v14, 0x6a00, v229
	global_load_ushort v22, v9, s[12:13]
	global_load_ushort v15, v13, s[12:13]
	s_nop 0
	global_load_ushort v9, v14, s[12:13]
	v_cvt_f32_f16_e32 v14, v244
	v_cvt_f32_f16_e32 v13, v243
	ds_read_u16 v16, v178
	ds_read_u16 v17, v176 offset:51216
	ds_read_u16 v18, v176 offset:17936
	v_sub_f32_e32 v11, v11, v14
	v_fma_mix_f32 v19, v161, v11, v244 op_sel_hi:[0,0,1]
	v_sub_f32_e32 v11, v12, v13
	s_waitcnt lgkmcnt(1)
	v_fma_mix_f32 v12, v17, s31, v171 op_sel_hi:[1,0,0]
	v_fma_mix_f32 v17, v160, v11, v243 op_sel_hi:[0,0,1]
	s_waitcnt lgkmcnt(0)
; __device__ __forceinline__ bf16 f2bf(float f) { return (bf16)(pk2(f, 0.f) & 0xffffu); }
; __device__ __forceinline__ float wave_sum_d(float v) {
;     v = row16_sum(v);
;     v += __builtin_bit_cast(float, __builtin_amdgcn_update_dpp(0, __builtin_bit_cast(int, v), 0x142, 0xa, 0xf, false));
;     v += __builtin_bit_cast(float, __builtin_amdgcn_update_dpp(0, __builtin_bit_cast(int, v), 0x143, 0xc, 0xf, false));
;     return __builtin_bit_cast(float, __builtin_amdgcn_readlane(__builtin_bit_cast(int, v), 63));
; }
; __device__ __forceinline__ void prep_phase(const Ctx& F, const float* mu, const float* w0, const float* a0, const float* k_k, const float* k_a, const float* r_k) {
;     ...
;             if (t + 6 < 32) { rin[t + 7] = PRL((t + 6) * PRWW); kin[t + 7] = PRL((t + 6) * PRWW + 512); vin[t + 7] = PRL((t + 6) * PRWW + 1024); }
;             asm volatile("" ::: "memory");
;             const float rc = bf2f(rin[t + 1]), kc = bf2f(kin[t + 1]), vc = bf2f(vin[t + 1]), rp = bf2f(rin[t]), kp = bf2f(kin[t]), vp = bf2f(vin[t]);
;             const float r = rc + (rp - rc) * mur, kx = kc + (kp - kc) * muk, vx = vc + (vp - vc) * muv;
;             const float ld = bf2f(outs[t * OP + c]), la = bf2f(outs[32 * OP + t * OP + c]), g = bf2f(outs[64 * OP + t * OP + c]);
;             const float een = -0.87504979f * __builtin_amdgcn_rcpf(1.f + __builtin_amdgcn_exp2f(w0n - 1.44269504f * ld));
;             const float omw = 1.f - __builtin_amdgcn_exp2f(een);
;             const float a = __builtin_amdgcn_rcpf(1.f + __builtin_amdgcn_exp2f(a0n - 1.44269504f * la));
;             const float kkv = kx * kkc; const float n2 = wave_sum_d(kkv * kkv); const float kk = kkv * __builtin_amdgcn_rsqf(fmaxf(n2, 1e-24f));
;             const float kmod = kx * (1.f + (a - 1.f) * kac); const float bb = kk * a;
;             float s_kr = kmod * r, s_bs = s_kr * rkc, s_br = bb * r;
;             wave_sum3(s_kr, s_bs, s_br, lane);
;             const float wr = (1.f - omw) * r - s_br * kk;
;             const unsigned o = ob0 + t * 128u;
;             ST16(SWR, o, f2bf(wr)); ST16(SC, o, f2bf(omw)); ST16(SK, o, f2bf(kmod)); ST16(SV, o, f2bf(vx)); ST16(SKK, o, f2bf(kk)); ST16(SB, o, f2bf(bb));
;             ST16(GG, gb0 + t * 1024u, f2bf(g));
;             if (lane == 0) *(f32x2*)(SCAL + ((size_t)bh * SEQ + pos0 + t) * 2) = (f32x2){s_kr, s_bs};
	v_fma_mix_f32 v11, v18, s31, v170 op_sel_hi:[1,0,0]
	v_mul_f32_e32 v18, v1, v17
	v_mul_f32_e32 v20, v18, v18
	v_mov_b32_e32 v21, 0
	v_exp_f32_e32 v12, v12
	v_exp_f32_e32 v11, v11
	v_mov_b32_dpp v21, v20 quad_perm:[1,0,3,2] row_mask:0xf bank_mask:0xf
	v_fmac_f32_e32 v21, v18, v18
	v_add_f32_e32 v12, 1.0, v12
	v_rcp_f32_e32 v12, v12
	v_add_f32_dpp v20, v21, v21 quad_perm:[2,3,0,1] row_mask:0xf bank_mask:0xf bound_ctrl:1
	v_add_f32_e32 v11, 1.0, v11
	s_nop 0
	v_add_f32_dpp v20, v20, v20 row_half_mirror row_mask:0xf bank_mask:0xf bound_ctrl:1
	s_nop 1
	v_add_f32_dpp v20, v20, v20 row_mirror row_mask:0xf bank_mask:0xf bound_ctrl:1
	s_nop 1
	v_add_f32_dpp v20, v20, v20 row_bcast:15 row_mask:0xa bank_mask:0xf
	s_nop 1
	v_add_f32_dpp v20, v20, v20 row_bcast:31 row_mask:0xc bank_mask:0xf
	v_rcp_f32_e32 v21, v11
	v_readlane_b32 s28, v20, 63
	v_add_f32_e32 v11, -1.0, v12
	v_fma_f32 v24, v156, v11, 1.0
	v_max_f32_e64 v20, s28, s28
	v_max_f32_e32 v20, 0x179abe15, v20
	v_rsq_f32_e32 v20, v20
	v_mul_f32_e32 v11, v17, v24
	v_mul_f32_e32 v11, v19, v11
	v_mul_f32_e32 v26, v157, v11
	v_mul_f32_e32 v23, v18, v20
	v_mul_f32_e32 v25, v12, v23
	v_mul_f32_e32 v25, v19, v25
	v_cndmask_b32_e64 v27, v25, v11, s[6:7]
	v_cndmask_b32_e64 v11, v11, v25, s[6:7]
	v_cndmask_b32_e64 v25, 0, v26, s[6:7]
	v_cndmask_b32_e64 v26, v26, 0, s[6:7]
	v_add_f32_dpp v11, v11, v27 quad_perm:[1,0,3,2] row_mask:0xf bank_mask:0xf bound_ctrl:1
	v_mul_f32_e32 v21, 0xbf600343, v21
	v_add_f32_dpp v25, v26, v25 quad_perm:[1,0,3,2] row_mask:0xf bank_mask:0xf bound_ctrl:1
	v_cndmask_b32_e64 v26, v25, v11, s[8:9]
	v_cndmask_b32_e64 v11, v11, v25, s[8:9]
	v_exp_f32_e32 v21, v21
	v_or_b32_e32 v27, 0x80, v3
	v_add_f32_dpp v11, v11, v26 quad_perm:[2,3,0,1] row_mask:0xf bank_mask:0xf bound_ctrl:1
	v_fma_mixlo_f16 v17, v17, v24, 0
	v_sub_f32_e32 v21, 1.0, v21
	v_add_f32_dpp v11, v11, v11 row_ror:4 row_mask:0xf bank_mask:0xf bound_ctrl:1
	s_nop 1
	v_add_f32_dpp v25, v11, v11 row_ror:8 row_mask:0xf bank_mask:0xf bound_ctrl:1
	ds_bpermute_b32 v26, v4, v25
	v_cvt_f32_f16_e32 v11, v242
	s_waitcnt lgkmcnt(0)
	v_add_f32_e32 v25, v25, v26
	ds_bpermute_b32 v26, v5, v25
	v_sub_f32_e32 v10, v10, v11
	v_fma_mixlo_f16 v10, v164, v10, v242 op_sel_hi:[0,0,1]
	s_waitcnt lgkmcnt(0)
	v_add_f32_e32 v25, v25, v26
	s_nop 0
	v_readlane_b32 s42, v25, 0
	v_readlane_b32 s28, v25, 1
	v_readlane_b32 s43, v25, 2
	v_sub_f32_e32 v25, 1.0, v21
	v_cvt_f16_f32_e32 v21, v21
	v_mul_f32_e32 v26, s28, v23
	v_fma_mixlo_f16 v19, v19, v25, -v26
	global_store_short v27, v19, s[66:67]
	global_store_short v27, v21, s[14:15]
	global_store_short v27, v10, s[18:19]
	v_fma_mixlo_f16 v10, v18, v20, 0
	global_store_short v27, v10, s[20:21]
	v_fma_mixlo_f16 v10, v12, v23, 0
	global_store_short v27, v10, s[22:23]
	v_add_u32_e32 v10, 0x400, v2
	global_store_short v27, v17, s[16:17]
	global_store_short v10, v16, s[24:25]
	s_and_saveexec_b64 s[28:29], s[2:3]
	s_cbranch_execz .LBB0_532
	s_lshl_b64 s[44:45], s[26:27], 3
	s_add_u32 s44, s34, s44
	s_addc_u32 s45, s35, s45
	v_mov_b32_e32 v16, s42
	v_mov_b32_e32 v17, s43
	global_store_dwordx2 v139, v[16:17], s[44:45] offset:8
.LBB0_532:
	s_or_b64 exec, exec, s[28:29]
	v_add_u32_e32 v10, 0x7000, v229
	v_add_u32_e32 v12, 0x7400, v229
	v_add_u32_e32 v17, 0x7800, v229
	global_load_ushort v23, v10, s[12:13]
	global_load_ushort v16, v12, s[12:13]
	s_nop 0
	global_load_ushort v10, v17, s[12:13]
	v_cvt_f32_f16_e32 v12, v240
	v_cvt_f32_f16_e32 v18, v241
	ds_read_u16 v17, v179
	ds_read_u16 v19, v176 offset:52256
	ds_read_u16 v20, v176 offset:18976
	v_mov_b32_e32 v25, 0
	v_sub_f32_e32 v13, v13, v12
	v_sub_f32_e32 v14, v14, v18
	v_fma_mix_f32 v13, v160, v13, v240 op_sel_hi:[0,0,1]
	v_fma_mix_f32 v21, v161, v14, v241 op_sel_hi:[0,0,1]
	s_waitcnt lgkmcnt(1)
	v_fma_mix_f32 v14, v19, s31, v171 op_sel_hi:[1,0,0]
	s_waitcnt lgkmcnt(0)
	v_fma_mix_f32 v19, v20, s31, v170 op_sel_hi:[1,0,0]
	v_mul_f32_e32 v20, v1, v13
	v_mul_f32_e32 v24, v20, v20
	v_exp_f32_e32 v14, v14
	v_exp_f32_e32 v19, v19
	v_mov_b32_dpp v25, v24 quad_perm:[1,0,3,2] row_mask:0xf bank_mask:0xf
	v_fmac_f32_e32 v25, v20, v20
	v_add_f32_e32 v14, 1.0, v14
	s_nop 0
	v_add_f32_dpp v24, v25, v25 quad_perm:[2,3,0,1] row_mask:0xf bank_mask:0xf bound_ctrl:1
	s_nop 0
	s_nop 0
	v_add_f32_dpp v24, v24, v24 row_half_mirror row_mask:0xf bank_mask:0xf bound_ctrl:1
	s_nop 1
	v_add_f32_dpp v24, v24, v24 row_mirror row_mask:0xf bank_mask:0xf bound_ctrl:1
	s_nop 1
	v_add_f32_dpp v24, v24, v24 row_bcast:15 row_mask:0xa bank_mask:0xf
	s_nop 1
	v_add_f32_dpp v24, v24, v24 row_bcast:31 row_mask:0xc bank_mask:0xf
	v_rcp_f32_e32 v25, v14
	v_readlane_b32 s28, v24, 63
	v_add_f32_e32 v14, 1.0, v19
	v_rcp_f32_e32 v19, v14
	v_max_f32_e64 v24, s28, s28
	v_max_f32_e32 v24, 0x179abe15, v24
	v_rsq_f32_e32 v24, v24
	v_add_f32_e32 v14, -1.0, v25
	v_fma_f32 v27, v156, v14, 1.0
	v_mul_f32_e32 v14, v13, v27
	v_mul_f32_e32 v26, v20, v24
	v_mul_f32_e32 v28, v25, v26
	v_mul_f32_e32 v14, v21, v14
	v_mul_f32_e32 v29, v157, v14
	v_mul_f32_e32 v28, v21, v28
	v_cndmask_b32_e64 v30, v28, v14, s[6:7]
	v_cndmask_b32_e64 v14, v14, v28, s[6:7]
	v_cndmask_b32_e64 v28, 0, v29, s[6:7]
	v_cndmask_b32_e64 v29, v29, 0, s[6:7]
	v_add_f32_dpp v14, v14, v30 quad_perm:[1,0,3,2] row_mask:0xf bank_mask:0xf bound_ctrl:1
	v_mul_f32_e32 v19, 0xbf600343, v19
	v_add_f32_dpp v28, v29, v28 quad_perm:[1,0,3,2] row_mask:0xf bank_mask:0xf bound_ctrl:1
	v_cndmask_b32_e64 v29, v28, v14, s[8:9]
	v_cndmask_b32_e64 v14, v14, v28, s[8:9]
	v_exp_f32_e32 v19, v19
	v_or_b32_e32 v30, 0x100, v3
	v_add_f32_dpp v14, v14, v29 quad_perm:[2,3,0,1] row_mask:0xf bank_mask:0xf bound_ctrl:1
	v_fma_mixlo_f16 v13, v13, v27, 0
	v_sub_f32_e32 v19, 1.0, v19
	v_add_f32_dpp v14, v14, v14 row_ror:4 row_mask:0xf bank_mask:0xf bound_ctrl:1
	s_nop 1
	v_add_f32_dpp v28, v14, v14 row_ror:8 row_mask:0xf bank_mask:0xf bound_ctrl:1
	ds_bpermute_b32 v29, v4, v28
	v_cvt_f32_f16_e32 v14, v239
	s_waitcnt lgkmcnt(0)
	v_add_f32_e32 v28, v28, v29
	ds_bpermute_b32 v29, v5, v28
	v_sub_f32_e32 v11, v11, v14
	v_fma_mixlo_f16 v11, v164, v11, v239 op_sel_hi:[0,0,1]
	s_waitcnt lgkmcnt(0)
	v_add_f32_e32 v28, v28, v29
	s_nop 0
	v_readlane_b32 s42, v28, 0
	v_readlane_b32 s28, v28, 1
	v_readlane_b32 s43, v28, 2
	v_sub_f32_e32 v28, 1.0, v19
	v_cvt_f16_f32_e32 v19, v19
	v_mul_f32_e32 v29, s28, v26
	v_fma_mixlo_f16 v21, v21, v28, -v29
	global_store_short v30, v21, s[66:67]
	global_store_short v30, v19, s[14:15]
	global_store_short v30, v11, s[18:19]
	v_fma_mixlo_f16 v11, v20, v24, 0
	global_store_short v30, v11, s[20:21]
	v_fma_mixlo_f16 v11, v25, v26, 0
	global_store_short v30, v11, s[22:23]
	v_add_u32_e32 v11, 0x800, v2
	global_store_short v30, v13, s[16:17]
	global_store_short v11, v17, s[24:25]
	s_and_saveexec_b64 s[28:29], s[2:3]
	s_cbranch_execz .LBB0_534
	s_lshl_b64 s[44:45], s[26:27], 3
	s_add_u32 s44, s34, s44
	s_addc_u32 s45, s35, s45
	v_mov_b32_e32 v20, s42
	v_mov_b32_e32 v21, s43
	global_store_dwordx2 v139, v[20:21], s[44:45] offset:16
; __device__ __forceinline__ bf16 f2bf(float f) { return (bf16)(pk2(f, 0.f) & 0xffffu); }
; __device__ __forceinline__ float wave_sum_d(float v) {
;     v = row16_sum(v);
;     v += __builtin_bit_cast(float, __builtin_amdgcn_update_dpp(0, __builtin_bit_cast(int, v), 0x142, 0xa, 0xf, false));
;     v += __builtin_bit_cast(float, __builtin_amdgcn_update_dpp(0, __builtin_bit_cast(int, v), 0x143, 0xc, 0xf, false));
;     return __builtin_bit_cast(float, __builtin_amdgcn_readlane(__builtin_bit_cast(int, v), 63));
; }
; __device__ __forceinline__ void prep_phase(const Ctx& F, const float* mu, const float* w0, const float* a0, const float* k_k, const float* k_a, const float* r_k) {
;     ...
;             if (t + 6 < 32) { rin[t + 7] = PRL((t + 6) * PRWW); kin[t + 7] = PRL((t + 6) * PRWW + 512); vin[t + 7] = PRL((t + 6) * PRWW + 1024); }
;             asm volatile("" ::: "memory");
;             const float rc = bf2f(rin[t + 1]), kc = bf2f(kin[t + 1]), vc = bf2f(vin[t + 1]), rp = bf2f(rin[t]), kp = bf2f(kin[t]), vp = bf2f(vin[t]);
;             const float r = rc + (rp - rc) * mur, kx = kc + (kp - kc) * muk, vx = vc + (vp - vc) * muv;
;             const float ld = bf2f(outs[t * OP + c]), la = bf2f(outs[32 * OP + t * OP + c]), g = bf2f(outs[64 * OP + t * OP + c]);
;             const float een = -0.87504979f * __builtin_amdgcn_rcpf(1.f + __builtin_amdgcn_exp2f(w0n - 1.44269504f * ld));
;             const float omw = 1.f - __builtin_amdgcn_exp2f(een);
;             const float a = __builtin_amdgcn_rcpf(1.f + __builtin_amdgcn_exp2f(a0n - 1.44269504f * la));
;             const float kkv = kx * kkc; const float n2 = wave_sum_d(kkv * kkv); const float kk = kkv * __builtin_amdgcn_rsqf(fmaxf(n2, 1e-24f));
;             const float kmod = kx * (1.f + (a - 1.f) * kac); const float bb = kk * a;
;             float s_kr = kmod * r, s_bs = s_kr * rkc, s_br = bb * r;
;             wave_sum3(s_kr, s_bs, s_br, lane);
;             const float wr = (1.f - omw) * r - s_br * kk;
;             const unsigned o = ob0 + t * 128u;
;             ST16(SWR, o, f2bf(wr)); ST16(SC, o, f2bf(omw)); ST16(SK, o, f2bf(kmod)); ST16(SV, o, f2bf(vx)); ST16(SKK, o, f2bf(kk)); ST16(SB, o, f2bf(bb));
;             ST16(GG, gb0 + t * 1024u, f2bf(g));
;             if (lane == 0) *(f32x2*)(SCAL + ((size_t)bh * SEQ + pos0 + t) * 2) = (f32x2){s_kr, s_bs};
.LBB0_534:
	s_or_b64 exec, exec, s[28:29]
	v_add_u32_e32 v11, 0x7e00, v229
	v_add_u32_e32 v13, 0x8200, v229
	v_add_u32_e32 v19, 0x8600, v229
	global_load_ushort v24, v11, s[12:13]
	global_load_ushort v17, v13, s[12:13]
	s_nop 0
	global_load_ushort v11, v19, s[12:13]
	v_cvt_f32_f16_e32 v13, v237
	v_mov_b32_e32 v28, 0
	ds_read_u16 v20, v180
	ds_read_u16 v21, v176 offset:53296
	ds_read_u16 v25, v176 offset:20016
	v_sub_f32_e32 v12, v12, v13
	v_fma_mix_f32 v12, v160, v12, v237 op_sel_hi:[0,0,1]
	v_mul_f32_e32 v26, v1, v12
	v_mul_f32_e32 v27, v26, v26
	s_waitcnt lgkmcnt(1)
	v_fma_mix_f32 v21, v21, s31, v171 op_sel_hi:[1,0,0]
	s_waitcnt lgkmcnt(0)
	v_fma_mix_f32 v25, v25, s31, v170 op_sel_hi:[1,0,0]
	v_mov_b32_dpp v28, v27 quad_perm:[1,0,3,2] row_mask:0xf bank_mask:0xf
	v_fmac_f32_e32 v28, v26, v26
	v_exp_f32_e32 v21, v21
	v_exp_f32_e32 v25, v25
	v_add_f32_dpp v27, v28, v28 quad_perm:[2,3,0,1] row_mask:0xf bank_mask:0xf bound_ctrl:1
	v_add_f32_e32 v21, 1.0, v21
	s_nop 0
	v_add_f32_dpp v27, v27, v27 row_half_mirror row_mask:0xf bank_mask:0xf bound_ctrl:1
	v_cvt_f32_f16_e32 v19, v238
	v_sub_f32_e32 v18, v18, v19
	v_add_f32_dpp v27, v27, v27 row_mirror row_mask:0xf bank_mask:0xf bound_ctrl:1
	v_fma_mix_f32 v18, v161, v18, v238 op_sel_hi:[0,0,1]
	s_nop 0
	v_add_f32_dpp v27, v27, v27 row_bcast:15 row_mask:0xa bank_mask:0xf
	s_nop 1
	v_add_f32_dpp v27, v27, v27 row_bcast:31 row_mask:0xc bank_mask:0xf
	v_rcp_f32_e32 v28, v21
	v_readlane_b32 s28, v27, 63
	v_add_f32_e32 v21, 1.0, v25
	v_rcp_f32_e32 v25, v21
	v_max_f32_e64 v27, s28, s28
	v_max_f32_e32 v27, 0x179abe15, v27
	v_rsq_f32_e32 v27, v27
	v_add_f32_e32 v21, -1.0, v28
	v_fma_f32 v30, v156, v21, 1.0
	v_mul_f32_e32 v21, v12, v30
	v_mul_f32_e32 v29, v26, v27
	v_mul_f32_e32 v31, v28, v29
	v_mul_f32_e32 v21, v18, v21
	v_mul_f32_e32 v32, v157, v21
	v_mul_f32_e32 v31, v18, v31
	v_cndmask_b32_e64 v33, v31, v21, s[6:7]
	v_cndmask_b32_e64 v21, v21, v31, s[6:7]
	v_cndmask_b32_e64 v31, 0, v32, s[6:7]
	v_cndmask_b32_e64 v32, v32, 0, s[6:7]
	v_add_f32_dpp v21, v21, v33 quad_perm:[1,0,3,2] row_mask:0xf bank_mask:0xf bound_ctrl:1
	v_mul_f32_e32 v25, 0xbf600343, v25
	v_add_f32_dpp v31, v32, v31 quad_perm:[1,0,3,2] row_mask:0xf bank_mask:0xf bound_ctrl:1
	v_cndmask_b32_e64 v32, v31, v21, s[8:9]
	v_cndmask_b32_e64 v21, v21, v31, s[8:9]
	v_exp_f32_e32 v25, v25
	v_or_b32_e32 v33, 0x180, v3
	v_add_f32_dpp v21, v21, v32 quad_perm:[2,3,0,1] row_mask:0xf bank_mask:0xf bound_ctrl:1
	v_fma_mixlo_f16 v12, v12, v30, 0
	v_sub_f32_e32 v25, 1.0, v25
	v_add_f32_dpp v21, v21, v21 row_ror:4 row_mask:0xf bank_mask:0xf bound_ctrl:1
	s_nop 1
	v_add_f32_dpp v31, v21, v21 row_ror:8 row_mask:0xf bank_mask:0xf bound_ctrl:1
	ds_bpermute_b32 v32, v4, v31
	v_cvt_f32_f16_e32 v21, v236
	s_waitcnt lgkmcnt(0)
	v_add_f32_e32 v31, v31, v32
	ds_bpermute_b32 v32, v5, v31
	v_sub_f32_e32 v14, v14, v21
	s_waitcnt lgkmcnt(0)
	v_add_f32_e32 v31, v31, v32
	s_nop 0
	v_readlane_b32 s42, v31, 0
	v_readlane_b32 s28, v31, 1
	v_readlane_b32 s43, v31, 2
	v_sub_f32_e32 v31, 1.0, v25
	v_cvt_f16_f32_e32 v25, v25
	v_mul_f32_e32 v32, s28, v29
	v_fma_mixlo_f16 v18, v18, v31, -v32
	global_store_short v33, v18, s[66:67]
	global_store_short v33, v25, s[14:15]
	global_store_short v33, v12, s[16:17]
	v_fma_mixlo_f16 v12, v164, v14, v236 op_sel_hi:[0,0,1]
	global_store_short v33, v12, s[18:19]
	v_fma_mixlo_f16 v12, v26, v27, 0
	global_store_short v33, v12, s[20:21]
	v_fma_mixlo_f16 v12, v28, v29, 0
	global_store_short v33, v12, s[22:23]
	v_add_u32_e32 v12, 0xc00, v2
	global_store_short v12, v20, s[24:25]
	s_and_saveexec_b64 s[28:29], s[2:3]
	s_cbranch_execz .LBB0_536
	s_lshl_b64 s[44:45], s[26:27], 3
	s_add_u32 s44, s34, s44
	s_addc_u32 s45, s35, s45
	v_mov_b32_e32 v26, s42
	v_mov_b32_e32 v27, s43
	global_store_dwordx2 v139, v[26:27], s[44:45] offset:24
.LBB0_536:
	s_or_b64 exec, exec, s[28:29]
	v_add_u32_e32 v12, 0x8c00, v229
	v_add_u32_e32 v14, 0x9000, v229
	v_add_u32_e32 v20, 0x9400, v229
	global_load_ushort v25, v12, s[12:13]
	global_load_ushort v18, v14, s[12:13]
	s_nop 0
	global_load_ushort v12, v20, s[12:13]
	v_cvt_f32_f16_e32 v14, v234
	v_mov_b32_e32 v31, 0
	ds_read_u16 v26, v181
	ds_read_u16 v27, v176 offset:54336
	ds_read_u16 v28, v176 offset:21056
	v_sub_f32_e32 v13, v13, v14
	v_fma_mix_f32 v13, v160, v13, v234 op_sel_hi:[0,0,1]
	v_mul_f32_e32 v29, v1, v13
	v_mul_f32_e32 v30, v29, v29
	s_waitcnt lgkmcnt(1)
	v_fma_mix_f32 v27, v27, s31, v171 op_sel_hi:[1,0,0]
	s_waitcnt lgkmcnt(0)
	v_fma_mix_f32 v28, v28, s31, v170 op_sel_hi:[1,0,0]
	v_mov_b32_dpp v31, v30 quad_perm:[1,0,3,2] row_mask:0xf bank_mask:0xf
	v_fmac_f32_e32 v31, v29, v29
	v_exp_f32_e32 v27, v27
	v_exp_f32_e32 v28, v28
	v_add_f32_dpp v30, v31, v31 quad_perm:[2,3,0,1] row_mask:0xf bank_mask:0xf bound_ctrl:1
	v_add_f32_e32 v27, 1.0, v27
	s_nop 0
	v_add_f32_dpp v30, v30, v30 row_half_mirror row_mask:0xf bank_mask:0xf bound_ctrl:1
	v_cvt_f32_f16_e32 v20, v235
	v_sub_f32_e32 v19, v19, v20
	v_add_f32_dpp v30, v30, v30 row_mirror row_mask:0xf bank_mask:0xf bound_ctrl:1
	v_fma_mix_f32 v19, v161, v19, v235 op_sel_hi:[0,0,1]
	s_nop 0
	v_add_f32_dpp v30, v30, v30 row_bcast:15 row_mask:0xa bank_mask:0xf
	s_nop 1
	v_add_f32_dpp v30, v30, v30 row_bcast:31 row_mask:0xc bank_mask:0xf
	v_rcp_f32_e32 v31, v27
	v_readlane_b32 s28, v30, 63
	v_add_f32_e32 v27, 1.0, v28
	v_rcp_f32_e32 v28, v27
	v_max_f32_e64 v30, s28, s28
	v_max_f32_e32 v30, 0x179abe15, v30
	v_rsq_f32_e32 v30, v30
	v_add_f32_e32 v27, -1.0, v31
	v_fma_f32 v33, v156, v27, 1.0
	v_mul_f32_e32 v27, v13, v33
	v_mul_f32_e32 v32, v29, v30
	v_mul_f32_e32 v34, v31, v32
	v_mul_f32_e32 v27, v19, v27
	v_mul_f32_e32 v35, v157, v27
	v_mul_f32_e32 v34, v19, v34
	v_cndmask_b32_e64 v36, v34, v27, s[6:7]
	v_cndmask_b32_e64 v27, v27, v34, s[6:7]
	v_cndmask_b32_e64 v34, 0, v35, s[6:7]
	v_cndmask_b32_e64 v35, v35, 0, s[6:7]
	v_add_f32_dpp v27, v27, v36 quad_perm:[1,0,3,2] row_mask:0xf bank_mask:0xf bound_ctrl:1
	v_mul_f32_e32 v28, 0xbf600343, v28
	v_add_f32_dpp v34, v35, v34 quad_perm:[1,0,3,2] row_mask:0xf bank_mask:0xf bound_ctrl:1
	v_cndmask_b32_e64 v35, v34, v27, s[8:9]
	v_cndmask_b32_e64 v27, v27, v34, s[8:9]
	v_exp_f32_e32 v28, v28
	v_or_b32_e32 v36, 0x200, v3
	v_add_f32_dpp v27, v27, v35 quad_perm:[2,3,0,1] row_mask:0xf bank_mask:0xf bound_ctrl:1
	v_fma_mixlo_f16 v13, v13, v33, 0
	v_sub_f32_e32 v28, 1.0, v28
	v_add_f32_dpp v27, v27, v27 row_ror:4 row_mask:0xf bank_mask:0xf bound_ctrl:1
	s_nop 1
	v_add_f32_dpp v34, v27, v27 row_ror:8 row_mask:0xf bank_mask:0xf bound_ctrl:1
	ds_bpermute_b32 v35, v4, v34
	v_cvt_f32_f16_e32 v27, v233
	s_waitcnt lgkmcnt(0)
; __device__ __forceinline__ bf16 f2bf(float f) { return (bf16)(pk2(f, 0.f) & 0xffffu); }
; __device__ __forceinline__ float wave_sum_d(float v) {
;     v = row16_sum(v);
;     v += __builtin_bit_cast(float, __builtin_amdgcn_update_dpp(0, __builtin_bit_cast(int, v), 0x142, 0xa, 0xf, false));
;     v += __builtin_bit_cast(float, __builtin_amdgcn_update_dpp(0, __builtin_bit_cast(int, v), 0x143, 0xc, 0xf, false));
;     return __builtin_bit_cast(float, __builtin_amdgcn_readlane(__builtin_bit_cast(int, v), 63));
; }
; __device__ __forceinline__ void prep_phase(const Ctx& F, const float* mu, const float* w0, const float* a0, const float* k_k, const float* k_a, const float* r_k) {
;     ...
;             if (t + 6 < 32) { rin[t + 7] = PRL((t + 6) * PRWW); kin[t + 7] = PRL((t + 6) * PRWW + 512); vin[t + 7] = PRL((t + 6) * PRWW + 1024); }
;             asm volatile("" ::: "memory");
;             const float rc = bf2f(rin[t + 1]), kc = bf2f(kin[t + 1]), vc = bf2f(vin[t + 1]), rp = bf2f(rin[t]), kp = bf2f(kin[t]), vp = bf2f(vin[t]);
;             const float r = rc + (rp - rc) * mur, kx = kc + (kp - kc) * muk, vx = vc + (vp - vc) * muv;
;             const float ld = bf2f(outs[t * OP + c]), la = bf2f(outs[32 * OP + t * OP + c]), g = bf2f(outs[64 * OP + t * OP + c]);
;             const float een = -0.87504979f * __builtin_amdgcn_rcpf(1.f + __builtin_amdgcn_exp2f(w0n - 1.44269504f * ld));
;             const float omw = 1.f - __builtin_amdgcn_exp2f(een);
;             const float a = __builtin_amdgcn_rcpf(1.f + __builtin_amdgcn_exp2f(a0n - 1.44269504f * la));
;             const float kkv = kx * kkc; const float n2 = wave_sum_d(kkv * kkv); const float kk = kkv * __builtin_amdgcn_rsqf(fmaxf(n2, 1e-24f));
;             const float kmod = kx * (1.f + (a - 1.f) * kac); const float bb = kk * a;
;             float s_kr = kmod * r, s_bs = s_kr * rkc, s_br = bb * r;
;             wave_sum3(s_kr, s_bs, s_br, lane);
;             const float wr = (1.f - omw) * r - s_br * kk;
;             const unsigned o = ob0 + t * 128u;
;             ST16(SWR, o, f2bf(wr)); ST16(SC, o, f2bf(omw)); ST16(SK, o, f2bf(kmod)); ST16(SV, o, f2bf(vx)); ST16(SKK, o, f2bf(kk)); ST16(SB, o, f2bf(bb));
;             ST16(GG, gb0 + t * 1024u, f2bf(g));
;             if (lane == 0) *(f32x2*)(SCAL + ((size_t)bh * SEQ + pos0 + t) * 2) = (f32x2){s_kr, s_bs};
	v_add_f32_e32 v34, v34, v35
	ds_bpermute_b32 v35, v5, v34
	v_sub_f32_e32 v21, v21, v27
	s_waitcnt lgkmcnt(0)
	v_add_f32_e32 v34, v34, v35
	s_nop 0
	v_readlane_b32 s42, v34, 0
	v_readlane_b32 s28, v34, 1
	v_readlane_b32 s43, v34, 2
	v_sub_f32_e32 v34, 1.0, v28
	v_cvt_f16_f32_e32 v28, v28
	v_mul_f32_e32 v35, s28, v32
	v_fma_mixlo_f16 v19, v19, v34, -v35
	global_store_short v36, v19, s[66:67]
	global_store_short v36, v28, s[14:15]
	global_store_short v36, v13, s[16:17]
	v_fma_mixlo_f16 v13, v164, v21, v233 op_sel_hi:[0,0,1]
	global_store_short v36, v13, s[18:19]
	v_fma_mixlo_f16 v13, v29, v30, 0
	global_store_short v36, v13, s[20:21]
	v_fma_mixlo_f16 v13, v31, v32, 0
	global_store_short v36, v13, s[22:23]
	v_add_u32_e32 v13, 0x1000, v2
	global_store_short v13, v26, s[24:25]
	s_and_saveexec_b64 s[28:29], s[2:3]
	s_cbranch_execz .LBB0_538
	s_lshl_b64 s[44:45], s[26:27], 3
	s_add_u32 s44, s34, s44
	s_addc_u32 s45, s35, s45
	v_mov_b32_e32 v28, s42
	v_mov_b32_e32 v29, s43
	global_store_dwordx2 v139, v[28:29], s[44:45] offset:32
.LBB0_538:
	s_or_b64 exec, exec, s[28:29]
	v_add_u32_e32 v13, 0x9a00, v229
	v_add_u32_e32 v19, 0x9e00, v229
	v_add_u32_e32 v21, 0xa200, v229
	global_load_ushort v26, v13, s[12:13]
	s_nop 0
	global_load_ushort v19, v19, s[12:13]
	s_nop 0
	global_load_ushort v13, v21, s[12:13]
	v_cvt_f32_f16_e32 v21, v231
	v_mov_b32_e32 v34, 0
	ds_read_u16 v29, v182
	ds_read_u16 v30, v176 offset:55376
	ds_read_u16 v31, v176 offset:22096
	v_sub_f32_e32 v14, v14, v21
	v_fma_mix_f32 v14, v160, v14, v231 op_sel_hi:[0,0,1]
	v_mul_f32_e32 v32, v1, v14
	v_mul_f32_e32 v33, v32, v32
	s_waitcnt lgkmcnt(1)
	v_fma_mix_f32 v30, v30, s31, v171 op_sel_hi:[1,0,0]
	s_waitcnt lgkmcnt(0)
	v_fma_mix_f32 v31, v31, s31, v170 op_sel_hi:[1,0,0]
	v_mov_b32_dpp v34, v33 quad_perm:[1,0,3,2] row_mask:0xf bank_mask:0xf
	v_fmac_f32_e32 v34, v32, v32
	v_exp_f32_e32 v30, v30
	v_exp_f32_e32 v31, v31
	v_add_f32_dpp v33, v34, v34 quad_perm:[2,3,0,1] row_mask:0xf bank_mask:0xf bound_ctrl:1
	v_add_f32_e32 v30, 1.0, v30
	s_nop 0
	v_add_f32_dpp v33, v33, v33 row_half_mirror row_mask:0xf bank_mask:0xf bound_ctrl:1
	v_rcp_f32_e32 v30, v30
	v_cvt_f32_f16_e32 v28, v232
	v_add_f32_dpp v33, v33, v33 row_mirror row_mask:0xf bank_mask:0xf bound_ctrl:1
	v_add_f32_e32 v31, 1.0, v31
	v_sub_f32_e32 v20, v20, v28
	v_add_f32_dpp v33, v33, v33 row_bcast:15 row_mask:0xa bank_mask:0xf
	v_fma_mix_f32 v20, v161, v20, v232 op_sel_hi:[0,0,1]
	s_nop 0
	v_add_f32_dpp v33, v33, v33 row_bcast:31 row_mask:0xc bank_mask:0xf
	v_rcp_f32_e32 v34, v31
	v_readlane_b32 s28, v33, 63
	v_add_f32_e32 v31, -1.0, v30
	v_fma_f32 v36, v156, v31, 1.0
	v_max_f32_e64 v33, s28, s28
	v_max_f32_e32 v33, 0x179abe15, v33
	v_rsq_f32_e32 v33, v33
	v_mul_f32_e32 v31, v14, v36
	v_mul_f32_e32 v31, v20, v31
	v_mul_f32_e32 v38, v157, v31
	v_mul_f32_e32 v35, v32, v33
	v_mul_f32_e32 v37, v30, v35
	v_mul_f32_e32 v37, v20, v37
	v_cndmask_b32_e64 v39, v37, v31, s[6:7]
	v_cndmask_b32_e64 v31, v31, v37, s[6:7]
	v_cndmask_b32_e64 v37, 0, v38, s[6:7]
	v_cndmask_b32_e64 v38, v38, 0, s[6:7]
	v_add_f32_dpp v31, v31, v39 quad_perm:[1,0,3,2] row_mask:0xf bank_mask:0xf bound_ctrl:1
	v_mul_f32_e32 v34, 0xbf600343, v34
	v_add_f32_dpp v37, v38, v37 quad_perm:[1,0,3,2] row_mask:0xf bank_mask:0xf bound_ctrl:1
	v_cndmask_b32_e64 v38, v37, v31, s[8:9]
	v_cndmask_b32_e64 v31, v31, v37, s[8:9]
	v_exp_f32_e32 v34, v34
	v_or_b32_e32 v39, 0x280, v3
	v_add_f32_dpp v31, v31, v38 quad_perm:[2,3,0,1] row_mask:0xf bank_mask:0xf bound_ctrl:1
	v_fma_mixlo_f16 v14, v14, v36, 0
	v_sub_f32_e32 v34, 1.0, v34
	v_add_f32_dpp v31, v31, v31 row_ror:4 row_mask:0xf bank_mask:0xf bound_ctrl:1
	s_nop 1
	v_add_f32_dpp v37, v31, v31 row_ror:8 row_mask:0xf bank_mask:0xf bound_ctrl:1
	ds_bpermute_b32 v38, v4, v37
	v_cvt_f32_f16_e32 v31, v230
	s_waitcnt lgkmcnt(0)
	v_add_f32_e32 v37, v37, v38
	ds_bpermute_b32 v38, v5, v37
	v_sub_f32_e32 v27, v27, v31
	s_waitcnt lgkmcnt(0)
	v_add_f32_e32 v37, v37, v38
	s_nop 0
	v_readlane_b32 s42, v37, 0
	v_readlane_b32 s28, v37, 1
	v_readlane_b32 s43, v37, 2
	v_sub_f32_e32 v37, 1.0, v34
	v_cvt_f16_f32_e32 v34, v34
	v_mul_f32_e32 v38, s28, v35
	v_fma_mixlo_f16 v20, v20, v37, -v38
	global_store_short v39, v20, s[66:67]
	global_store_short v39, v34, s[14:15]
	global_store_short v39, v14, s[16:17]
	v_fma_mixlo_f16 v14, v164, v27, v230 op_sel_hi:[0,0,1]
	global_store_short v39, v14, s[18:19]
	v_fma_mixlo_f16 v14, v32, v33, 0
	global_store_short v39, v14, s[20:21]
	v_fma_mixlo_f16 v14, v30, v35, 0
	global_store_short v39, v14, s[22:23]
	v_add_u32_e32 v14, 0x1400, v2
	global_store_short v14, v29, s[24:25]
	s_and_saveexec_b64 s[28:29], s[2:3]
	s_cbranch_execz .LBB0_540
	s_lshl_b64 s[44:45], s[26:27], 3
	s_add_u32 s44, s34, s44
	s_addc_u32 s45, s35, s45
	v_mov_b32_e32 v32, s42
	v_mov_b32_e32 v33, s43
	global_store_dwordx2 v139, v[32:33], s[44:45] offset:40
; __device__ __forceinline__ bf16 f2bf(float f) { return (bf16)(pk2(f, 0.f) & 0xffffu); }
; __device__ __forceinline__ float wave_sum_d(float v) {
;     v = row16_sum(v);
;     v += __builtin_bit_cast(float, __builtin_amdgcn_update_dpp(0, __builtin_bit_cast(int, v), 0x142, 0xa, 0xf, false));
;     v += __builtin_bit_cast(float, __builtin_amdgcn_update_dpp(0, __builtin_bit_cast(int, v), 0x143, 0xc, 0xf, false));
;     return __builtin_bit_cast(float, __builtin_amdgcn_readlane(__builtin_bit_cast(int, v), 63));
; }
; __device__ __forceinline__ void prep_phase(const Ctx& F, const float* mu, const float* w0, const float* a0, const float* k_k, const float* k_a, const float* r_k) {
;     ...
;             if (t + 6 < 32) { rin[t + 7] = PRL((t + 6) * PRWW); kin[t + 7] = PRL((t + 6) * PRWW + 512); vin[t + 7] = PRL((t + 6) * PRWW + 1024); }
;             asm volatile("" ::: "memory");
;             const float rc = bf2f(rin[t + 1]), kc = bf2f(kin[t + 1]), vc = bf2f(vin[t + 1]), rp = bf2f(rin[t]), kp = bf2f(kin[t]), vp = bf2f(vin[t]);
;             const float r = rc + (rp - rc) * mur, kx = kc + (kp - kc) * muk, vx = vc + (vp - vc) * muv;
;             const float ld = bf2f(outs[t * OP + c]), la = bf2f(outs[32 * OP + t * OP + c]), g = bf2f(outs[64 * OP + t * OP + c]);
;             const float een = -0.87504979f * __builtin_amdgcn_rcpf(1.f + __builtin_amdgcn_exp2f(w0n - 1.44269504f * ld));
;             const float omw = 1.f - __builtin_amdgcn_exp2f(een);
;             const float a = __builtin_amdgcn_rcpf(1.f + __builtin_amdgcn_exp2f(a0n - 1.44269504f * la));
;             const float kkv = kx * kkc; const float n2 = wave_sum_d(kkv * kkv); const float kk = kkv * __builtin_amdgcn_rsqf(fmaxf(n2, 1e-24f));
;             const float kmod = kx * (1.f + (a - 1.f) * kac); const float bb = kk * a;
;             float s_kr = kmod * r, s_bs = s_kr * rkc, s_br = bb * r;
;             wave_sum3(s_kr, s_bs, s_br, lane);
;             const float wr = (1.f - omw) * r - s_br * kk;
;             const unsigned o = ob0 + t * 128u;
;             ST16(SWR, o, f2bf(wr)); ST16(SC, o, f2bf(omw)); ST16(SK, o, f2bf(kmod)); ST16(SV, o, f2bf(vx)); ST16(SKK, o, f2bf(kk)); ST16(SB, o, f2bf(bb));
;             ST16(GG, gb0 + t * 1024u, f2bf(g));
;             if (lane == 0) *(f32x2*)(SCAL + ((size_t)bh * SEQ + pos0 + t) * 2) = (f32x2){s_kr, s_bs};
.LBB0_540:
	s_or_b64 exec, exec, s[28:29]
	v_add_u32_e32 v14, 0xa800, v229
	v_add_u32_e32 v20, 0xac00, v229
	v_add_u32_e32 v29, 0xb000, v229
	global_load_ushort v27, v14, s[12:13]
	s_nop 0
	global_load_ushort v20, v20, s[12:13]
	s_nop 0
	global_load_ushort v14, v29, s[12:13]
	s_waitcnt vmcnt(61)
	v_cvt_f32_f16_e32 v29, v7
	v_cvt_f32_f16_e32 v30, v8
	ds_read_u16 v32, v183
	ds_read_u16 v33, v176 offset:56416
	ds_read_u16 v34, v176 offset:23136
	v_sub_f32_e32 v21, v21, v29
	v_fma_mix_f32 v21, v160, v21, v7 op_sel_hi:[0,0,1]
	v_sub_f32_e32 v28, v28, v30
	v_fma_mix_f32 v8, v161, v28, v8 op_sel_hi:[0,0,1]
	s_waitcnt lgkmcnt(1)
	v_fma_mix_f32 v28, v33, s31, v171 op_sel_hi:[1,0,0]
	v_mul_f32_e32 v33, v1, v21
	s_waitcnt lgkmcnt(0)
	v_fma_mix_f32 v7, v34, s31, v170 op_sel_hi:[1,0,0]
	v_mul_f32_e32 v34, v33, v33
	v_mov_b32_e32 v35, 0
	v_exp_f32_e32 v28, v28
	v_exp_f32_e32 v7, v7
	v_mov_b32_dpp v35, v34 quad_perm:[1,0,3,2] row_mask:0xf bank_mask:0xf
	v_fmac_f32_e32 v35, v33, v33
	v_add_f32_e32 v28, 1.0, v28
	v_rcp_f32_e32 v28, v28
	v_add_f32_dpp v34, v35, v35 quad_perm:[2,3,0,1] row_mask:0xf bank_mask:0xf bound_ctrl:1
	v_add_f32_e32 v7, 1.0, v7
	s_nop 0
	v_add_f32_dpp v34, v34, v34 row_half_mirror row_mask:0xf bank_mask:0xf bound_ctrl:1
	s_nop 1
	v_add_f32_dpp v34, v34, v34 row_mirror row_mask:0xf bank_mask:0xf bound_ctrl:1
	s_nop 1
	v_add_f32_dpp v34, v34, v34 row_bcast:15 row_mask:0xa bank_mask:0xf
	s_nop 1
	v_add_f32_dpp v34, v34, v34 row_bcast:31 row_mask:0xc bank_mask:0xf
	v_rcp_f32_e32 v35, v7
	v_readlane_b32 s28, v34, 63
	v_add_f32_e32 v7, -1.0, v28
	v_fma_f32 v37, v156, v7, 1.0
	v_max_f32_e64 v34, s28, s28
	v_max_f32_e32 v34, 0x179abe15, v34
	v_rsq_f32_e32 v34, v34
	v_mul_f32_e32 v7, v21, v37
	v_mul_f32_e32 v7, v8, v7
	v_mul_f32_e32 v39, v157, v7
	v_mul_f32_e32 v36, v33, v34
	v_mul_f32_e32 v38, v28, v36
	v_mul_f32_e32 v38, v8, v38
	v_cndmask_b32_e64 v40, v38, v7, s[6:7]
	v_cndmask_b32_e64 v7, v7, v38, s[6:7]
	v_cndmask_b32_e64 v38, 0, v39, s[6:7]
	v_cndmask_b32_e64 v39, v39, 0, s[6:7]
	v_add_f32_dpp v7, v7, v40 quad_perm:[1,0,3,2] row_mask:0xf bank_mask:0xf bound_ctrl:1
	v_mul_f32_e32 v35, 0xbf600343, v35
	v_add_f32_dpp v38, v39, v38 quad_perm:[1,0,3,2] row_mask:0xf bank_mask:0xf bound_ctrl:1
	v_cndmask_b32_e64 v39, v38, v7, s[8:9]
	v_cndmask_b32_e64 v7, v7, v38, s[8:9]
	v_exp_f32_e32 v35, v35
	v_or_b32_e32 v40, 0x300, v3
	v_add_f32_dpp v7, v7, v39 quad_perm:[2,3,0,1] row_mask:0xf bank_mask:0xf bound_ctrl:1
	v_sub_f32_e32 v35, 1.0, v35
	s_nop 0
	v_add_f32_dpp v7, v7, v7 row_ror:4 row_mask:0xf bank_mask:0xf bound_ctrl:1
	s_nop 1
	v_add_f32_dpp v38, v7, v7 row_ror:8 row_mask:0xf bank_mask:0xf bound_ctrl:1
	ds_bpermute_b32 v39, v4, v38
	s_waitcnt vmcnt(60)
	v_cvt_f32_f16_e32 v7, v6
	s_waitcnt lgkmcnt(0)
	v_add_f32_e32 v38, v38, v39
	ds_bpermute_b32 v39, v5, v38
	v_sub_f32_e32 v31, v31, v7
	v_fma_mixlo_f16 v6, v164, v31, v6 op_sel_hi:[0,0,1]
	s_waitcnt lgkmcnt(0)
	v_add_f32_e32 v38, v38, v39
	s_nop 0
	v_readlane_b32 s42, v38, 0
	v_readlane_b32 s28, v38, 1
	v_readlane_b32 s43, v38, 2
	v_sub_f32_e32 v38, 1.0, v35
	v_cvt_f16_f32_e32 v35, v35
	v_mul_f32_e32 v39, s28, v36
	v_fma_mixlo_f16 v8, v8, v38, -v39
	global_store_short v40, v8, s[66:67]
	global_store_short v40, v35, s[14:15]
	global_store_short v40, v6, s[18:19]
	v_fma_mixlo_f16 v6, v33, v34, 0
	global_store_short v40, v6, s[20:21]
	v_fma_mixlo_f16 v6, v28, v36, 0
	v_fma_mixlo_f16 v8, v21, v37, 0
	global_store_short v40, v6, s[22:23]
	v_add_u32_e32 v6, 0x1800, v2
	global_store_short v40, v8, s[16:17]
	global_store_short v6, v32, s[24:25]
	s_and_saveexec_b64 s[28:29], s[2:3]
	s_cbranch_execz .LBB0_542
	s_lshl_b64 s[44:45], s[26:27], 3
	s_add_u32 s44, s34, s44
	s_addc_u32 s45, s35, s45
	v_mov_b32_e32 v32, s42
	v_mov_b32_e32 v33, s43
	global_store_dwordx2 v139, v[32:33], s[44:45] offset:48
.LBB0_542:
	s_or_b64 exec, exec, s[28:29]
	v_add_u32_e32 v6, 0xb600, v229
	v_add_u32_e32 v8, 0xba00, v229
	v_add_u32_e32 v31, 0xbe00, v229
	global_load_ushort v28, v6, s[12:13]
	global_load_ushort v21, v8, s[12:13]
	s_nop 0
	global_load_ushort v6, v31, s[12:13]
	s_waitcnt vmcnt(61)
	v_cvt_f32_f16_e32 v8, v15
	v_cvt_f32_f16_e32 v31, v22
	ds_read_u16 v32, v184
	ds_read_u16 v33, v176 offset:57456
	ds_read_u16 v34, v176 offset:24176
	v_sub_f32_e32 v29, v29, v8
	v_fma_mix_f32 v15, v160, v29, v15 op_sel_hi:[0,0,1]
	v_sub_f32_e32 v30, v30, v31
	v_fma_mix_f32 v22, v161, v30, v22 op_sel_hi:[0,0,1]
	s_waitcnt lgkmcnt(1)
	v_fma_mix_f32 v30, v33, s31, v171 op_sel_hi:[1,0,0]
	v_mul_f32_e32 v33, v1, v15
	s_waitcnt lgkmcnt(0)
	v_fma_mix_f32 v29, v34, s31, v170 op_sel_hi:[1,0,0]
	v_mul_f32_e32 v34, v33, v33
	v_mov_b32_e32 v35, 0
	v_exp_f32_e32 v30, v30
	v_exp_f32_e32 v29, v29
	v_mov_b32_dpp v35, v34 quad_perm:[1,0,3,2] row_mask:0xf bank_mask:0xf
	v_fmac_f32_e32 v35, v33, v33
	v_add_f32_e32 v30, 1.0, v30
	v_add_f32_e32 v29, 1.0, v29
	v_add_f32_dpp v34, v35, v35 quad_perm:[2,3,0,1] row_mask:0xf bank_mask:0xf bound_ctrl:1
	v_rcp_f32_e32 v29, v29
	s_nop 0
	v_add_f32_dpp v34, v34, v34 row_half_mirror row_mask:0xf bank_mask:0xf bound_ctrl:1
	v_mul_f32_e32 v29, 0xbf600343, v29
	s_nop 0
	v_add_f32_dpp v34, v34, v34 row_mirror row_mask:0xf bank_mask:0xf bound_ctrl:1
	v_exp_f32_e32 v29, v29
	s_nop 0
	v_add_f32_dpp v34, v34, v34 row_bcast:15 row_mask:0xa bank_mask:0xf
	v_sub_f32_e32 v29, 1.0, v29
	s_nop 0
	v_add_f32_dpp v34, v34, v34 row_bcast:31 row_mask:0xc bank_mask:0xf
	v_rcp_f32_e32 v35, v30
	v_readlane_b32 s28, v34, 63
	v_add_f32_e32 v30, -1.0, v35
	s_nop 0
	v_max_f32_e64 v34, s28, s28
	v_max_f32_e32 v34, 0x179abe15, v34
	v_rsq_f32_e32 v34, v34
	v_fma_f32 v37, v156, v30, 1.0
	v_mul_f32_e32 v30, v15, v37
	v_mul_f32_e32 v30, v22, v30
	v_mul_f32_e32 v36, v33, v34
	v_mul_f32_e32 v38, v35, v36
	v_mul_f32_e32 v39, v157, v30
	v_mul_f32_e32 v38, v22, v38
	v_cndmask_b32_e64 v40, v38, v30, s[6:7]
	v_cndmask_b32_e64 v30, v30, v38, s[6:7]
	v_cndmask_b32_e64 v38, 0, v39, s[6:7]
	v_cndmask_b32_e64 v39, v39, 0, s[6:7]
	v_add_f32_dpp v30, v30, v40 quad_perm:[1,0,3,2] row_mask:0xf bank_mask:0xf bound_ctrl:1
	v_or_b32_e32 v40, 0x380, v3
	v_add_f32_dpp v38, v39, v38 quad_perm:[1,0,3,2] row_mask:0xf bank_mask:0xf bound_ctrl:1
	v_cndmask_b32_e64 v39, v38, v30, s[8:9]
	v_cndmask_b32_e64 v30, v30, v38, s[8:9]
	v_fma_mixlo_f16 v15, v15, v37, 0
	s_nop 0
	v_add_f32_dpp v30, v30, v39 quad_perm:[2,3,0,1] row_mask:0xf bank_mask:0xf bound_ctrl:1
	s_nop 1
	v_add_f32_dpp v30, v30, v30 row_ror:4 row_mask:0xf bank_mask:0xf bound_ctrl:1
	s_nop 1
	v_add_f32_dpp v38, v30, v30 row_ror:8 row_mask:0xf bank_mask:0xf bound_ctrl:1
	ds_bpermute_b32 v39, v4, v38
	s_waitcnt vmcnt(60)
; __device__ __forceinline__ bf16 f2bf(float f) { return (bf16)(pk2(f, 0.f) & 0xffffu); }
; __device__ __forceinline__ float wave_sum_d(float v) {
;     v = row16_sum(v);
;     v += __builtin_bit_cast(float, __builtin_amdgcn_update_dpp(0, __builtin_bit_cast(int, v), 0x142, 0xa, 0xf, false));
;     v += __builtin_bit_cast(float, __builtin_amdgcn_update_dpp(0, __builtin_bit_cast(int, v), 0x143, 0xc, 0xf, false));
;     return __builtin_bit_cast(float, __builtin_amdgcn_readlane(__builtin_bit_cast(int, v), 63));
; }
; __device__ __forceinline__ void prep_phase(const Ctx& F, const float* mu, const float* w0, const float* a0, const float* k_k, const float* k_a, const float* r_k) {
;     ...
;             if (t + 6 < 32) { rin[t + 7] = PRL((t + 6) * PRWW); kin[t + 7] = PRL((t + 6) * PRWW + 512); vin[t + 7] = PRL((t + 6) * PRWW + 1024); }
;             asm volatile("" ::: "memory");
;             const float rc = bf2f(rin[t + 1]), kc = bf2f(kin[t + 1]), vc = bf2f(vin[t + 1]), rp = bf2f(rin[t]), kp = bf2f(kin[t]), vp = bf2f(vin[t]);
;             const float r = rc + (rp - rc) * mur, kx = kc + (kp - kc) * muk, vx = vc + (vp - vc) * muv;
;             const float ld = bf2f(outs[t * OP + c]), la = bf2f(outs[32 * OP + t * OP + c]), g = bf2f(outs[64 * OP + t * OP + c]);
;             const float een = -0.87504979f * __builtin_amdgcn_rcpf(1.f + __builtin_amdgcn_exp2f(w0n - 1.44269504f * ld));
;             const float omw = 1.f - __builtin_amdgcn_exp2f(een);
;             const float a = __builtin_amdgcn_rcpf(1.f + __builtin_amdgcn_exp2f(a0n - 1.44269504f * la));
;             const float kkv = kx * kkc; const float n2 = wave_sum_d(kkv * kkv); const float kk = kkv * __builtin_amdgcn_rsqf(fmaxf(n2, 1e-24f));
;             const float kmod = kx * (1.f + (a - 1.f) * kac); const float bb = kk * a;
;             float s_kr = kmod * r, s_bs = s_kr * rkc, s_br = bb * r;
;             wave_sum3(s_kr, s_bs, s_br, lane);
;             const float wr = (1.f - omw) * r - s_br * kk;
;             const unsigned o = ob0 + t * 128u;
;             ST16(SWR, o, f2bf(wr)); ST16(SC, o, f2bf(omw)); ST16(SK, o, f2bf(kmod)); ST16(SV, o, f2bf(vx)); ST16(SKK, o, f2bf(kk)); ST16(SB, o, f2bf(bb));
;             ST16(GG, gb0 + t * 1024u, f2bf(g));
;             if (lane == 0) *(f32x2*)(SCAL + ((size_t)bh * SEQ + pos0 + t) * 2) = (f32x2){s_kr, s_bs};
	v_cvt_f32_f16_e32 v30, v9
	s_waitcnt lgkmcnt(0)
	v_add_f32_e32 v38, v38, v39
	ds_bpermute_b32 v39, v5, v38
	v_sub_f32_e32 v7, v7, v30
	v_fma_mixlo_f16 v7, v164, v7, v9 op_sel_hi:[0,0,1]
	s_waitcnt lgkmcnt(0)
	v_add_f32_e32 v38, v38, v39
	s_nop 0
	v_readlane_b32 s42, v38, 0
	v_readlane_b32 s28, v38, 1
	v_readlane_b32 s43, v38, 2
	v_sub_f32_e32 v38, 1.0, v29
	v_cvt_f16_f32_e32 v29, v29
	v_mul_f32_e32 v39, s28, v36
	v_fma_mixlo_f16 v22, v22, v38, -v39
	global_store_short v40, v22, s[66:67]
	global_store_short v40, v29, s[14:15]
	global_store_short v40, v7, s[18:19]
	v_fma_mixlo_f16 v7, v33, v34, 0
	global_store_short v40, v7, s[20:21]
	v_fma_mixlo_f16 v7, v35, v36, 0
	global_store_short v40, v7, s[22:23]
	v_add_u32_e32 v7, 0x1c00, v2
	global_store_short v40, v15, s[16:17]
	global_store_short v7, v32, s[24:25]
	s_and_saveexec_b64 s[28:29], s[2:3]
	s_cbranch_execz .LBB0_544
	s_lshl_b64 s[44:45], s[26:27], 3
	s_add_u32 s44, s34, s44
	s_addc_u32 s45, s35, s45
	v_mov_b32_e32 v32, s42
	v_mov_b32_e32 v33, s43
	global_store_dwordx2 v139, v[32:33], s[44:45] offset:56
.LBB0_544:
	s_or_b64 exec, exec, s[28:29]
	v_add_u32_e32 v7, 0xc400, v229
	v_add_u32_e32 v9, 0xc800, v229
	v_add_u32_e32 v29, 0xcc00, v229
	global_load_ushort v22, v7, s[12:13]
	global_load_ushort v15, v9, s[12:13]
	s_nop 0
	global_load_ushort v7, v29, s[12:13]
	s_waitcnt vmcnt(61)
	v_cvt_f32_f16_e32 v9, v16
	v_cvt_f32_f16_e32 v29, v23
	ds_read_u16 v32, v185
	ds_read_u16 v33, v176 offset:58496
	ds_read_u16 v34, v176 offset:25216
	v_sub_f32_e32 v8, v8, v9
	v_fma_mix_f32 v8, v160, v8, v16 op_sel_hi:[0,0,1]
	v_sub_f32_e32 v31, v31, v29
	v_fma_mix_f32 v23, v161, v31, v23 op_sel_hi:[0,0,1]
	s_waitcnt lgkmcnt(1)
	v_fma_mix_f32 v31, v33, s31, v171 op_sel_hi:[1,0,0]
	v_mul_f32_e32 v33, v1, v8
	s_waitcnt lgkmcnt(0)
	v_fma_mix_f32 v16, v34, s31, v170 op_sel_hi:[1,0,0]
	v_mul_f32_e32 v34, v33, v33
	v_mov_b32_e32 v35, 0
	v_exp_f32_e32 v31, v31
	v_exp_f32_e32 v16, v16
	v_mov_b32_dpp v35, v34 quad_perm:[1,0,3,2] row_mask:0xf bank_mask:0xf
	v_fmac_f32_e32 v35, v33, v33
	v_add_f32_e32 v31, 1.0, v31
	v_add_f32_e32 v16, 1.0, v16
	v_add_f32_dpp v34, v35, v35 quad_perm:[2,3,0,1] row_mask:0xf bank_mask:0xf bound_ctrl:1
	v_rcp_f32_e32 v16, v16
	s_nop 0
	v_add_f32_dpp v34, v34, v34 row_half_mirror row_mask:0xf bank_mask:0xf bound_ctrl:1
	v_mul_f32_e32 v16, 0xbf600343, v16
	s_nop 0
	v_add_f32_dpp v34, v34, v34 row_mirror row_mask:0xf bank_mask:0xf bound_ctrl:1
	v_exp_f32_e32 v16, v16
	s_nop 0
	v_add_f32_dpp v34, v34, v34 row_bcast:15 row_mask:0xa bank_mask:0xf
	v_sub_f32_e32 v16, 1.0, v16
	s_nop 0
	v_add_f32_dpp v34, v34, v34 row_bcast:31 row_mask:0xc bank_mask:0xf
	v_rcp_f32_e32 v35, v31
	v_readlane_b32 s28, v34, 63
	v_add_f32_e32 v31, -1.0, v35
	s_nop 0
	v_max_f32_e64 v34, s28, s28
	v_max_f32_e32 v34, 0x179abe15, v34
	v_rsq_f32_e32 v34, v34
	v_fma_f32 v37, v156, v31, 1.0
	v_mul_f32_e32 v31, v8, v37
	v_mul_f32_e32 v31, v23, v31
	v_mul_f32_e32 v36, v33, v34
	v_mul_f32_e32 v38, v35, v36
	v_mul_f32_e32 v39, v157, v31
	v_mul_f32_e32 v38, v23, v38
	v_cndmask_b32_e64 v40, v38, v31, s[6:7]
	v_cndmask_b32_e64 v31, v31, v38, s[6:7]
	v_cndmask_b32_e64 v38, 0, v39, s[6:7]
	v_cndmask_b32_e64 v39, v39, 0, s[6:7]
	v_add_f32_dpp v31, v31, v40 quad_perm:[1,0,3,2] row_mask:0xf bank_mask:0xf bound_ctrl:1
	v_or_b32_e32 v40, 0x400, v3
	v_add_f32_dpp v38, v39, v38 quad_perm:[1,0,3,2] row_mask:0xf bank_mask:0xf bound_ctrl:1
	v_cndmask_b32_e64 v39, v38, v31, s[8:9]
	v_cndmask_b32_e64 v31, v31, v38, s[8:9]
	v_fma_mixlo_f16 v8, v8, v37, 0
	s_nop 0
	v_add_f32_dpp v31, v31, v39 quad_perm:[2,3,0,1] row_mask:0xf bank_mask:0xf bound_ctrl:1
	s_nop 1
	v_add_f32_dpp v31, v31, v31 row_ror:4 row_mask:0xf bank_mask:0xf bound_ctrl:1
	s_nop 1
	v_add_f32_dpp v38, v31, v31 row_ror:8 row_mask:0xf bank_mask:0xf bound_ctrl:1
	ds_bpermute_b32 v39, v4, v38
	s_waitcnt vmcnt(60)
	v_cvt_f32_f16_e32 v31, v10
	s_waitcnt lgkmcnt(0)
	v_add_f32_e32 v38, v38, v39
	ds_bpermute_b32 v39, v5, v38
	v_sub_f32_e32 v30, v30, v31
	s_waitcnt lgkmcnt(0)
	v_add_f32_e32 v38, v38, v39
	s_nop 0
	v_readlane_b32 s42, v38, 0
	v_readlane_b32 s28, v38, 1
	v_readlane_b32 s43, v38, 2
	v_sub_f32_e32 v38, 1.0, v16
	v_cvt_f16_f32_e32 v16, v16
	v_mul_f32_e32 v39, s28, v36
	v_fma_mixlo_f16 v23, v23, v38, -v39
	global_store_short v40, v23, s[66:67]
	global_store_short v40, v16, s[14:15]
	global_store_short v40, v8, s[16:17]
	v_fma_mixlo_f16 v8, v164, v30, v10 op_sel_hi:[0,0,1]
	global_store_short v40, v8, s[18:19]
	v_fma_mixlo_f16 v8, v33, v34, 0
	global_store_short v40, v8, s[20:21]
	v_fma_mixlo_f16 v8, v35, v36, 0
	global_store_short v40, v8, s[22:23]
	v_add_u32_e32 v8, 0x2000, v2
	global_store_short v8, v32, s[24:25]
	s_and_saveexec_b64 s[28:29], s[2:3]
	s_cbranch_execz .LBB0_546
	s_lshl_b64 s[44:45], s[26:27], 3
	s_add_u32 s44, s34, s44
	s_addc_u32 s45, s35, s45
	v_mov_b32_e32 v32, s42
	v_mov_b32_e32 v33, s43
	global_store_dwordx2 v139, v[32:33], s[44:45] offset:64
; __device__ __forceinline__ bf16 f2bf(float f) { return (bf16)(pk2(f, 0.f) & 0xffffu); }
; __device__ __forceinline__ float wave_sum_d(float v) {
;     v = row16_sum(v);
;     v += __builtin_bit_cast(float, __builtin_amdgcn_update_dpp(0, __builtin_bit_cast(int, v), 0x142, 0xa, 0xf, false));
;     v += __builtin_bit_cast(float, __builtin_amdgcn_update_dpp(0, __builtin_bit_cast(int, v), 0x143, 0xc, 0xf, false));
;     return __builtin_bit_cast(float, __builtin_amdgcn_readlane(__builtin_bit_cast(int, v), 63));
; }
; __device__ __forceinline__ void prep_phase(const Ctx& F, const float* mu, const float* w0, const float* a0, const float* k_k, const float* k_a, const float* r_k) {
;     ...
;             if (t + 6 < 32) { rin[t + 7] = PRL((t + 6) * PRWW); kin[t + 7] = PRL((t + 6) * PRWW + 512); vin[t + 7] = PRL((t + 6) * PRWW + 1024); }
;             asm volatile("" ::: "memory");
;             const float rc = bf2f(rin[t + 1]), kc = bf2f(kin[t + 1]), vc = bf2f(vin[t + 1]), rp = bf2f(rin[t]), kp = bf2f(kin[t]), vp = bf2f(vin[t]);
;             const float r = rc + (rp - rc) * mur, kx = kc + (kp - kc) * muk, vx = vc + (vp - vc) * muv;
;             const float ld = bf2f(outs[t * OP + c]), la = bf2f(outs[32 * OP + t * OP + c]), g = bf2f(outs[64 * OP + t * OP + c]);
;             const float een = -0.87504979f * __builtin_amdgcn_rcpf(1.f + __builtin_amdgcn_exp2f(w0n - 1.44269504f * ld));
;             const float omw = 1.f - __builtin_amdgcn_exp2f(een);
;             const float a = __builtin_amdgcn_rcpf(1.f + __builtin_amdgcn_exp2f(a0n - 1.44269504f * la));
;             const float kkv = kx * kkc; const float n2 = wave_sum_d(kkv * kkv); const float kk = kkv * __builtin_amdgcn_rsqf(fmaxf(n2, 1e-24f));
;             const float kmod = kx * (1.f + (a - 1.f) * kac); const float bb = kk * a;
;             float s_kr = kmod * r, s_bs = s_kr * rkc, s_br = bb * r;
;             wave_sum3(s_kr, s_bs, s_br, lane);
;             const float wr = (1.f - omw) * r - s_br * kk;
;             const unsigned o = ob0 + t * 128u;
;             ST16(SWR, o, f2bf(wr)); ST16(SC, o, f2bf(omw)); ST16(SK, o, f2bf(kmod)); ST16(SV, o, f2bf(vx)); ST16(SKK, o, f2bf(kk)); ST16(SB, o, f2bf(bb));
;             ST16(GG, gb0 + t * 1024u, f2bf(g));
;             if (lane == 0) *(f32x2*)(SCAL + ((size_t)bh * SEQ + pos0 + t) * 2) = (f32x2){s_kr, s_bs};
.LBB0_546:
	s_or_b64 exec, exec, s[28:29]
	v_add_u32_e32 v8, 0xd200, v229
	v_add_u32_e32 v10, 0xd600, v229
	v_add_u32_e32 v30, 0xda00, v229
	global_load_ushort v23, v8, s[12:13]
	global_load_ushort v16, v10, s[12:13]
	s_nop 0
	global_load_ushort v8, v30, s[12:13]
	s_waitcnt vmcnt(61)
	v_cvt_f32_f16_e32 v10, v17
	ds_read_u16 v33, v186
	ds_read_u16 v32, v176 offset:59536
	ds_read_u16 v34, v176 offset:26256
	v_cvt_f32_f16_e32 v30, v24
	v_mov_b32_e32 v35, 0
	v_sub_f32_e32 v9, v9, v10
	v_fma_mix_f32 v9, v160, v9, v17 op_sel_hi:[0,0,1]
	v_sub_f32_e32 v29, v29, v30
	s_waitcnt lgkmcnt(0)
	v_fma_mix_f32 v17, v34, s31, v170 op_sel_hi:[1,0,0]
	v_mul_f32_e32 v34, v1, v9
	v_fma_mix_f32 v24, v161, v29, v24 op_sel_hi:[0,0,1]
	v_fma_mix_f32 v29, v32, s31, v171 op_sel_hi:[1,0,0]
	v_mul_f32_e32 v32, v34, v34
	v_exp_f32_e32 v29, v29
	v_exp_f32_e32 v17, v17
	v_mov_b32_dpp v35, v32 quad_perm:[1,0,3,2] row_mask:0xf bank_mask:0xf
	v_fmac_f32_e32 v35, v34, v34
	v_add_f32_e32 v29, 1.0, v29
	v_rcp_f32_e32 v29, v29
	v_add_f32_dpp v32, v35, v35 quad_perm:[2,3,0,1] row_mask:0xf bank_mask:0xf bound_ctrl:1
	v_add_f32_e32 v17, 1.0, v17
	s_nop 0
	v_add_f32_dpp v32, v32, v32 row_half_mirror row_mask:0xf bank_mask:0xf bound_ctrl:1
	v_rcp_f32_e32 v17, v17
	s_nop 0
	v_add_f32_dpp v32, v32, v32 row_mirror row_mask:0xf bank_mask:0xf bound_ctrl:1
	v_mul_f32_e32 v17, 0xbf600343, v17
	s_nop 0
	v_add_f32_dpp v32, v32, v32 row_bcast:15 row_mask:0xa bank_mask:0xf
	v_exp_f32_e32 v17, v17
	s_nop 0
	v_add_f32_dpp v32, v32, v32 row_bcast:31 row_mask:0xc bank_mask:0xf
	v_sub_f32_e32 v17, 1.0, v17
	v_readlane_b32 s28, v32, 63
	s_nop 1
	v_max_f32_e64 v32, s28, s28
	v_max_f32_e32 v32, 0x179abe15, v32
	v_rsq_f32_e32 v35, v32
	v_add_f32_e32 v32, -1.0, v29
	v_fma_f32 v37, v156, v32, 1.0
	v_mul_f32_e32 v32, v9, v37
	v_mul_f32_e32 v36, v34, v35
	v_mul_f32_e32 v38, v29, v36
	v_mul_f32_e32 v32, v24, v32
	v_mul_f32_e32 v39, v157, v32
	v_mul_f32_e32 v38, v24, v38
	v_cndmask_b32_e64 v40, v38, v32, s[6:7]
	v_cndmask_b32_e64 v32, v32, v38, s[6:7]
	v_cndmask_b32_e64 v38, 0, v39, s[6:7]
	v_cndmask_b32_e64 v39, v39, 0, s[6:7]
	v_add_f32_dpp v32, v32, v40 quad_perm:[1,0,3,2] row_mask:0xf bank_mask:0xf bound_ctrl:1
	v_or_b32_e32 v40, 0x480, v3
	v_add_f32_dpp v38, v39, v38 quad_perm:[1,0,3,2] row_mask:0xf bank_mask:0xf bound_ctrl:1
	v_cndmask_b32_e64 v39, v38, v32, s[8:9]
	v_cndmask_b32_e64 v32, v32, v38, s[8:9]
	v_fma_mixlo_f16 v9, v9, v37, 0
	s_nop 0
	v_add_f32_dpp v32, v32, v39 quad_perm:[2,3,0,1] row_mask:0xf bank_mask:0xf bound_ctrl:1
	s_nop 1
	v_add_f32_dpp v32, v32, v32 row_ror:4 row_mask:0xf bank_mask:0xf bound_ctrl:1
	s_nop 1
	v_add_f32_dpp v38, v32, v32 row_ror:8 row_mask:0xf bank_mask:0xf bound_ctrl:1
	ds_bpermute_b32 v39, v4, v38
	s_waitcnt vmcnt(60)
	v_cvt_f32_f16_e32 v32, v11
	s_waitcnt lgkmcnt(0)
	v_add_f32_e32 v38, v38, v39
	ds_bpermute_b32 v39, v5, v38
	v_sub_f32_e32 v31, v31, v32
	s_waitcnt lgkmcnt(0)
	v_add_f32_e32 v38, v38, v39
	s_nop 0
	v_readlane_b32 s42, v38, 0
	v_readlane_b32 s28, v38, 1
	v_readlane_b32 s43, v38, 2
	v_sub_f32_e32 v38, 1.0, v17
	v_cvt_f16_f32_e32 v17, v17
	v_mul_f32_e32 v39, s28, v36
	v_fma_mixlo_f16 v24, v24, v38, -v39
	global_store_short v40, v24, s[66:67]
	global_store_short v40, v17, s[14:15]
	global_store_short v40, v9, s[16:17]
	v_fma_mixlo_f16 v9, v164, v31, v11 op_sel_hi:[0,0,1]
	global_store_short v40, v9, s[18:19]
	v_fma_mixlo_f16 v9, v34, v35, 0
	global_store_short v40, v9, s[20:21]
	v_fma_mixlo_f16 v9, v29, v36, 0
	global_store_short v40, v9, s[22:23]
	v_add_u32_e32 v9, 0x2400, v2
	global_store_short v9, v33, s[24:25]
	s_and_saveexec_b64 s[28:29], s[2:3]
	s_cbranch_execz .LBB0_548
	s_lshl_b64 s[44:45], s[26:27], 3
	s_add_u32 s44, s34, s44
	s_addc_u32 s45, s35, s45
	v_mov_b32_e32 v34, s42
	v_mov_b32_e32 v35, s43
	global_store_dwordx2 v139, v[34:35], s[44:45] offset:72
.LBB0_548:
	s_or_b64 exec, exec, s[28:29]
	v_add_u32_e32 v9, 0xe000, v229
	v_add_u32_e32 v11, 0xe400, v229
	v_add_u32_e32 v29, 0xe800, v229
	global_load_ushort v24, v9, s[12:13]
	global_load_ushort v17, v11, s[12:13]
	s_nop 0
	global_load_ushort v9, v29, s[12:13]
	s_waitcnt vmcnt(61)
	v_cvt_f32_f16_e32 v11, v18
	ds_read_u16 v33, v187
	ds_read_u16 v31, v176 offset:60576
	ds_read_u16 v34, v176 offset:27296
	v_cvt_f32_f16_e32 v29, v25
	v_mov_b32_e32 v35, 0
	v_sub_f32_e32 v10, v10, v11
	v_fma_mix_f32 v10, v160, v10, v18 op_sel_hi:[0,0,1]
	v_sub_f32_e32 v30, v30, v29
	s_waitcnt lgkmcnt(0)
	v_fma_mix_f32 v18, v34, s31, v170 op_sel_hi:[1,0,0]
	v_mul_f32_e32 v34, v1, v10
	v_fma_mix_f32 v25, v161, v30, v25 op_sel_hi:[0,0,1]
	v_fma_mix_f32 v30, v31, s31, v171 op_sel_hi:[1,0,0]
	v_mul_f32_e32 v31, v34, v34
	v_exp_f32_e32 v30, v30
	v_exp_f32_e32 v18, v18
	v_mov_b32_dpp v35, v31 quad_perm:[1,0,3,2] row_mask:0xf bank_mask:0xf
	v_fmac_f32_e32 v35, v34, v34
	v_add_f32_e32 v30, 1.0, v30
	v_rcp_f32_e32 v30, v30
	v_add_f32_dpp v31, v35, v35 quad_perm:[2,3,0,1] row_mask:0xf bank_mask:0xf bound_ctrl:1
	v_add_f32_e32 v18, 1.0, v18
	s_nop 0
	v_add_f32_dpp v31, v31, v31 row_half_mirror row_mask:0xf bank_mask:0xf bound_ctrl:1
	v_rcp_f32_e32 v18, v18
	s_nop 0
	v_add_f32_dpp v31, v31, v31 row_mirror row_mask:0xf bank_mask:0xf bound_ctrl:1
	v_mul_f32_e32 v18, 0xbf600343, v18
	s_nop 0
	v_add_f32_dpp v31, v31, v31 row_bcast:15 row_mask:0xa bank_mask:0xf
	v_exp_f32_e32 v18, v18
	s_nop 0
	v_add_f32_dpp v31, v31, v31 row_bcast:31 row_mask:0xc bank_mask:0xf
	v_sub_f32_e32 v18, 1.0, v18
	v_readlane_b32 s28, v31, 63
	s_nop 1
	v_max_f32_e64 v31, s28, s28
	v_max_f32_e32 v31, 0x179abe15, v31
	v_rsq_f32_e32 v35, v31
	v_add_f32_e32 v31, -1.0, v30
	v_fma_f32 v37, v156, v31, 1.0
	v_mul_f32_e32 v31, v10, v37
	v_mul_f32_e32 v36, v34, v35
	v_mul_f32_e32 v38, v30, v36
	v_mul_f32_e32 v31, v25, v31
	v_mul_f32_e32 v39, v157, v31
	v_mul_f32_e32 v38, v25, v38
	v_cndmask_b32_e64 v40, v38, v31, s[6:7]
	v_cndmask_b32_e64 v31, v31, v38, s[6:7]
	v_cndmask_b32_e64 v38, 0, v39, s[6:7]
	v_cndmask_b32_e64 v39, v39, 0, s[6:7]
	v_add_f32_dpp v31, v31, v40 quad_perm:[1,0,3,2] row_mask:0xf bank_mask:0xf bound_ctrl:1
	v_or_b32_e32 v40, 0x500, v3
	v_add_f32_dpp v38, v39, v38 quad_perm:[1,0,3,2] row_mask:0xf bank_mask:0xf bound_ctrl:1
	v_cndmask_b32_e64 v39, v38, v31, s[8:9]
	v_cndmask_b32_e64 v31, v31, v38, s[8:9]
	v_fma_mixlo_f16 v10, v10, v37, 0
	s_nop 0
	v_add_f32_dpp v31, v31, v39 quad_perm:[2,3,0,1] row_mask:0xf bank_mask:0xf bound_ctrl:1
	s_nop 1
	v_add_f32_dpp v31, v31, v31 row_ror:4 row_mask:0xf bank_mask:0xf bound_ctrl:1
	s_nop 1
	v_add_f32_dpp v38, v31, v31 row_ror:8 row_mask:0xf bank_mask:0xf bound_ctrl:1
	ds_bpermute_b32 v39, v4, v38
	s_waitcnt vmcnt(60)
; __device__ __forceinline__ bf16 f2bf(float f) { return (bf16)(pk2(f, 0.f) & 0xffffu); }
; __device__ __forceinline__ float wave_sum_d(float v) {
;     v = row16_sum(v);
;     v += __builtin_bit_cast(float, __builtin_amdgcn_update_dpp(0, __builtin_bit_cast(int, v), 0x142, 0xa, 0xf, false));
;     v += __builtin_bit_cast(float, __builtin_amdgcn_update_dpp(0, __builtin_bit_cast(int, v), 0x143, 0xc, 0xf, false));
;     return __builtin_bit_cast(float, __builtin_amdgcn_readlane(__builtin_bit_cast(int, v), 63));
; }
; __device__ __forceinline__ void prep_phase(const Ctx& F, const float* mu, const float* w0, const float* a0, const float* k_k, const float* k_a, const float* r_k) {
;     ...
;             if (t + 6 < 32) { rin[t + 7] = PRL((t + 6) * PRWW); kin[t + 7] = PRL((t + 6) * PRWW + 512); vin[t + 7] = PRL((t + 6) * PRWW + 1024); }
;             asm volatile("" ::: "memory");
;             const float rc = bf2f(rin[t + 1]), kc = bf2f(kin[t + 1]), vc = bf2f(vin[t + 1]), rp = bf2f(rin[t]), kp = bf2f(kin[t]), vp = bf2f(vin[t]);
;             const float r = rc + (rp - rc) * mur, kx = kc + (kp - kc) * muk, vx = vc + (vp - vc) * muv;
;             const float ld = bf2f(outs[t * OP + c]), la = bf2f(outs[32 * OP + t * OP + c]), g = bf2f(outs[64 * OP + t * OP + c]);
;             const float een = -0.87504979f * __builtin_amdgcn_rcpf(1.f + __builtin_amdgcn_exp2f(w0n - 1.44269504f * ld));
;             const float omw = 1.f - __builtin_amdgcn_exp2f(een);
;             const float a = __builtin_amdgcn_rcpf(1.f + __builtin_amdgcn_exp2f(a0n - 1.44269504f * la));
;             const float kkv = kx * kkc; const float n2 = wave_sum_d(kkv * kkv); const float kk = kkv * __builtin_amdgcn_rsqf(fmaxf(n2, 1e-24f));
;             const float kmod = kx * (1.f + (a - 1.f) * kac); const float bb = kk * a;
;             float s_kr = kmod * r, s_bs = s_kr * rkc, s_br = bb * r;
;             wave_sum3(s_kr, s_bs, s_br, lane);
;             const float wr = (1.f - omw) * r - s_br * kk;
;             const unsigned o = ob0 + t * 128u;
;             ST16(SWR, o, f2bf(wr)); ST16(SC, o, f2bf(omw)); ST16(SK, o, f2bf(kmod)); ST16(SV, o, f2bf(vx)); ST16(SKK, o, f2bf(kk)); ST16(SB, o, f2bf(bb));
;             ST16(GG, gb0 + t * 1024u, f2bf(g));
;             if (lane == 0) *(f32x2*)(SCAL + ((size_t)bh * SEQ + pos0 + t) * 2) = (f32x2){s_kr, s_bs};
	v_cvt_f32_f16_e32 v31, v12
	s_waitcnt lgkmcnt(0)
	v_add_f32_e32 v38, v38, v39
	ds_bpermute_b32 v39, v5, v38
	v_sub_f32_e32 v32, v32, v31
	s_waitcnt lgkmcnt(0)
	v_add_f32_e32 v38, v38, v39
	s_nop 0
	v_readlane_b32 s42, v38, 0
	v_readlane_b32 s28, v38, 1
	v_readlane_b32 s43, v38, 2
	v_sub_f32_e32 v38, 1.0, v18
	v_cvt_f16_f32_e32 v18, v18
	v_mul_f32_e32 v39, s28, v36
	v_fma_mixlo_f16 v25, v25, v38, -v39
	global_store_short v40, v25, s[66:67]
	global_store_short v40, v18, s[14:15]
	global_store_short v40, v10, s[16:17]
	v_fma_mixlo_f16 v10, v164, v32, v12 op_sel_hi:[0,0,1]
	global_store_short v40, v10, s[18:19]
	v_fma_mixlo_f16 v10, v34, v35, 0
	global_store_short v40, v10, s[20:21]
	v_fma_mixlo_f16 v10, v30, v36, 0
	global_store_short v40, v10, s[22:23]
	v_add_u32_e32 v10, 0x2800, v2
	global_store_short v10, v33, s[24:25]
	s_and_saveexec_b64 s[28:29], s[2:3]
	s_cbranch_execz .LBB0_550
	s_lshl_b64 s[44:45], s[26:27], 3
	s_add_u32 s44, s34, s44
	s_addc_u32 s45, s35, s45
	v_mov_b32_e32 v32, s42
	v_mov_b32_e32 v33, s43
	global_store_dwordx2 v139, v[32:33], s[44:45] offset:80
.LBB0_550:
	s_or_b64 exec, exec, s[28:29]
	v_add_u32_e32 v10, 0xee00, v229
	v_add_u32_e32 v12, 0xf200, v229
	v_add_u32_e32 v30, 0xf600, v229
	global_load_ushort v25, v10, s[12:13]
	global_load_ushort v18, v12, s[12:13]
	s_nop 0
	global_load_ushort v10, v30, s[12:13]
	s_waitcnt vmcnt(61)
	v_cvt_f32_f16_e32 v12, v19
	ds_read_u16 v33, v188
	ds_read_u16 v32, v176 offset:61616
	ds_read_u16 v34, v176 offset:28336
	v_cvt_f32_f16_e32 v30, v26
	v_mov_b32_e32 v35, 0
	v_sub_f32_e32 v11, v11, v12
	v_fma_mix_f32 v11, v160, v11, v19 op_sel_hi:[0,0,1]
	v_sub_f32_e32 v29, v29, v30
	s_waitcnt lgkmcnt(0)
	v_fma_mix_f32 v19, v34, s31, v170 op_sel_hi:[1,0,0]
	v_mul_f32_e32 v34, v1, v11
	v_fma_mix_f32 v26, v161, v29, v26 op_sel_hi:[0,0,1]
	v_fma_mix_f32 v29, v32, s31, v171 op_sel_hi:[1,0,0]
	v_mul_f32_e32 v32, v34, v34
	v_exp_f32_e32 v29, v29
	v_exp_f32_e32 v19, v19
	v_mov_b32_dpp v35, v32 quad_perm:[1,0,3,2] row_mask:0xf bank_mask:0xf
	v_fmac_f32_e32 v35, v34, v34
	v_add_f32_e32 v29, 1.0, v29
	v_rcp_f32_e32 v29, v29
	v_add_f32_dpp v32, v35, v35 quad_perm:[2,3,0,1] row_mask:0xf bank_mask:0xf bound_ctrl:1
	v_add_f32_e32 v19, 1.0, v19
	s_nop 0
	v_add_f32_dpp v32, v32, v32 row_half_mirror row_mask:0xf bank_mask:0xf bound_ctrl:1
	v_rcp_f32_e32 v19, v19
	s_nop 0
	v_add_f32_dpp v32, v32, v32 row_mirror row_mask:0xf bank_mask:0xf bound_ctrl:1
	v_mul_f32_e32 v19, 0xbf600343, v19
	s_nop 0
	v_add_f32_dpp v32, v32, v32 row_bcast:15 row_mask:0xa bank_mask:0xf
	v_exp_f32_e32 v19, v19
	s_nop 0
	v_add_f32_dpp v32, v32, v32 row_bcast:31 row_mask:0xc bank_mask:0xf
	v_sub_f32_e32 v19, 1.0, v19
	v_readlane_b32 s28, v32, 63
	s_nop 1
	v_max_f32_e64 v32, s28, s28
	v_max_f32_e32 v32, 0x179abe15, v32
	v_rsq_f32_e32 v35, v32
	v_add_f32_e32 v32, -1.0, v29
	v_fma_f32 v37, v156, v32, 1.0
	v_mul_f32_e32 v32, v11, v37
	v_mul_f32_e32 v36, v34, v35
	v_mul_f32_e32 v38, v29, v36
	v_mul_f32_e32 v32, v26, v32
	v_mul_f32_e32 v39, v157, v32
	v_mul_f32_e32 v38, v26, v38
	v_cndmask_b32_e64 v40, v38, v32, s[6:7]
	v_cndmask_b32_e64 v32, v32, v38, s[6:7]
	v_cndmask_b32_e64 v38, 0, v39, s[6:7]
	v_cndmask_b32_e64 v39, v39, 0, s[6:7]
	v_add_f32_dpp v32, v32, v40 quad_perm:[1,0,3,2] row_mask:0xf bank_mask:0xf bound_ctrl:1
	v_or_b32_e32 v40, 0x580, v3
	v_add_f32_dpp v38, v39, v38 quad_perm:[1,0,3,2] row_mask:0xf bank_mask:0xf bound_ctrl:1
	v_cndmask_b32_e64 v39, v38, v32, s[8:9]
	v_cndmask_b32_e64 v32, v32, v38, s[8:9]
	v_fma_mixlo_f16 v11, v11, v37, 0
	s_nop 0
	v_add_f32_dpp v32, v32, v39 quad_perm:[2,3,0,1] row_mask:0xf bank_mask:0xf bound_ctrl:1
	s_nop 1
	v_add_f32_dpp v32, v32, v32 row_ror:4 row_mask:0xf bank_mask:0xf bound_ctrl:1
	s_nop 1
	v_add_f32_dpp v38, v32, v32 row_ror:8 row_mask:0xf bank_mask:0xf bound_ctrl:1
	ds_bpermute_b32 v39, v4, v38
	s_waitcnt vmcnt(60)
	v_cvt_f32_f16_e32 v32, v13
	s_waitcnt lgkmcnt(0)
	v_add_f32_e32 v38, v38, v39
	ds_bpermute_b32 v39, v5, v38
	v_sub_f32_e32 v31, v31, v32
	s_waitcnt lgkmcnt(0)
	v_add_f32_e32 v38, v38, v39
	s_nop 0
	v_readlane_b32 s42, v38, 0
	v_readlane_b32 s28, v38, 1
	v_readlane_b32 s43, v38, 2
	v_sub_f32_e32 v38, 1.0, v19
	v_cvt_f16_f32_e32 v19, v19
	v_mul_f32_e32 v39, s28, v36
	v_fma_mixlo_f16 v26, v26, v38, -v39
	global_store_short v40, v26, s[66:67]
	global_store_short v40, v19, s[14:15]
	global_store_short v40, v11, s[16:17]
	v_fma_mixlo_f16 v11, v164, v31, v13 op_sel_hi:[0,0,1]
	global_store_short v40, v11, s[18:19]
	v_fma_mixlo_f16 v11, v34, v35, 0
	global_store_short v40, v11, s[20:21]
	v_fma_mixlo_f16 v11, v29, v36, 0
	global_store_short v40, v11, s[22:23]
	v_add_u32_e32 v11, 0x2c00, v2
	global_store_short v11, v33, s[24:25]
	s_and_saveexec_b64 s[28:29], s[2:3]
	s_cbranch_execz .LBB0_552
	s_lshl_b64 s[44:45], s[26:27], 3
	s_add_u32 s44, s34, s44
	s_addc_u32 s45, s35, s45
	v_mov_b32_e32 v34, s42
	v_mov_b32_e32 v35, s43
	global_store_dwordx2 v139, v[34:35], s[44:45] offset:88
; __device__ __forceinline__ bf16 f2bf(float f) { return (bf16)(pk2(f, 0.f) & 0xffffu); }
; __device__ __forceinline__ float wave_sum_d(float v) {
;     v = row16_sum(v);
;     v += __builtin_bit_cast(float, __builtin_amdgcn_update_dpp(0, __builtin_bit_cast(int, v), 0x142, 0xa, 0xf, false));
;     v += __builtin_bit_cast(float, __builtin_amdgcn_update_dpp(0, __builtin_bit_cast(int, v), 0x143, 0xc, 0xf, false));
;     return __builtin_bit_cast(float, __builtin_amdgcn_readlane(__builtin_bit_cast(int, v), 63));
; }
; __device__ __forceinline__ void prep_phase(const Ctx& F, const float* mu, const float* w0, const float* a0, const float* k_k, const float* k_a, const float* r_k) {
;     ...
;             if (t + 6 < 32) { rin[t + 7] = PRL((t + 6) * PRWW); kin[t + 7] = PRL((t + 6) * PRWW + 512); vin[t + 7] = PRL((t + 6) * PRWW + 1024); }
;             asm volatile("" ::: "memory");
;             const float rc = bf2f(rin[t + 1]), kc = bf2f(kin[t + 1]), vc = bf2f(vin[t + 1]), rp = bf2f(rin[t]), kp = bf2f(kin[t]), vp = bf2f(vin[t]);
;             const float r = rc + (rp - rc) * mur, kx = kc + (kp - kc) * muk, vx = vc + (vp - vc) * muv;
;             const float ld = bf2f(outs[t * OP + c]), la = bf2f(outs[32 * OP + t * OP + c]), g = bf2f(outs[64 * OP + t * OP + c]);
;             const float een = -0.87504979f * __builtin_amdgcn_rcpf(1.f + __builtin_amdgcn_exp2f(w0n - 1.44269504f * ld));
;             const float omw = 1.f - __builtin_amdgcn_exp2f(een);
;             const float a = __builtin_amdgcn_rcpf(1.f + __builtin_amdgcn_exp2f(a0n - 1.44269504f * la));
;             const float kkv = kx * kkc; const float n2 = wave_sum_d(kkv * kkv); const float kk = kkv * __builtin_amdgcn_rsqf(fmaxf(n2, 1e-24f));
;             const float kmod = kx * (1.f + (a - 1.f) * kac); const float bb = kk * a;
;             float s_kr = kmod * r, s_bs = s_kr * rkc, s_br = bb * r;
;             wave_sum3(s_kr, s_bs, s_br, lane);
;             const float wr = (1.f - omw) * r - s_br * kk;
;             const unsigned o = ob0 + t * 128u;
;             ST16(SWR, o, f2bf(wr)); ST16(SC, o, f2bf(omw)); ST16(SK, o, f2bf(kmod)); ST16(SV, o, f2bf(vx)); ST16(SKK, o, f2bf(kk)); ST16(SB, o, f2bf(bb));
;             ST16(GG, gb0 + t * 1024u, f2bf(g));
;             if (lane == 0) *(f32x2*)(SCAL + ((size_t)bh * SEQ + pos0 + t) * 2) = (f32x2){s_kr, s_bs};
.LBB0_552:
	s_or_b64 exec, exec, s[28:29]
	v_add_u32_e32 v11, 0xfc00, v229
	v_add_u32_e32 v13, 0x10000, v229
	v_add_u32_e32 v19, 0x10400, v229
	global_load_ushort v26, v11, s[12:13]
	s_nop 0
	global_load_ushort v13, v13, s[12:13]
	s_nop 0
	global_load_ushort v11, v19, s[12:13]
	s_waitcnt vmcnt(61)
	v_cvt_f32_f16_e32 v19, v20
	ds_read_u16 v33, v189
	ds_read_u16 v31, v176 offset:62656
	ds_read_u16 v34, v176 offset:29376
	v_cvt_f32_f16_e32 v29, v27
	v_mov_b32_e32 v35, 0
	v_sub_f32_e32 v12, v12, v19
	v_fma_mix_f32 v12, v160, v12, v20 op_sel_hi:[0,0,1]
	v_sub_f32_e32 v30, v30, v29
	s_waitcnt lgkmcnt(0)
	v_fma_mix_f32 v20, v34, s31, v170 op_sel_hi:[1,0,0]
	v_mul_f32_e32 v34, v1, v12
	v_fma_mix_f32 v27, v161, v30, v27 op_sel_hi:[0,0,1]
	v_fma_mix_f32 v30, v31, s31, v171 op_sel_hi:[1,0,0]
	v_mul_f32_e32 v31, v34, v34
	v_exp_f32_e32 v30, v30
	v_exp_f32_e32 v20, v20
	v_mov_b32_dpp v35, v31 quad_perm:[1,0,3,2] row_mask:0xf bank_mask:0xf
	v_fmac_f32_e32 v35, v34, v34
	v_add_f32_e32 v30, 1.0, v30
	v_rcp_f32_e32 v30, v30
	v_add_f32_dpp v31, v35, v35 quad_perm:[2,3,0,1] row_mask:0xf bank_mask:0xf bound_ctrl:1
	v_add_f32_e32 v20, 1.0, v20
	s_nop 0
	v_add_f32_dpp v31, v31, v31 row_half_mirror row_mask:0xf bank_mask:0xf bound_ctrl:1
	v_rcp_f32_e32 v20, v20
	s_nop 0
	v_add_f32_dpp v31, v31, v31 row_mirror row_mask:0xf bank_mask:0xf bound_ctrl:1
	v_mul_f32_e32 v20, 0xbf600343, v20
	s_nop 0
	v_add_f32_dpp v31, v31, v31 row_bcast:15 row_mask:0xa bank_mask:0xf
	v_exp_f32_e32 v20, v20
	s_nop 0
	v_add_f32_dpp v31, v31, v31 row_bcast:31 row_mask:0xc bank_mask:0xf
	v_sub_f32_e32 v20, 1.0, v20
	v_readlane_b32 s28, v31, 63
	s_nop 1
	v_max_f32_e64 v31, s28, s28
	v_max_f32_e32 v31, 0x179abe15, v31
	v_rsq_f32_e32 v35, v31
	v_add_f32_e32 v31, -1.0, v30
	v_fma_f32 v37, v156, v31, 1.0
	v_mul_f32_e32 v31, v12, v37
	v_mul_f32_e32 v36, v34, v35
	v_mul_f32_e32 v38, v30, v36
	v_mul_f32_e32 v31, v27, v31
	v_mul_f32_e32 v39, v157, v31
	v_mul_f32_e32 v38, v27, v38
	v_cndmask_b32_e64 v40, v38, v31, s[6:7]
	v_cndmask_b32_e64 v31, v31, v38, s[6:7]
	v_cndmask_b32_e64 v38, 0, v39, s[6:7]
	v_cndmask_b32_e64 v39, v39, 0, s[6:7]
	v_add_f32_dpp v31, v31, v40 quad_perm:[1,0,3,2] row_mask:0xf bank_mask:0xf bound_ctrl:1
	v_or_b32_e32 v40, 0x600, v3
	v_add_f32_dpp v38, v39, v38 quad_perm:[1,0,3,2] row_mask:0xf bank_mask:0xf bound_ctrl:1
	v_cndmask_b32_e64 v39, v38, v31, s[8:9]
	v_cndmask_b32_e64 v31, v31, v38, s[8:9]
	v_fma_mixlo_f16 v12, v12, v37, 0
	s_nop 0
	v_add_f32_dpp v31, v31, v39 quad_perm:[2,3,0,1] row_mask:0xf bank_mask:0xf bound_ctrl:1
	s_nop 1
	v_add_f32_dpp v31, v31, v31 row_ror:4 row_mask:0xf bank_mask:0xf bound_ctrl:1
	s_nop 1
	v_add_f32_dpp v38, v31, v31 row_ror:8 row_mask:0xf bank_mask:0xf bound_ctrl:1
	ds_bpermute_b32 v39, v4, v38
	s_waitcnt vmcnt(60)
	v_cvt_f32_f16_e32 v31, v14
	s_waitcnt lgkmcnt(0)
	v_add_f32_e32 v38, v38, v39
	ds_bpermute_b32 v39, v5, v38
	v_sub_f32_e32 v32, v32, v31
	s_waitcnt lgkmcnt(0)
	v_add_f32_e32 v38, v38, v39
	s_nop 0
	v_readlane_b32 s42, v38, 0
	v_readlane_b32 s28, v38, 1
	v_readlane_b32 s43, v38, 2
	v_sub_f32_e32 v38, 1.0, v20
	v_cvt_f16_f32_e32 v20, v20
	v_mul_f32_e32 v39, s28, v36
	v_fma_mixlo_f16 v27, v27, v38, -v39
	global_store_short v40, v27, s[66:67]
	global_store_short v40, v20, s[14:15]
	global_store_short v40, v12, s[16:17]
	v_fma_mixlo_f16 v12, v164, v32, v14 op_sel_hi:[0,0,1]
	global_store_short v40, v12, s[18:19]
	v_fma_mixlo_f16 v12, v34, v35, 0
	global_store_short v40, v12, s[20:21]
	v_fma_mixlo_f16 v12, v30, v36, 0
	global_store_short v40, v12, s[22:23]
	v_add_u32_e32 v12, 0x3000, v2
	global_store_short v12, v33, s[24:25]
	s_and_saveexec_b64 s[28:29], s[2:3]
	s_cbranch_execz .LBB0_554
	s_lshl_b64 s[44:45], s[26:27], 3
	s_add_u32 s44, s34, s44
	s_addc_u32 s45, s35, s45
	v_mov_b32_e32 v32, s42
	v_mov_b32_e32 v33, s43
	global_store_dwordx2 v139, v[32:33], s[44:45] offset:96
.LBB0_554:
	s_or_b64 exec, exec, s[28:29]
	v_add_u32_e32 v12, 0x10a00, v229
	v_add_u32_e32 v14, 0x10e00, v229
	v_add_u32_e32 v27, 0x11200, v229
	global_load_ushort v20, v12, s[12:13]
	s_nop 0
	global_load_ushort v14, v14, s[12:13]
	s_nop 0
	global_load_ushort v12, v27, s[12:13]
	s_waitcnt vmcnt(61)
	v_cvt_f32_f16_e32 v27, v21
	v_cvt_f32_f16_e32 v30, v28
	ds_read_u16 v32, v190
	ds_read_u16 v33, v176 offset:63696
	ds_read_u16 v34, v176 offset:30416
	v_sub_f32_e32 v19, v19, v27
	v_fma_mix_f32 v19, v160, v19, v21 op_sel_hi:[0,0,1]
	v_sub_f32_e32 v29, v29, v30
	v_fma_mix_f32 v28, v161, v29, v28 op_sel_hi:[0,0,1]
	s_waitcnt lgkmcnt(1)
	v_fma_mix_f32 v29, v33, s31, v171 op_sel_hi:[1,0,0]
	v_mul_f32_e32 v33, v1, v19
	s_waitcnt lgkmcnt(0)
	v_fma_mix_f32 v21, v34, s31, v170 op_sel_hi:[1,0,0]
	v_mul_f32_e32 v34, v33, v33
	v_mov_b32_e32 v35, 0
	v_exp_f32_e32 v29, v29
	v_exp_f32_e32 v21, v21
	v_mov_b32_dpp v35, v34 quad_perm:[1,0,3,2] row_mask:0xf bank_mask:0xf
	v_fmac_f32_e32 v35, v33, v33
	v_add_f32_e32 v29, 1.0, v29
	v_add_f32_e32 v21, 1.0, v21
	v_add_f32_dpp v34, v35, v35 quad_perm:[2,3,0,1] row_mask:0xf bank_mask:0xf bound_ctrl:1
	v_rcp_f32_e32 v21, v21
	s_nop 0
	v_add_f32_dpp v34, v34, v34 row_half_mirror row_mask:0xf bank_mask:0xf bound_ctrl:1
	v_mul_f32_e32 v21, 0xbf600343, v21
	s_nop 0
	v_add_f32_dpp v34, v34, v34 row_mirror row_mask:0xf bank_mask:0xf bound_ctrl:1
	v_exp_f32_e32 v21, v21
	s_nop 0
	v_add_f32_dpp v34, v34, v34 row_bcast:15 row_mask:0xa bank_mask:0xf
	v_sub_f32_e32 v21, 1.0, v21
	s_nop 0
	v_add_f32_dpp v34, v34, v34 row_bcast:31 row_mask:0xc bank_mask:0xf
	v_rcp_f32_e32 v35, v29
	v_readlane_b32 s28, v34, 63
	v_add_f32_e32 v29, -1.0, v35
	s_nop 0
	v_max_f32_e64 v34, s28, s28
	v_max_f32_e32 v34, 0x179abe15, v34
	v_rsq_f32_e32 v34, v34
	v_fma_f32 v37, v156, v29, 1.0
	v_mul_f32_e32 v29, v19, v37
	v_mul_f32_e32 v29, v28, v29
	v_mul_f32_e32 v36, v33, v34
	v_mul_f32_e32 v38, v35, v36
	v_mul_f32_e32 v39, v157, v29
	v_mul_f32_e32 v38, v28, v38
	v_cndmask_b32_e64 v40, v38, v29, s[6:7]
	v_cndmask_b32_e64 v29, v29, v38, s[6:7]
	v_cndmask_b32_e64 v38, 0, v39, s[6:7]
	v_cndmask_b32_e64 v39, v39, 0, s[6:7]
	v_add_f32_dpp v29, v29, v40 quad_perm:[1,0,3,2] row_mask:0xf bank_mask:0xf bound_ctrl:1
	v_or_b32_e32 v40, 0x680, v3
	v_add_f32_dpp v38, v39, v38 quad_perm:[1,0,3,2] row_mask:0xf bank_mask:0xf bound_ctrl:1
	v_cndmask_b32_e64 v39, v38, v29, s[8:9]
	v_cndmask_b32_e64 v29, v29, v38, s[8:9]
	v_fma_mixlo_f16 v19, v19, v37, 0
	s_nop 0
	v_add_f32_dpp v29, v29, v39 quad_perm:[2,3,0,1] row_mask:0xf bank_mask:0xf bound_ctrl:1
	s_nop 1
	v_add_f32_dpp v29, v29, v29 row_ror:4 row_mask:0xf bank_mask:0xf bound_ctrl:1
	s_nop 1
	v_add_f32_dpp v38, v29, v29 row_ror:8 row_mask:0xf bank_mask:0xf bound_ctrl:1
	ds_bpermute_b32 v39, v4, v38
	s_waitcnt vmcnt(60)
; __device__ __forceinline__ bf16 f2bf(float f) { return (bf16)(pk2(f, 0.f) & 0xffffu); }
; __device__ __forceinline__ float wave_sum_d(float v) {
;     v = row16_sum(v);
;     v += __builtin_bit_cast(float, __builtin_amdgcn_update_dpp(0, __builtin_bit_cast(int, v), 0x142, 0xa, 0xf, false));
;     v += __builtin_bit_cast(float, __builtin_amdgcn_update_dpp(0, __builtin_bit_cast(int, v), 0x143, 0xc, 0xf, false));
;     return __builtin_bit_cast(float, __builtin_amdgcn_readlane(__builtin_bit_cast(int, v), 63));
; }
; __device__ __forceinline__ void prep_phase(const Ctx& F, const float* mu, const float* w0, const float* a0, const float* k_k, const float* k_a, const float* r_k) {
;     ...
;             if (t + 6 < 32) { rin[t + 7] = PRL((t + 6) * PRWW); kin[t + 7] = PRL((t + 6) * PRWW + 512); vin[t + 7] = PRL((t + 6) * PRWW + 1024); }
;             asm volatile("" ::: "memory");
;             const float rc = bf2f(rin[t + 1]), kc = bf2f(kin[t + 1]), vc = bf2f(vin[t + 1]), rp = bf2f(rin[t]), kp = bf2f(kin[t]), vp = bf2f(vin[t]);
;             const float r = rc + (rp - rc) * mur, kx = kc + (kp - kc) * muk, vx = vc + (vp - vc) * muv;
;             const float ld = bf2f(outs[t * OP + c]), la = bf2f(outs[32 * OP + t * OP + c]), g = bf2f(outs[64 * OP + t * OP + c]);
;             const float een = -0.87504979f * __builtin_amdgcn_rcpf(1.f + __builtin_amdgcn_exp2f(w0n - 1.44269504f * ld));
;             const float omw = 1.f - __builtin_amdgcn_exp2f(een);
;             const float a = __builtin_amdgcn_rcpf(1.f + __builtin_amdgcn_exp2f(a0n - 1.44269504f * la));
;             const float kkv = kx * kkc; const float n2 = wave_sum_d(kkv * kkv); const float kk = kkv * __builtin_amdgcn_rsqf(fmaxf(n2, 1e-24f));
;             const float kmod = kx * (1.f + (a - 1.f) * kac); const float bb = kk * a;
;             float s_kr = kmod * r, s_bs = s_kr * rkc, s_br = bb * r;
;             wave_sum3(s_kr, s_bs, s_br, lane);
;             const float wr = (1.f - omw) * r - s_br * kk;
;             const unsigned o = ob0 + t * 128u;
;             ST16(SWR, o, f2bf(wr)); ST16(SC, o, f2bf(omw)); ST16(SK, o, f2bf(kmod)); ST16(SV, o, f2bf(vx)); ST16(SKK, o, f2bf(kk)); ST16(SB, o, f2bf(bb));
;             ST16(GG, gb0 + t * 1024u, f2bf(g));
;             if (lane == 0) *(f32x2*)(SCAL + ((size_t)bh * SEQ + pos0 + t) * 2) = (f32x2){s_kr, s_bs};
	v_cvt_f32_f16_e32 v29, v6
	s_waitcnt lgkmcnt(0)
	v_add_f32_e32 v38, v38, v39
	ds_bpermute_b32 v39, v5, v38
	v_sub_f32_e32 v31, v31, v29
	v_fma_mixlo_f16 v6, v164, v31, v6 op_sel_hi:[0,0,1]
	s_waitcnt lgkmcnt(0)
	v_add_f32_e32 v38, v38, v39
	s_nop 0
	v_readlane_b32 s42, v38, 0
	v_readlane_b32 s28, v38, 1
	v_readlane_b32 s43, v38, 2
	v_sub_f32_e32 v38, 1.0, v21
	v_cvt_f16_f32_e32 v21, v21
	v_mul_f32_e32 v39, s28, v36
	v_fma_mixlo_f16 v28, v28, v38, -v39
	global_store_short v40, v28, s[66:67]
	global_store_short v40, v21, s[14:15]
	global_store_short v40, v6, s[18:19]
	v_fma_mixlo_f16 v6, v33, v34, 0
	global_store_short v40, v6, s[20:21]
	v_fma_mixlo_f16 v6, v35, v36, 0
	global_store_short v40, v6, s[22:23]
	v_add_u32_e32 v6, 0x3400, v2
	global_store_short v40, v19, s[16:17]
	global_store_short v6, v32, s[24:25]
	s_and_saveexec_b64 s[28:29], s[2:3]
	s_cbranch_execz .LBB0_556
	s_lshl_b64 s[44:45], s[26:27], 3
	s_add_u32 s44, s34, s44
	s_addc_u32 s45, s35, s45
	v_mov_b32_e32 v32, s42
	v_mov_b32_e32 v33, s43
	global_store_dwordx2 v139, v[32:33], s[44:45] offset:104
.LBB0_556:
	s_or_b64 exec, exec, s[28:29]
	v_add_u32_e32 v6, 0x11800, v229
	v_add_u32_e32 v19, 0x11c00, v229
	v_add_u32_e32 v28, 0x12000, v229
	global_load_ushort v21, v6, s[12:13]
	s_nop 0
	global_load_ushort v19, v19, s[12:13]
	s_nop 0
	global_load_ushort v6, v28, s[12:13]
	s_waitcnt vmcnt(61)
	v_cvt_f32_f16_e32 v28, v15
	v_cvt_f32_f16_e32 v31, v22
	ds_read_u16 v32, v191
	ds_read_u16 v33, v176 offset:64736
	ds_read_u16 v34, v176 offset:31456
	v_sub_f32_e32 v27, v27, v28
	v_fma_mix_f32 v15, v160, v27, v15 op_sel_hi:[0,0,1]
	v_sub_f32_e32 v30, v30, v31
	v_fma_mix_f32 v22, v161, v30, v22 op_sel_hi:[0,0,1]
	s_waitcnt lgkmcnt(1)
	v_fma_mix_f32 v30, v33, s31, v171 op_sel_hi:[1,0,0]
	v_mul_f32_e32 v33, v1, v15
	s_waitcnt lgkmcnt(0)
	v_fma_mix_f32 v27, v34, s31, v170 op_sel_hi:[1,0,0]
	v_mul_f32_e32 v34, v33, v33
	v_mov_b32_e32 v35, 0
	v_exp_f32_e32 v30, v30
	v_exp_f32_e32 v27, v27
	v_mov_b32_dpp v35, v34 quad_perm:[1,0,3,2] row_mask:0xf bank_mask:0xf
	v_fmac_f32_e32 v35, v33, v33
	v_add_f32_e32 v30, 1.0, v30
	v_add_f32_e32 v27, 1.0, v27
	v_add_f32_dpp v34, v35, v35 quad_perm:[2,3,0,1] row_mask:0xf bank_mask:0xf bound_ctrl:1
	v_rcp_f32_e32 v27, v27
	s_nop 0
	v_add_f32_dpp v34, v34, v34 row_half_mirror row_mask:0xf bank_mask:0xf bound_ctrl:1
	v_mul_f32_e32 v27, 0xbf600343, v27
	s_nop 0
	v_add_f32_dpp v34, v34, v34 row_mirror row_mask:0xf bank_mask:0xf bound_ctrl:1
	v_exp_f32_e32 v27, v27
	s_nop 0
	v_add_f32_dpp v34, v34, v34 row_bcast:15 row_mask:0xa bank_mask:0xf
	v_sub_f32_e32 v27, 1.0, v27
	s_nop 0
	v_add_f32_dpp v34, v34, v34 row_bcast:31 row_mask:0xc bank_mask:0xf
	v_rcp_f32_e32 v35, v30
	v_readlane_b32 s28, v34, 63
	v_add_f32_e32 v30, -1.0, v35
	s_nop 0
	v_max_f32_e64 v34, s28, s28
	v_max_f32_e32 v34, 0x179abe15, v34
	v_rsq_f32_e32 v34, v34
	v_fma_f32 v37, v156, v30, 1.0
	v_mul_f32_e32 v30, v15, v37
	v_mul_f32_e32 v30, v22, v30
	v_mul_f32_e32 v36, v33, v34
	v_mul_f32_e32 v38, v35, v36
	v_mul_f32_e32 v39, v157, v30
	v_mul_f32_e32 v38, v22, v38
	v_cndmask_b32_e64 v40, v38, v30, s[6:7]
	v_cndmask_b32_e64 v30, v30, v38, s[6:7]
	v_cndmask_b32_e64 v38, 0, v39, s[6:7]
	v_cndmask_b32_e64 v39, v39, 0, s[6:7]
	v_add_f32_dpp v30, v30, v40 quad_perm:[1,0,3,2] row_mask:0xf bank_mask:0xf bound_ctrl:1
	v_or_b32_e32 v40, 0x700, v3
	v_add_f32_dpp v38, v39, v38 quad_perm:[1,0,3,2] row_mask:0xf bank_mask:0xf bound_ctrl:1
	v_cndmask_b32_e64 v39, v38, v30, s[8:9]
	v_cndmask_b32_e64 v30, v30, v38, s[8:9]
	v_fma_mixlo_f16 v15, v15, v37, 0
	s_nop 0
	v_add_f32_dpp v30, v30, v39 quad_perm:[2,3,0,1] row_mask:0xf bank_mask:0xf bound_ctrl:1
	s_nop 1
	v_add_f32_dpp v30, v30, v30 row_ror:4 row_mask:0xf bank_mask:0xf bound_ctrl:1
	s_nop 1
	v_add_f32_dpp v38, v30, v30 row_ror:8 row_mask:0xf bank_mask:0xf bound_ctrl:1
	ds_bpermute_b32 v39, v4, v38
	s_waitcnt vmcnt(60)
	v_cvt_f32_f16_e32 v30, v7
	s_waitcnt lgkmcnt(0)
	v_add_f32_e32 v38, v38, v39
	ds_bpermute_b32 v39, v5, v38
	v_sub_f32_e32 v29, v29, v30
	v_fma_mixlo_f16 v7, v164, v29, v7 op_sel_hi:[0,0,1]
	s_waitcnt lgkmcnt(0)
	v_add_f32_e32 v38, v38, v39
	s_nop 0
	v_readlane_b32 s42, v38, 0
	v_readlane_b32 s28, v38, 1
	v_readlane_b32 s43, v38, 2
	v_sub_f32_e32 v38, 1.0, v27
	v_cvt_f16_f32_e32 v27, v27
	v_mul_f32_e32 v39, s28, v36
	v_fma_mixlo_f16 v22, v22, v38, -v39
	global_store_short v40, v22, s[66:67]
	global_store_short v40, v27, s[14:15]
	global_store_short v40, v7, s[18:19]
	v_fma_mixlo_f16 v7, v33, v34, 0
	global_store_short v40, v7, s[20:21]
	v_fma_mixlo_f16 v7, v35, v36, 0
	global_store_short v40, v7, s[22:23]
	v_add_u32_e32 v7, 0x3800, v2
	global_store_short v40, v15, s[16:17]
	global_store_short v7, v32, s[24:25]
	s_and_saveexec_b64 s[28:29], s[2:3]
	s_cbranch_execz .LBB0_558
	s_lshl_b64 s[44:45], s[26:27], 3
	s_add_u32 s44, s34, s44
	s_addc_u32 s45, s35, s45
	v_mov_b32_e32 v32, s42
	v_mov_b32_e32 v33, s43
	global_store_dwordx2 v139, v[32:33], s[44:45] offset:112
; __device__ __forceinline__ bf16 f2bf(float f) { return (bf16)(pk2(f, 0.f) & 0xffffu); }
; __device__ __forceinline__ float wave_sum_d(float v) {
;     v = row16_sum(v);
;     v += __builtin_bit_cast(float, __builtin_amdgcn_update_dpp(0, __builtin_bit_cast(int, v), 0x142, 0xa, 0xf, false));
;     v += __builtin_bit_cast(float, __builtin_amdgcn_update_dpp(0, __builtin_bit_cast(int, v), 0x143, 0xc, 0xf, false));
;     return __builtin_bit_cast(float, __builtin_amdgcn_readlane(__builtin_bit_cast(int, v), 63));
; }
; __device__ __forceinline__ void prep_phase(const Ctx& F, const float* mu, const float* w0, const float* a0, const float* k_k, const float* k_a, const float* r_k) {
;     ...
;             if (t + 6 < 32) { rin[t + 7] = PRL((t + 6) * PRWW); kin[t + 7] = PRL((t + 6) * PRWW + 512); vin[t + 7] = PRL((t + 6) * PRWW + 1024); }
;             asm volatile("" ::: "memory");
;             const float rc = bf2f(rin[t + 1]), kc = bf2f(kin[t + 1]), vc = bf2f(vin[t + 1]), rp = bf2f(rin[t]), kp = bf2f(kin[t]), vp = bf2f(vin[t]);
;             const float r = rc + (rp - rc) * mur, kx = kc + (kp - kc) * muk, vx = vc + (vp - vc) * muv;
;             const float ld = bf2f(outs[t * OP + c]), la = bf2f(outs[32 * OP + t * OP + c]), g = bf2f(outs[64 * OP + t * OP + c]);
;             const float een = -0.87504979f * __builtin_amdgcn_rcpf(1.f + __builtin_amdgcn_exp2f(w0n - 1.44269504f * ld));
;             const float omw = 1.f - __builtin_amdgcn_exp2f(een);
;             const float a = __builtin_amdgcn_rcpf(1.f + __builtin_amdgcn_exp2f(a0n - 1.44269504f * la));
;             const float kkv = kx * kkc; const float n2 = wave_sum_d(kkv * kkv); const float kk = kkv * __builtin_amdgcn_rsqf(fmaxf(n2, 1e-24f));
;             const float kmod = kx * (1.f + (a - 1.f) * kac); const float bb = kk * a;
;             float s_kr = kmod * r, s_bs = s_kr * rkc, s_br = bb * r;
;             wave_sum3(s_kr, s_bs, s_br, lane);
;             const float wr = (1.f - omw) * r - s_br * kk;
;             const unsigned o = ob0 + t * 128u;
;             ST16(SWR, o, f2bf(wr)); ST16(SC, o, f2bf(omw)); ST16(SK, o, f2bf(kmod)); ST16(SV, o, f2bf(vx)); ST16(SKK, o, f2bf(kk)); ST16(SB, o, f2bf(bb));
;             ST16(GG, gb0 + t * 1024u, f2bf(g));
;             if (lane == 0) *(f32x2*)(SCAL + ((size_t)bh * SEQ + pos0 + t) * 2) = (f32x2){s_kr, s_bs};
.LBB0_558:
	s_or_b64 exec, exec, s[28:29]
	v_add_u32_e32 v7, 0x12600, v229
	v_add_u32_e32 v15, 0x12a00, v229
	v_add_u32_e32 v27, 0x12e00, v229
	global_load_ushort v22, v7, s[12:13]
	s_nop 0
	global_load_ushort v15, v15, s[12:13]
	s_nop 0
	global_load_ushort v7, v27, s[12:13]
	ds_read_u16 v32, v192
	s_waitcnt vmcnt(62)
	v_cvt_f32_f16_e32 v29, v23
	s_waitcnt vmcnt(61)
	v_cvt_f32_f16_e32 v27, v16
	v_mov_b32_e32 v35, 0
	v_sub_f32_e32 v31, v31, v29
	s_waitcnt lgkmcnt(0)
	v_fma_mix_f32 v32, v32, s31, v171 op_sel_hi:[1,0,0]
	v_fma_mix_f32 v23, v161, v31, v23 op_sel_hi:[0,0,1]
	ds_read_u16 v31, v176 offset:32496
	ds_read_u16 v33, v193
	v_exp_f32_e32 v32, v32
	v_sub_f32_e32 v28, v28, v27
	v_fma_mix_f32 v16, v160, v28, v16 op_sel_hi:[0,0,1]
	s_waitcnt lgkmcnt(1)
	v_fma_mix_f32 v28, v31, s31, v170 op_sel_hi:[1,0,0]
	v_add_f32_e32 v31, 1.0, v32
	v_mul_f32_e32 v32, v1, v16
	v_mul_f32_e32 v34, v32, v32
	v_exp_f32_e32 v28, v28
	s_nop 0
	v_mov_b32_dpp v35, v34 quad_perm:[1,0,3,2] row_mask:0xf bank_mask:0xf
	v_fmac_f32_e32 v35, v32, v32
	v_add_f32_e32 v28, 1.0, v28
	v_rcp_f32_e32 v28, v28
	v_add_f32_dpp v34, v35, v35 quad_perm:[2,3,0,1] row_mask:0xf bank_mask:0xf bound_ctrl:1
	v_mul_f32_e32 v28, 0xbf600343, v28
	s_nop 0
	v_add_f32_dpp v34, v34, v34 row_half_mirror row_mask:0xf bank_mask:0xf bound_ctrl:1
	v_exp_f32_e32 v28, v28
	s_nop 0
	v_add_f32_dpp v34, v34, v34 row_mirror row_mask:0xf bank_mask:0xf bound_ctrl:1
	v_sub_f32_e32 v28, 1.0, v28
	s_nop 0
	v_add_f32_dpp v34, v34, v34 row_bcast:15 row_mask:0xa bank_mask:0xf
	s_nop 1
	v_add_f32_dpp v34, v34, v34 row_bcast:31 row_mask:0xc bank_mask:0xf
	v_rcp_f32_e32 v35, v31
	v_readlane_b32 s28, v34, 63
	v_add_f32_e32 v31, -1.0, v35
	s_nop 0
	v_max_f32_e64 v34, s28, s28
	v_max_f32_e32 v34, 0x179abe15, v34
	v_rsq_f32_e32 v34, v34
	v_fma_f32 v37, v156, v31, 1.0
	v_mul_f32_e32 v31, v16, v37
	v_mul_f32_e32 v31, v23, v31
	v_mul_f32_e32 v36, v32, v34
	v_mul_f32_e32 v38, v35, v36
	v_mul_f32_e32 v39, v157, v31
	v_mul_f32_e32 v38, v23, v38
	v_cndmask_b32_e64 v40, v38, v31, s[6:7]
	v_cndmask_b32_e64 v31, v31, v38, s[6:7]
	v_cndmask_b32_e64 v38, 0, v39, s[6:7]
	v_cndmask_b32_e64 v39, v39, 0, s[6:7]
	v_add_f32_dpp v31, v31, v40 quad_perm:[1,0,3,2] row_mask:0xf bank_mask:0xf bound_ctrl:1
	v_or_b32_e32 v40, 0x780, v3
	v_add_f32_dpp v38, v39, v38 quad_perm:[1,0,3,2] row_mask:0xf bank_mask:0xf bound_ctrl:1
	v_cndmask_b32_e64 v39, v38, v31, s[8:9]
	v_cndmask_b32_e64 v31, v31, v38, s[8:9]
	v_fma_mixlo_f16 v16, v16, v37, 0
	s_nop 0
	v_add_f32_dpp v31, v31, v39 quad_perm:[2,3,0,1] row_mask:0xf bank_mask:0xf bound_ctrl:1
	s_nop 1
	v_add_f32_dpp v31, v31, v31 row_ror:4 row_mask:0xf bank_mask:0xf bound_ctrl:1
	s_nop 1
	v_add_f32_dpp v38, v31, v31 row_ror:8 row_mask:0xf bank_mask:0xf bound_ctrl:1
	ds_bpermute_b32 v39, v4, v38
	s_waitcnt vmcnt(60)
	v_cvt_f32_f16_e32 v31, v8
	s_waitcnt lgkmcnt(0)
	v_add_f32_e32 v38, v38, v39
	ds_bpermute_b32 v39, v5, v38
	v_sub_f32_e32 v30, v30, v31
	v_fma_mixlo_f16 v8, v164, v30, v8 op_sel_hi:[0,0,1]
	s_waitcnt lgkmcnt(0)
	v_add_f32_e32 v38, v38, v39
	s_nop 0
	v_readlane_b32 s42, v38, 0
	v_readlane_b32 s28, v38, 1
	v_readlane_b32 s43, v38, 2
	v_sub_f32_e32 v38, 1.0, v28
	v_cvt_f16_f32_e32 v28, v28
	v_mul_f32_e32 v39, s28, v36
	v_fma_mixlo_f16 v23, v23, v38, -v39
	global_store_short v40, v23, s[66:67]
	global_store_short v40, v28, s[14:15]
	global_store_short v40, v8, s[18:19]
	v_fma_mixlo_f16 v8, v32, v34, 0
	global_store_short v40, v8, s[20:21]
	v_fma_mixlo_f16 v8, v35, v36, 0
	global_store_short v40, v8, s[22:23]
	v_add_u32_e32 v8, 0x3c00, v2
	global_store_short v40, v16, s[16:17]
	global_store_short v8, v33, s[24:25]
	s_and_saveexec_b64 s[28:29], s[2:3]
	s_cbranch_execz .LBB0_560
	s_lshl_b64 s[44:45], s[26:27], 3
	s_add_u32 s44, s34, s44
	s_addc_u32 s45, s35, s45
	v_mov_b32_e32 v32, s42
	v_mov_b32_e32 v33, s43
	global_store_dwordx2 v139, v[32:33], s[44:45] offset:120
.LBB0_560:
	s_or_b64 exec, exec, s[28:29]
	v_add_u32_e32 v8, 0x13400, v229
	v_add_u32_e32 v16, 0x13800, v229
	v_add_u32_e32 v28, 0x13c00, v229
	global_load_ushort v23, v8, s[12:13]
	s_nop 0
	global_load_ushort v16, v16, s[12:13]
	s_nop 0
	global_load_ushort v8, v28, s[12:13]
	ds_read_u16 v32, v194
	s_waitcnt vmcnt(62)
	v_cvt_f32_f16_e32 v30, v24
	s_waitcnt vmcnt(61)
	v_cvt_f32_f16_e32 v28, v17
	v_mov_b32_e32 v35, 0
	v_sub_f32_e32 v29, v29, v30
	s_waitcnt lgkmcnt(0)
	v_fma_mix_f32 v32, v32, s31, v171 op_sel_hi:[1,0,0]
	v_fma_mix_f32 v24, v161, v29, v24 op_sel_hi:[0,0,1]
	ds_read_u16 v29, v176 offset:33536
	ds_read_u16 v33, v195
	v_exp_f32_e32 v32, v32
	v_sub_f32_e32 v27, v27, v28
	v_fma_mix_f32 v17, v160, v27, v17 op_sel_hi:[0,0,1]
	v_mul_f32_e32 v34, v1, v17
	s_waitcnt lgkmcnt(1)
; __device__ __forceinline__ bf16 f2bf(float f) { return (bf16)(pk2(f, 0.f) & 0xffffu); }
; __device__ __forceinline__ float wave_sum_d(float v) {
;     v = row16_sum(v);
;     v += __builtin_bit_cast(float, __builtin_amdgcn_update_dpp(0, __builtin_bit_cast(int, v), 0x142, 0xa, 0xf, false));
;     v += __builtin_bit_cast(float, __builtin_amdgcn_update_dpp(0, __builtin_bit_cast(int, v), 0x143, 0xc, 0xf, false));
;     return __builtin_bit_cast(float, __builtin_amdgcn_readlane(__builtin_bit_cast(int, v), 63));
; }
; __device__ __forceinline__ void prep_phase(const Ctx& F, const float* mu, const float* w0, const float* a0, const float* k_k, const float* k_a, const float* r_k) {
;     ...
;             if (t + 6 < 32) { rin[t + 7] = PRL((t + 6) * PRWW); kin[t + 7] = PRL((t + 6) * PRWW + 512); vin[t + 7] = PRL((t + 6) * PRWW + 1024); }
;             asm volatile("" ::: "memory");
;             const float rc = bf2f(rin[t + 1]), kc = bf2f(kin[t + 1]), vc = bf2f(vin[t + 1]), rp = bf2f(rin[t]), kp = bf2f(kin[t]), vp = bf2f(vin[t]);
;             const float r = rc + (rp - rc) * mur, kx = kc + (kp - kc) * muk, vx = vc + (vp - vc) * muv;
;             const float ld = bf2f(outs[t * OP + c]), la = bf2f(outs[32 * OP + t * OP + c]), g = bf2f(outs[64 * OP + t * OP + c]);
;             const float een = -0.87504979f * __builtin_amdgcn_rcpf(1.f + __builtin_amdgcn_exp2f(w0n - 1.44269504f * ld));
;             const float omw = 1.f - __builtin_amdgcn_exp2f(een);
;             const float a = __builtin_amdgcn_rcpf(1.f + __builtin_amdgcn_exp2f(a0n - 1.44269504f * la));
;             const float kkv = kx * kkc; const float n2 = wave_sum_d(kkv * kkv); const float kk = kkv * __builtin_amdgcn_rsqf(fmaxf(n2, 1e-24f));
;             const float kmod = kx * (1.f + (a - 1.f) * kac); const float bb = kk * a;
;             float s_kr = kmod * r, s_bs = s_kr * rkc, s_br = bb * r;
;             wave_sum3(s_kr, s_bs, s_br, lane);
;             const float wr = (1.f - omw) * r - s_br * kk;
;             const unsigned o = ob0 + t * 128u;
;             ST16(SWR, o, f2bf(wr)); ST16(SC, o, f2bf(omw)); ST16(SK, o, f2bf(kmod)); ST16(SV, o, f2bf(vx)); ST16(SKK, o, f2bf(kk)); ST16(SB, o, f2bf(bb));
;             ST16(GG, gb0 + t * 1024u, f2bf(g));
;             if (lane == 0) *(f32x2*)(SCAL + ((size_t)bh * SEQ + pos0 + t) * 2) = (f32x2){s_kr, s_bs};
	v_fma_mix_f32 v27, v29, s31, v170 op_sel_hi:[1,0,0]
	v_add_f32_e32 v29, 1.0, v32
	v_mul_f32_e32 v32, v34, v34
	v_rcp_f32_e32 v29, v29
	v_exp_f32_e32 v27, v27
	v_mov_b32_dpp v35, v32 quad_perm:[1,0,3,2] row_mask:0xf bank_mask:0xf
	v_fmac_f32_e32 v35, v34, v34
	v_add_f32_e32 v27, 1.0, v27
	s_nop 0
	v_add_f32_dpp v32, v35, v35 quad_perm:[2,3,0,1] row_mask:0xf bank_mask:0xf bound_ctrl:1
	v_rcp_f32_e32 v27, v27
	s_nop 0
	v_add_f32_dpp v32, v32, v32 row_half_mirror row_mask:0xf bank_mask:0xf bound_ctrl:1
	v_mul_f32_e32 v27, 0xbf600343, v27
	s_nop 0
	v_add_f32_dpp v32, v32, v32 row_mirror row_mask:0xf bank_mask:0xf bound_ctrl:1
	v_exp_f32_e32 v27, v27
	s_nop 0
	v_add_f32_dpp v32, v32, v32 row_bcast:15 row_mask:0xa bank_mask:0xf
	v_sub_f32_e32 v27, 1.0, v27
	s_nop 0
	v_add_f32_dpp v32, v32, v32 row_bcast:31 row_mask:0xc bank_mask:0xf
	s_nop 0
	v_readlane_b32 s28, v32, 63
	s_nop 1
	v_max_f32_e64 v32, s28, s28
	v_max_f32_e32 v32, 0x179abe15, v32
	v_rsq_f32_e32 v35, v32
	v_add_f32_e32 v32, -1.0, v29
	v_fma_f32 v37, v156, v32, 1.0
	v_mul_f32_e32 v32, v17, v37
	v_mul_f32_e32 v36, v34, v35
	v_mul_f32_e32 v38, v29, v36
	v_mul_f32_e32 v32, v24, v32
	v_mul_f32_e32 v39, v157, v32
	v_mul_f32_e32 v38, v24, v38
	v_cndmask_b32_e64 v40, v38, v32, s[6:7]
	v_cndmask_b32_e64 v32, v32, v38, s[6:7]
	v_cndmask_b32_e64 v38, 0, v39, s[6:7]
	v_cndmask_b32_e64 v39, v39, 0, s[6:7]
	v_add_f32_dpp v32, v32, v40 quad_perm:[1,0,3,2] row_mask:0xf bank_mask:0xf bound_ctrl:1
	v_or_b32_e32 v40, 0x800, v3
	v_add_f32_dpp v38, v39, v38 quad_perm:[1,0,3,2] row_mask:0xf bank_mask:0xf bound_ctrl:1
	v_cndmask_b32_e64 v39, v38, v32, s[8:9]
	v_cndmask_b32_e64 v32, v32, v38, s[8:9]
	v_fma_mixlo_f16 v17, v17, v37, 0
	s_nop 0
	v_add_f32_dpp v32, v32, v39 quad_perm:[2,3,0,1] row_mask:0xf bank_mask:0xf bound_ctrl:1
	s_nop 1
	v_add_f32_dpp v32, v32, v32 row_ror:4 row_mask:0xf bank_mask:0xf bound_ctrl:1
	s_nop 1
	v_add_f32_dpp v38, v32, v32 row_ror:8 row_mask:0xf bank_mask:0xf bound_ctrl:1
	ds_bpermute_b32 v39, v4, v38
	s_waitcnt vmcnt(60)
	v_cvt_f32_f16_e32 v32, v9
	s_waitcnt lgkmcnt(0)
	v_add_f32_e32 v38, v38, v39
	ds_bpermute_b32 v39, v5, v38
	v_sub_f32_e32 v31, v31, v32
	v_fma_mixlo_f16 v9, v164, v31, v9 op_sel_hi:[0,0,1]
	s_waitcnt lgkmcnt(0)
	v_add_f32_e32 v38, v38, v39
	s_nop 0
	v_readlane_b32 s42, v38, 0
	v_readlane_b32 s28, v38, 1
	v_readlane_b32 s43, v38, 2
	v_sub_f32_e32 v38, 1.0, v27
	v_cvt_f16_f32_e32 v27, v27
	v_mul_f32_e32 v39, s28, v36
	v_fma_mixlo_f16 v24, v24, v38, -v39
	global_store_short v40, v24, s[66:67]
	global_store_short v40, v27, s[14:15]
	global_store_short v40, v9, s[18:19]
	v_fma_mixlo_f16 v9, v34, v35, 0
	global_store_short v40, v9, s[20:21]
	v_fma_mixlo_f16 v9, v29, v36, 0
	global_store_short v40, v9, s[22:23]
	v_add_u32_e32 v9, 0x4000, v2
	global_store_short v40, v17, s[16:17]
	global_store_short v9, v33, s[24:25]
	s_and_saveexec_b64 s[28:29], s[2:3]
	s_cbranch_execz .LBB0_562
	s_lshl_b64 s[44:45], s[26:27], 3
	s_add_u32 s44, s34, s44
	s_addc_u32 s45, s35, s45
	v_mov_b32_e32 v34, s42
	v_mov_b32_e32 v35, s43
	global_store_dwordx2 v139, v[34:35], s[44:45] offset:128
.LBB0_562:
	s_or_b64 exec, exec, s[28:29]
	v_add_u32_e32 v9, 0x14200, v229
	v_add_u32_e32 v17, 0x14600, v229
	v_add_u32_e32 v27, 0x14a00, v229
	global_load_ushort v24, v9, s[12:13]
	s_nop 0
	global_load_ushort v17, v17, s[12:13]
	s_nop 0
	global_load_ushort v9, v27, s[12:13]
	ds_read_u16 v31, v196
	s_waitcnt vmcnt(62)
	v_cvt_f32_f16_e32 v29, v25
	s_waitcnt vmcnt(61)
	v_cvt_f32_f16_e32 v27, v18
	v_mov_b32_e32 v35, 0
	v_sub_f32_e32 v30, v30, v29
	s_waitcnt lgkmcnt(0)
	v_fma_mix_f32 v31, v31, s31, v171 op_sel_hi:[1,0,0]
	v_fma_mix_f32 v25, v161, v30, v25 op_sel_hi:[0,0,1]
	ds_read_u16 v30, v176 offset:34576
	ds_read_u16 v33, v197
	v_exp_f32_e32 v31, v31
	v_sub_f32_e32 v28, v28, v27
	v_fma_mix_f32 v18, v160, v28, v18 op_sel_hi:[0,0,1]
	v_mul_f32_e32 v34, v1, v18
	s_waitcnt lgkmcnt(1)
	v_fma_mix_f32 v28, v30, s31, v170 op_sel_hi:[1,0,0]
	v_add_f32_e32 v30, 1.0, v31
	v_mul_f32_e32 v31, v34, v34
	v_rcp_f32_e32 v30, v30
	v_exp_f32_e32 v28, v28
	v_mov_b32_dpp v35, v31 quad_perm:[1,0,3,2] row_mask:0xf bank_mask:0xf
	v_fmac_f32_e32 v35, v34, v34
	v_add_f32_e32 v28, 1.0, v28
	s_nop 0
	v_add_f32_dpp v31, v35, v35 quad_perm:[2,3,0,1] row_mask:0xf bank_mask:0xf bound_ctrl:1
	v_rcp_f32_e32 v28, v28
	s_nop 0
	v_add_f32_dpp v31, v31, v31 row_half_mirror row_mask:0xf bank_mask:0xf bound_ctrl:1
	v_mul_f32_e32 v28, 0xbf600343, v28
	s_nop 0
	v_add_f32_dpp v31, v31, v31 row_mirror row_mask:0xf bank_mask:0xf bound_ctrl:1
	v_exp_f32_e32 v28, v28
	s_nop 0
	v_add_f32_dpp v31, v31, v31 row_bcast:15 row_mask:0xa bank_mask:0xf
	v_sub_f32_e32 v28, 1.0, v28
	s_nop 0
	v_add_f32_dpp v31, v31, v31 row_bcast:31 row_mask:0xc bank_mask:0xf
	s_nop 0
	v_readlane_b32 s28, v31, 63
	s_nop 1
	v_max_f32_e64 v31, s28, s28
	v_max_f32_e32 v31, 0x179abe15, v31
	v_rsq_f32_e32 v35, v31
	v_add_f32_e32 v31, -1.0, v30
	v_fma_f32 v37, v156, v31, 1.0
	v_mul_f32_e32 v31, v18, v37
	v_mul_f32_e32 v36, v34, v35
	v_mul_f32_e32 v38, v30, v36
	v_mul_f32_e32 v31, v25, v31
	v_mul_f32_e32 v39, v157, v31
	v_mul_f32_e32 v38, v25, v38
	v_cndmask_b32_e64 v40, v38, v31, s[6:7]
	v_cndmask_b32_e64 v31, v31, v38, s[6:7]
	v_cndmask_b32_e64 v38, 0, v39, s[6:7]
	v_cndmask_b32_e64 v39, v39, 0, s[6:7]
	v_add_f32_dpp v31, v31, v40 quad_perm:[1,0,3,2] row_mask:0xf bank_mask:0xf bound_ctrl:1
	v_or_b32_e32 v40, 0x880, v3
	v_add_f32_dpp v38, v39, v38 quad_perm:[1,0,3,2] row_mask:0xf bank_mask:0xf bound_ctrl:1
	v_cndmask_b32_e64 v39, v38, v31, s[8:9]
	v_cndmask_b32_e64 v31, v31, v38, s[8:9]
	v_fma_mixlo_f16 v18, v18, v37, 0
	s_nop 0
	v_add_f32_dpp v31, v31, v39 quad_perm:[2,3,0,1] row_mask:0xf bank_mask:0xf bound_ctrl:1
	s_nop 1
	v_add_f32_dpp v31, v31, v31 row_ror:4 row_mask:0xf bank_mask:0xf bound_ctrl:1
	s_nop 1
	v_add_f32_dpp v38, v31, v31 row_ror:8 row_mask:0xf bank_mask:0xf bound_ctrl:1
	ds_bpermute_b32 v39, v4, v38
	s_waitcnt vmcnt(60)
	v_cvt_f32_f16_e32 v31, v10
	s_waitcnt lgkmcnt(0)
	v_add_f32_e32 v38, v38, v39
	ds_bpermute_b32 v39, v5, v38
	v_sub_f32_e32 v32, v32, v31
	v_fma_mixlo_f16 v10, v164, v32, v10 op_sel_hi:[0,0,1]
	s_waitcnt lgkmcnt(0)
	v_add_f32_e32 v38, v38, v39
	s_nop 0
	v_readlane_b32 s42, v38, 0
	v_readlane_b32 s28, v38, 1
	v_readlane_b32 s43, v38, 2
	v_sub_f32_e32 v38, 1.0, v28
	v_cvt_f16_f32_e32 v28, v28
	v_mul_f32_e32 v39, s28, v36
	v_fma_mixlo_f16 v25, v25, v38, -v39
	global_store_short v40, v25, s[66:67]
	global_store_short v40, v28, s[14:15]
	global_store_short v40, v10, s[18:19]
	v_fma_mixlo_f16 v10, v34, v35, 0
	global_store_short v40, v10, s[20:21]
	v_fma_mixlo_f16 v10, v30, v36, 0
	global_store_short v40, v10, s[22:23]
	v_add_u32_e32 v10, 0x4400, v2
	global_store_short v40, v18, s[16:17]
	global_store_short v10, v33, s[24:25]
	s_and_saveexec_b64 s[28:29], s[2:3]
	s_cbranch_execz .LBB0_564
	s_lshl_b64 s[44:45], s[26:27], 3
	s_add_u32 s44, s34, s44
	s_addc_u32 s45, s35, s45
	v_mov_b32_e32 v32, s42
	v_mov_b32_e32 v33, s43
	global_store_dwordx2 v139, v[32:33], s[44:45] offset:136
; __device__ __forceinline__ bf16 f2bf(float f) { return (bf16)(pk2(f, 0.f) & 0xffffu); }
; __device__ __forceinline__ float wave_sum_d(float v) {
;     v = row16_sum(v);
;     v += __builtin_bit_cast(float, __builtin_amdgcn_update_dpp(0, __builtin_bit_cast(int, v), 0x142, 0xa, 0xf, false));
;     v += __builtin_bit_cast(float, __builtin_amdgcn_update_dpp(0, __builtin_bit_cast(int, v), 0x143, 0xc, 0xf, false));
;     return __builtin_bit_cast(float, __builtin_amdgcn_readlane(__builtin_bit_cast(int, v), 63));
; }
; __device__ __forceinline__ void prep_phase(const Ctx& F, const float* mu, const float* w0, const float* a0, const float* k_k, const float* k_a, const float* r_k) {
;     ...
;             if (t + 6 < 32) { rin[t + 7] = PRL((t + 6) * PRWW); kin[t + 7] = PRL((t + 6) * PRWW + 512); vin[t + 7] = PRL((t + 6) * PRWW + 1024); }
;             asm volatile("" ::: "memory");
;             const float rc = bf2f(rin[t + 1]), kc = bf2f(kin[t + 1]), vc = bf2f(vin[t + 1]), rp = bf2f(rin[t]), kp = bf2f(kin[t]), vp = bf2f(vin[t]);
;             const float r = rc + (rp - rc) * mur, kx = kc + (kp - kc) * muk, vx = vc + (vp - vc) * muv;
;             const float ld = bf2f(outs[t * OP + c]), la = bf2f(outs[32 * OP + t * OP + c]), g = bf2f(outs[64 * OP + t * OP + c]);
;             const float een = -0.87504979f * __builtin_amdgcn_rcpf(1.f + __builtin_amdgcn_exp2f(w0n - 1.44269504f * ld));
;             const float omw = 1.f - __builtin_amdgcn_exp2f(een);
;             const float a = __builtin_amdgcn_rcpf(1.f + __builtin_amdgcn_exp2f(a0n - 1.44269504f * la));
;             const float kkv = kx * kkc; const float n2 = wave_sum_d(kkv * kkv); const float kk = kkv * __builtin_amdgcn_rsqf(fmaxf(n2, 1e-24f));
;             const float kmod = kx * (1.f + (a - 1.f) * kac); const float bb = kk * a;
;             float s_kr = kmod * r, s_bs = s_kr * rkc, s_br = bb * r;
;             wave_sum3(s_kr, s_bs, s_br, lane);
;             const float wr = (1.f - omw) * r - s_br * kk;
;             const unsigned o = ob0 + t * 128u;
;             ST16(SWR, o, f2bf(wr)); ST16(SC, o, f2bf(omw)); ST16(SK, o, f2bf(kmod)); ST16(SV, o, f2bf(vx)); ST16(SKK, o, f2bf(kk)); ST16(SB, o, f2bf(bb));
;             ST16(GG, gb0 + t * 1024u, f2bf(g));
;             if (lane == 0) *(f32x2*)(SCAL + ((size_t)bh * SEQ + pos0 + t) * 2) = (f32x2){s_kr, s_bs};
.LBB0_564:
	s_or_b64 exec, exec, s[28:29]
	v_add_u32_e32 v10, 0x15000, v229
	v_add_u32_e32 v18, 0x15400, v229
	v_add_u32_e32 v28, 0x15800, v229
	global_load_ushort v25, v10, s[12:13]
	s_nop 0
	global_load_ushort v18, v18, s[12:13]
	s_nop 0
	global_load_ushort v10, v28, s[12:13]
	ds_read_u16 v32, v198
	s_waitcnt vmcnt(62)
	v_cvt_f32_f16_e32 v30, v26
	s_waitcnt vmcnt(61)
	v_cvt_f32_f16_e32 v28, v13
	v_mov_b32_e32 v35, 0
	v_sub_f32_e32 v29, v29, v30
	s_waitcnt lgkmcnt(0)
	v_fma_mix_f32 v32, v32, s31, v171 op_sel_hi:[1,0,0]
	v_fma_mix_f32 v26, v161, v29, v26 op_sel_hi:[0,0,1]
	ds_read_u16 v29, v176 offset:35616
	ds_read_u16 v33, v199
	v_exp_f32_e32 v32, v32
	v_sub_f32_e32 v27, v27, v28
	v_fma_mix_f32 v13, v160, v27, v13 op_sel_hi:[0,0,1]
	v_mul_f32_e32 v34, v1, v13
	s_waitcnt lgkmcnt(1)
	v_fma_mix_f32 v27, v29, s31, v170 op_sel_hi:[1,0,0]
	v_add_f32_e32 v29, 1.0, v32
	v_mul_f32_e32 v32, v34, v34
	v_rcp_f32_e32 v29, v29
	v_exp_f32_e32 v27, v27
	v_mov_b32_dpp v35, v32 quad_perm:[1,0,3,2] row_mask:0xf bank_mask:0xf
	v_fmac_f32_e32 v35, v34, v34
	v_add_f32_e32 v27, 1.0, v27
	s_nop 0
	v_add_f32_dpp v32, v35, v35 quad_perm:[2,3,0,1] row_mask:0xf bank_mask:0xf bound_ctrl:1
	v_rcp_f32_e32 v27, v27
	s_nop 0
	v_add_f32_dpp v32, v32, v32 row_half_mirror row_mask:0xf bank_mask:0xf bound_ctrl:1
	v_mul_f32_e32 v27, 0xbf600343, v27
	s_nop 0
	v_add_f32_dpp v32, v32, v32 row_mirror row_mask:0xf bank_mask:0xf bound_ctrl:1
	v_exp_f32_e32 v27, v27
	s_nop 0
	v_add_f32_dpp v32, v32, v32 row_bcast:15 row_mask:0xa bank_mask:0xf
	v_sub_f32_e32 v27, 1.0, v27
	s_nop 0
	v_add_f32_dpp v32, v32, v32 row_bcast:31 row_mask:0xc bank_mask:0xf
	s_nop 0
	v_readlane_b32 s28, v32, 63
	s_nop 1
	v_max_f32_e64 v32, s28, s28
	v_max_f32_e32 v32, 0x179abe15, v32
	v_rsq_f32_e32 v35, v32
	v_add_f32_e32 v32, -1.0, v29
	v_fma_f32 v37, v156, v32, 1.0
	v_mul_f32_e32 v32, v13, v37
	v_mul_f32_e32 v36, v34, v35
	v_mul_f32_e32 v38, v29, v36
	v_mul_f32_e32 v32, v26, v32
	v_mul_f32_e32 v39, v157, v32
	v_mul_f32_e32 v38, v26, v38
	v_cndmask_b32_e64 v40, v38, v32, s[6:7]
	v_cndmask_b32_e64 v32, v32, v38, s[6:7]
	v_cndmask_b32_e64 v38, 0, v39, s[6:7]
	v_cndmask_b32_e64 v39, v39, 0, s[6:7]
	v_add_f32_dpp v32, v32, v40 quad_perm:[1,0,3,2] row_mask:0xf bank_mask:0xf bound_ctrl:1
	v_or_b32_e32 v40, 0x900, v3
	v_add_f32_dpp v38, v39, v38 quad_perm:[1,0,3,2] row_mask:0xf bank_mask:0xf bound_ctrl:1
	v_cndmask_b32_e64 v39, v38, v32, s[8:9]
	v_cndmask_b32_e64 v32, v32, v38, s[8:9]
	v_fma_mixlo_f16 v13, v13, v37, 0
	s_nop 0
	v_add_f32_dpp v32, v32, v39 quad_perm:[2,3,0,1] row_mask:0xf bank_mask:0xf bound_ctrl:1
	s_nop 1
	v_add_f32_dpp v32, v32, v32 row_ror:4 row_mask:0xf bank_mask:0xf bound_ctrl:1
	s_nop 1
	v_add_f32_dpp v38, v32, v32 row_ror:8 row_mask:0xf bank_mask:0xf bound_ctrl:1
	ds_bpermute_b32 v39, v4, v38
	s_waitcnt vmcnt(60)
	v_cvt_f32_f16_e32 v32, v11
	s_waitcnt lgkmcnt(0)
	v_add_f32_e32 v38, v38, v39
	ds_bpermute_b32 v39, v5, v38
	v_sub_f32_e32 v31, v31, v32
	v_fma_mixlo_f16 v11, v164, v31, v11 op_sel_hi:[0,0,1]
	s_waitcnt lgkmcnt(0)
	v_add_f32_e32 v38, v38, v39
	s_nop 0
	v_readlane_b32 s42, v38, 0
	v_readlane_b32 s28, v38, 1
	v_readlane_b32 s43, v38, 2
	v_sub_f32_e32 v38, 1.0, v27
	v_cvt_f16_f32_e32 v27, v27
	v_mul_f32_e32 v39, s28, v36
	v_fma_mixlo_f16 v26, v26, v38, -v39
	global_store_short v40, v26, s[66:67]
	global_store_short v40, v27, s[14:15]
	global_store_short v40, v11, s[18:19]
	v_fma_mixlo_f16 v11, v34, v35, 0
	global_store_short v40, v11, s[20:21]
	v_fma_mixlo_f16 v11, v29, v36, 0
	global_store_short v40, v11, s[22:23]
	v_add_u32_e32 v11, 0x4800, v2
	global_store_short v40, v13, s[16:17]
	global_store_short v11, v33, s[24:25]
	s_and_saveexec_b64 s[28:29], s[2:3]
	s_cbranch_execz .LBB0_566
	s_lshl_b64 s[44:45], s[26:27], 3
	s_add_u32 s44, s34, s44
	s_addc_u32 s45, s35, s45
	v_mov_b32_e32 v26, s42
	v_mov_b32_e32 v27, s43
	global_store_dwordx2 v139, v[26:27], s[44:45] offset:144
.LBB0_566:
	s_or_b64 exec, exec, s[28:29]
	v_add_u32_e32 v11, 0x15e00, v229
	v_add_u32_e32 v13, 0x16200, v229
	v_add_u32_e32 v27, 0x16600, v229
	global_load_ushort v26, v11, s[12:13]
	s_nop 0
	global_load_ushort v13, v13, s[12:13]
	s_nop 0
	global_load_ushort v11, v27, s[12:13]
	ds_read_u16 v31, v200
	s_waitcnt vmcnt(62)
	v_cvt_f32_f16_e32 v29, v20
	s_waitcnt vmcnt(61)
	v_cvt_f32_f16_e32 v27, v14
	v_mov_b32_e32 v35, 0
	v_sub_f32_e32 v30, v30, v29
	s_waitcnt lgkmcnt(0)
	v_fma_mix_f32 v31, v31, s31, v171 op_sel_hi:[1,0,0]
	v_fma_mix_f32 v20, v161, v30, v20 op_sel_hi:[0,0,1]
	ds_read_u16 v30, v176 offset:36656
	ds_read_u16 v33, v201
	v_exp_f32_e32 v31, v31
	v_sub_f32_e32 v28, v28, v27
	v_fma_mix_f32 v14, v160, v28, v14 op_sel_hi:[0,0,1]
	v_mul_f32_e32 v34, v1, v14
	s_waitcnt lgkmcnt(1)
; __device__ __forceinline__ bf16 f2bf(float f) { return (bf16)(pk2(f, 0.f) & 0xffffu); }
; __device__ __forceinline__ float wave_sum_d(float v) {
;     v = row16_sum(v);
;     v += __builtin_bit_cast(float, __builtin_amdgcn_update_dpp(0, __builtin_bit_cast(int, v), 0x142, 0xa, 0xf, false));
;     v += __builtin_bit_cast(float, __builtin_amdgcn_update_dpp(0, __builtin_bit_cast(int, v), 0x143, 0xc, 0xf, false));
;     return __builtin_bit_cast(float, __builtin_amdgcn_readlane(__builtin_bit_cast(int, v), 63));
; }
; __device__ __forceinline__ void prep_phase(const Ctx& F, const float* mu, const float* w0, const float* a0, const float* k_k, const float* k_a, const float* r_k) {
;     ...
;             if (t + 6 < 32) { rin[t + 7] = PRL((t + 6) * PRWW); kin[t + 7] = PRL((t + 6) * PRWW + 512); vin[t + 7] = PRL((t + 6) * PRWW + 1024); }
;             asm volatile("" ::: "memory");
;             const float rc = bf2f(rin[t + 1]), kc = bf2f(kin[t + 1]), vc = bf2f(vin[t + 1]), rp = bf2f(rin[t]), kp = bf2f(kin[t]), vp = bf2f(vin[t]);
;             const float r = rc + (rp - rc) * mur, kx = kc + (kp - kc) * muk, vx = vc + (vp - vc) * muv;
;             const float ld = bf2f(outs[t * OP + c]), la = bf2f(outs[32 * OP + t * OP + c]), g = bf2f(outs[64 * OP + t * OP + c]);
;             const float een = -0.87504979f * __builtin_amdgcn_rcpf(1.f + __builtin_amdgcn_exp2f(w0n - 1.44269504f * ld));
;             const float omw = 1.f - __builtin_amdgcn_exp2f(een);
;             const float a = __builtin_amdgcn_rcpf(1.f + __builtin_amdgcn_exp2f(a0n - 1.44269504f * la));
;             const float kkv = kx * kkc; const float n2 = wave_sum_d(kkv * kkv); const float kk = kkv * __builtin_amdgcn_rsqf(fmaxf(n2, 1e-24f));
;             const float kmod = kx * (1.f + (a - 1.f) * kac); const float bb = kk * a;
;             float s_kr = kmod * r, s_bs = s_kr * rkc, s_br = bb * r;
;             wave_sum3(s_kr, s_bs, s_br, lane);
;             const float wr = (1.f - omw) * r - s_br * kk;
;             const unsigned o = ob0 + t * 128u;
;             ST16(SWR, o, f2bf(wr)); ST16(SC, o, f2bf(omw)); ST16(SK, o, f2bf(kmod)); ST16(SV, o, f2bf(vx)); ST16(SKK, o, f2bf(kk)); ST16(SB, o, f2bf(bb));
;             ST16(GG, gb0 + t * 1024u, f2bf(g));
;             if (lane == 0) *(f32x2*)(SCAL + ((size_t)bh * SEQ + pos0 + t) * 2) = (f32x2){s_kr, s_bs};
	v_fma_mix_f32 v28, v30, s31, v170 op_sel_hi:[1,0,0]
	v_add_f32_e32 v30, 1.0, v31
	v_mul_f32_e32 v31, v34, v34
	v_rcp_f32_e32 v30, v30
	v_exp_f32_e32 v28, v28
	v_mov_b32_dpp v35, v31 quad_perm:[1,0,3,2] row_mask:0xf bank_mask:0xf
	v_fmac_f32_e32 v35, v34, v34
	v_add_f32_e32 v28, 1.0, v28
	s_nop 0
	v_add_f32_dpp v31, v35, v35 quad_perm:[2,3,0,1] row_mask:0xf bank_mask:0xf bound_ctrl:1
	v_rcp_f32_e32 v28, v28
	s_nop 0
	v_add_f32_dpp v31, v31, v31 row_half_mirror row_mask:0xf bank_mask:0xf bound_ctrl:1
	v_mul_f32_e32 v28, 0xbf600343, v28
	s_nop 0
	v_add_f32_dpp v31, v31, v31 row_mirror row_mask:0xf bank_mask:0xf bound_ctrl:1
	v_exp_f32_e32 v28, v28
	s_nop 0
	v_add_f32_dpp v31, v31, v31 row_bcast:15 row_mask:0xa bank_mask:0xf
	v_sub_f32_e32 v28, 1.0, v28
	s_nop 0
	v_add_f32_dpp v31, v31, v31 row_bcast:31 row_mask:0xc bank_mask:0xf
	s_nop 0
	v_readlane_b32 s28, v31, 63
	s_nop 1
	v_max_f32_e64 v31, s28, s28
	v_max_f32_e32 v31, 0x179abe15, v31
	v_rsq_f32_e32 v35, v31
	v_add_f32_e32 v31, -1.0, v30
	v_fma_f32 v37, v156, v31, 1.0
	v_mul_f32_e32 v31, v14, v37
	v_mul_f32_e32 v36, v34, v35
	v_mul_f32_e32 v38, v30, v36
	v_mul_f32_e32 v31, v20, v31
	v_mul_f32_e32 v39, v157, v31
	v_mul_f32_e32 v38, v20, v38
	v_cndmask_b32_e64 v40, v38, v31, s[6:7]
	v_cndmask_b32_e64 v31, v31, v38, s[6:7]
	v_cndmask_b32_e64 v38, 0, v39, s[6:7]
	v_cndmask_b32_e64 v39, v39, 0, s[6:7]
	v_add_f32_dpp v31, v31, v40 quad_perm:[1,0,3,2] row_mask:0xf bank_mask:0xf bound_ctrl:1
	v_or_b32_e32 v40, 0x980, v3
	v_add_f32_dpp v38, v39, v38 quad_perm:[1,0,3,2] row_mask:0xf bank_mask:0xf bound_ctrl:1
	v_cndmask_b32_e64 v39, v38, v31, s[8:9]
	v_cndmask_b32_e64 v31, v31, v38, s[8:9]
	v_fma_mixlo_f16 v14, v14, v37, 0
	s_nop 0
	v_add_f32_dpp v31, v31, v39 quad_perm:[2,3,0,1] row_mask:0xf bank_mask:0xf bound_ctrl:1
	s_nop 1
	v_add_f32_dpp v31, v31, v31 row_ror:4 row_mask:0xf bank_mask:0xf bound_ctrl:1
	s_nop 1
	v_add_f32_dpp v38, v31, v31 row_ror:8 row_mask:0xf bank_mask:0xf bound_ctrl:1
	ds_bpermute_b32 v39, v4, v38
	s_waitcnt vmcnt(60)
	v_cvt_f32_f16_e32 v31, v12
	s_waitcnt lgkmcnt(0)
	v_add_f32_e32 v38, v38, v39
	ds_bpermute_b32 v39, v5, v38
	v_sub_f32_e32 v32, v32, v31
	v_fma_mixlo_f16 v12, v164, v32, v12 op_sel_hi:[0,0,1]
	s_waitcnt lgkmcnt(0)
	v_add_f32_e32 v38, v38, v39
	s_nop 0
	v_readlane_b32 s42, v38, 0
	v_readlane_b32 s28, v38, 1
	v_readlane_b32 s43, v38, 2
	v_sub_f32_e32 v38, 1.0, v28
	v_cvt_f16_f32_e32 v28, v28
	v_mul_f32_e32 v39, s28, v36
	v_fma_mixlo_f16 v20, v20, v38, -v39
	global_store_short v40, v20, s[66:67]
	global_store_short v40, v28, s[14:15]
	global_store_short v40, v12, s[18:19]
	v_fma_mixlo_f16 v12, v34, v35, 0
	global_store_short v40, v12, s[20:21]
	v_fma_mixlo_f16 v12, v30, v36, 0
	global_store_short v40, v12, s[22:23]
	v_add_u32_e32 v12, 0x4c00, v2
	global_store_short v40, v14, s[16:17]
	global_store_short v12, v33, s[24:25]
	s_and_saveexec_b64 s[28:29], s[2:3]
	s_cbranch_execz .LBB0_568
	s_lshl_b64 s[44:45], s[26:27], 3
	s_add_u32 s44, s34, s44
	s_addc_u32 s45, s35, s45
	v_mov_b32_e32 v32, s42
	v_mov_b32_e32 v33, s43
	global_store_dwordx2 v139, v[32:33], s[44:45] offset:152
.LBB0_568:
	s_or_b64 exec, exec, s[28:29]
	v_add_u32_e32 v12, 0x16c00, v229
	v_add_u32_e32 v14, 0x17000, v229
	v_add_u32_e32 v28, 0x17400, v229
	global_load_ushort v20, v12, s[12:13]
	s_nop 0
	global_load_ushort v14, v14, s[12:13]
	s_nop 0
	global_load_ushort v12, v28, s[12:13]
	ds_read_u16 v32, v202
	s_waitcnt vmcnt(62)
	v_cvt_f32_f16_e32 v30, v21
	s_waitcnt vmcnt(61)
	v_cvt_f32_f16_e32 v28, v19
	v_mov_b32_e32 v35, 0
	v_sub_f32_e32 v29, v29, v30
	s_waitcnt lgkmcnt(0)
	v_fma_mix_f32 v32, v32, s31, v171 op_sel_hi:[1,0,0]
	v_fma_mix_f32 v21, v161, v29, v21 op_sel_hi:[0,0,1]
	ds_read_u16 v29, v176 offset:37696
	ds_read_u16 v33, v203
	v_exp_f32_e32 v32, v32
	v_sub_f32_e32 v27, v27, v28
	v_fma_mix_f32 v19, v160, v27, v19 op_sel_hi:[0,0,1]
	v_mul_f32_e32 v34, v1, v19
	s_waitcnt lgkmcnt(1)
	v_fma_mix_f32 v27, v29, s31, v170 op_sel_hi:[1,0,0]
	v_add_f32_e32 v29, 1.0, v32
	v_mul_f32_e32 v32, v34, v34
	v_rcp_f32_e32 v29, v29
	v_exp_f32_e32 v27, v27
	v_mov_b32_dpp v35, v32 quad_perm:[1,0,3,2] row_mask:0xf bank_mask:0xf
	v_fmac_f32_e32 v35, v34, v34
	v_add_f32_e32 v27, 1.0, v27
	s_nop 0
	v_add_f32_dpp v32, v35, v35 quad_perm:[2,3,0,1] row_mask:0xf bank_mask:0xf bound_ctrl:1
	v_rcp_f32_e32 v27, v27
	s_nop 0
	v_add_f32_dpp v32, v32, v32 row_half_mirror row_mask:0xf bank_mask:0xf bound_ctrl:1
	v_mul_f32_e32 v27, 0xbf600343, v27
	s_nop 0
	v_add_f32_dpp v32, v32, v32 row_mirror row_mask:0xf bank_mask:0xf bound_ctrl:1
	v_exp_f32_e32 v27, v27
	s_nop 0
	v_add_f32_dpp v32, v32, v32 row_bcast:15 row_mask:0xa bank_mask:0xf
	v_sub_f32_e32 v27, 1.0, v27
	s_nop 0
	v_add_f32_dpp v32, v32, v32 row_bcast:31 row_mask:0xc bank_mask:0xf
	s_nop 0
	v_readlane_b32 s28, v32, 63
	s_nop 1
	v_max_f32_e64 v32, s28, s28
	v_max_f32_e32 v32, 0x179abe15, v32
	v_rsq_f32_e32 v35, v32
	v_add_f32_e32 v32, -1.0, v29
	v_fma_f32 v37, v156, v32, 1.0
	v_mul_f32_e32 v32, v19, v37
	v_mul_f32_e32 v36, v34, v35
	v_mul_f32_e32 v38, v29, v36
	v_mul_f32_e32 v32, v21, v32
	v_mul_f32_e32 v39, v157, v32
	v_mul_f32_e32 v38, v21, v38
	v_cndmask_b32_e64 v40, v38, v32, s[6:7]
	v_cndmask_b32_e64 v32, v32, v38, s[6:7]
	v_cndmask_b32_e64 v38, 0, v39, s[6:7]
	v_cndmask_b32_e64 v39, v39, 0, s[6:7]
	v_add_f32_dpp v32, v32, v40 quad_perm:[1,0,3,2] row_mask:0xf bank_mask:0xf bound_ctrl:1
	v_or_b32_e32 v40, 0xa00, v3
	v_add_f32_dpp v38, v39, v38 quad_perm:[1,0,3,2] row_mask:0xf bank_mask:0xf bound_ctrl:1
	v_cndmask_b32_e64 v39, v38, v32, s[8:9]
	v_cndmask_b32_e64 v32, v32, v38, s[8:9]
	v_fma_mixlo_f16 v19, v19, v37, 0
	s_nop 0
	v_add_f32_dpp v32, v32, v39 quad_perm:[2,3,0,1] row_mask:0xf bank_mask:0xf bound_ctrl:1
	s_nop 1
	v_add_f32_dpp v32, v32, v32 row_ror:4 row_mask:0xf bank_mask:0xf bound_ctrl:1
	s_nop 1
	v_add_f32_dpp v38, v32, v32 row_ror:8 row_mask:0xf bank_mask:0xf bound_ctrl:1
	ds_bpermute_b32 v39, v4, v38
	s_waitcnt vmcnt(60)
	v_cvt_f32_f16_e32 v32, v6
	s_waitcnt lgkmcnt(0)
	v_add_f32_e32 v38, v38, v39
	ds_bpermute_b32 v39, v5, v38
	v_sub_f32_e32 v31, v31, v32
	v_fma_mixlo_f16 v6, v164, v31, v6 op_sel_hi:[0,0,1]
	s_waitcnt lgkmcnt(0)
	v_add_f32_e32 v38, v38, v39
	s_nop 0
	v_readlane_b32 s42, v38, 0
	v_readlane_b32 s28, v38, 1
	v_readlane_b32 s43, v38, 2
	v_sub_f32_e32 v38, 1.0, v27
	v_cvt_f16_f32_e32 v27, v27
	v_mul_f32_e32 v39, s28, v36
	v_fma_mixlo_f16 v21, v21, v38, -v39
	global_store_short v40, v21, s[66:67]
	global_store_short v40, v27, s[14:15]
	global_store_short v40, v6, s[18:19]
	v_fma_mixlo_f16 v6, v34, v35, 0
	global_store_short v40, v6, s[20:21]
	v_fma_mixlo_f16 v6, v29, v36, 0
	global_store_short v40, v6, s[22:23]
	v_add_u32_e32 v6, 0x5000, v2
	global_store_short v40, v19, s[16:17]
	global_store_short v6, v33, s[24:25]
	s_and_saveexec_b64 s[28:29], s[2:3]
	s_cbranch_execz .LBB0_570
	s_lshl_b64 s[44:45], s[26:27], 3
	s_add_u32 s44, s34, s44
	s_addc_u32 s45, s35, s45
	v_mov_b32_e32 v34, s42
	v_mov_b32_e32 v35, s43
	global_store_dwordx2 v139, v[34:35], s[44:45] offset:160
; __device__ __forceinline__ bf16 f2bf(float f) { return (bf16)(pk2(f, 0.f) & 0xffffu); }
; __device__ __forceinline__ float wave_sum_d(float v) {
;     v = row16_sum(v);
;     v += __builtin_bit_cast(float, __builtin_amdgcn_update_dpp(0, __builtin_bit_cast(int, v), 0x142, 0xa, 0xf, false));
;     v += __builtin_bit_cast(float, __builtin_amdgcn_update_dpp(0, __builtin_bit_cast(int, v), 0x143, 0xc, 0xf, false));
;     return __builtin_bit_cast(float, __builtin_amdgcn_readlane(__builtin_bit_cast(int, v), 63));
; }
; __device__ __forceinline__ void prep_phase(const Ctx& F, const float* mu, const float* w0, const float* a0, const float* k_k, const float* k_a, const float* r_k) {
;     ...
;             if (t + 6 < 32) { rin[t + 7] = PRL((t + 6) * PRWW); kin[t + 7] = PRL((t + 6) * PRWW + 512); vin[t + 7] = PRL((t + 6) * PRWW + 1024); }
;             asm volatile("" ::: "memory");
;             const float rc = bf2f(rin[t + 1]), kc = bf2f(kin[t + 1]), vc = bf2f(vin[t + 1]), rp = bf2f(rin[t]), kp = bf2f(kin[t]), vp = bf2f(vin[t]);
;             const float r = rc + (rp - rc) * mur, kx = kc + (kp - kc) * muk, vx = vc + (vp - vc) * muv;
;             const float ld = bf2f(outs[t * OP + c]), la = bf2f(outs[32 * OP + t * OP + c]), g = bf2f(outs[64 * OP + t * OP + c]);
;             const float een = -0.87504979f * __builtin_amdgcn_rcpf(1.f + __builtin_amdgcn_exp2f(w0n - 1.44269504f * ld));
;             const float omw = 1.f - __builtin_amdgcn_exp2f(een);
;             const float a = __builtin_amdgcn_rcpf(1.f + __builtin_amdgcn_exp2f(a0n - 1.44269504f * la));
;             const float kkv = kx * kkc; const float n2 = wave_sum_d(kkv * kkv); const float kk = kkv * __builtin_amdgcn_rsqf(fmaxf(n2, 1e-24f));
;             const float kmod = kx * (1.f + (a - 1.f) * kac); const float bb = kk * a;
;             float s_kr = kmod * r, s_bs = s_kr * rkc, s_br = bb * r;
;             wave_sum3(s_kr, s_bs, s_br, lane);
;             const float wr = (1.f - omw) * r - s_br * kk;
;             const unsigned o = ob0 + t * 128u;
;             ST16(SWR, o, f2bf(wr)); ST16(SC, o, f2bf(omw)); ST16(SK, o, f2bf(kmod)); ST16(SV, o, f2bf(vx)); ST16(SKK, o, f2bf(kk)); ST16(SB, o, f2bf(bb));
;             ST16(GG, gb0 + t * 1024u, f2bf(g));
;             if (lane == 0) *(f32x2*)(SCAL + ((size_t)bh * SEQ + pos0 + t) * 2) = (f32x2){s_kr, s_bs};
.LBB0_570:
	s_or_b64 exec, exec, s[28:29]
	v_add_u32_e32 v6, 0x17a00, v229
	v_add_u32_e32 v19, 0x17e00, v229
	v_add_u32_e32 v27, 0x18200, v229
	global_load_ushort v21, v6, s[12:13]
	s_nop 0
	global_load_ushort v19, v19, s[12:13]
	s_nop 0
	global_load_ushort v6, v27, s[12:13]
	ds_read_u16 v31, v204
	s_waitcnt vmcnt(62)
	v_cvt_f32_f16_e32 v29, v22
	s_waitcnt vmcnt(61)
	v_cvt_f32_f16_e32 v27, v15
	v_mov_b32_e32 v35, 0
	v_sub_f32_e32 v30, v30, v29
	s_waitcnt lgkmcnt(0)
	v_fma_mix_f32 v31, v31, s31, v171 op_sel_hi:[1,0,0]
	v_fma_mix_f32 v22, v161, v30, v22 op_sel_hi:[0,0,1]
	ds_read_u16 v30, v176 offset:38736
	ds_read_u16 v33, v205
	v_exp_f32_e32 v31, v31
	v_sub_f32_e32 v28, v28, v27
	v_fma_mix_f32 v15, v160, v28, v15 op_sel_hi:[0,0,1]
	v_mul_f32_e32 v34, v1, v15
	s_waitcnt lgkmcnt(1)
	v_fma_mix_f32 v28, v30, s31, v170 op_sel_hi:[1,0,0]
	v_add_f32_e32 v30, 1.0, v31
	v_mul_f32_e32 v31, v34, v34
	v_rcp_f32_e32 v30, v30
	v_exp_f32_e32 v28, v28
	v_mov_b32_dpp v35, v31 quad_perm:[1,0,3,2] row_mask:0xf bank_mask:0xf
	v_fmac_f32_e32 v35, v34, v34
	v_add_f32_e32 v28, 1.0, v28
	s_nop 0
	v_add_f32_dpp v31, v35, v35 quad_perm:[2,3,0,1] row_mask:0xf bank_mask:0xf bound_ctrl:1
	v_rcp_f32_e32 v28, v28
	s_nop 0
	v_add_f32_dpp v31, v31, v31 row_half_mirror row_mask:0xf bank_mask:0xf bound_ctrl:1
	v_mul_f32_e32 v28, 0xbf600343, v28
	s_nop 0
	v_add_f32_dpp v31, v31, v31 row_mirror row_mask:0xf bank_mask:0xf bound_ctrl:1
	v_exp_f32_e32 v28, v28
	s_nop 0
	v_add_f32_dpp v31, v31, v31 row_bcast:15 row_mask:0xa bank_mask:0xf
	v_sub_f32_e32 v28, 1.0, v28
	s_nop 0
	v_add_f32_dpp v31, v31, v31 row_bcast:31 row_mask:0xc bank_mask:0xf
	s_nop 0
	v_readlane_b32 s28, v31, 63
	s_nop 1
	v_max_f32_e64 v31, s28, s28
	v_max_f32_e32 v31, 0x179abe15, v31
	v_rsq_f32_e32 v35, v31
	v_add_f32_e32 v31, -1.0, v30
	v_fma_f32 v37, v156, v31, 1.0
	v_mul_f32_e32 v31, v15, v37
	v_mul_f32_e32 v36, v34, v35
	v_mul_f32_e32 v38, v30, v36
	v_mul_f32_e32 v31, v22, v31
	v_mul_f32_e32 v39, v157, v31
	v_mul_f32_e32 v38, v22, v38
	v_cndmask_b32_e64 v40, v38, v31, s[6:7]
	v_cndmask_b32_e64 v31, v31, v38, s[6:7]
	v_cndmask_b32_e64 v38, 0, v39, s[6:7]
	v_cndmask_b32_e64 v39, v39, 0, s[6:7]
	v_add_f32_dpp v31, v31, v40 quad_perm:[1,0,3,2] row_mask:0xf bank_mask:0xf bound_ctrl:1
	v_or_b32_e32 v40, 0xa80, v3
	v_add_f32_dpp v38, v39, v38 quad_perm:[1,0,3,2] row_mask:0xf bank_mask:0xf bound_ctrl:1
	v_cndmask_b32_e64 v39, v38, v31, s[8:9]
	v_cndmask_b32_e64 v31, v31, v38, s[8:9]
	v_fma_mixlo_f16 v15, v15, v37, 0
	s_nop 0
	v_add_f32_dpp v31, v31, v39 quad_perm:[2,3,0,1] row_mask:0xf bank_mask:0xf bound_ctrl:1
	s_nop 1
	v_add_f32_dpp v31, v31, v31 row_ror:4 row_mask:0xf bank_mask:0xf bound_ctrl:1
	s_nop 1
	v_add_f32_dpp v38, v31, v31 row_ror:8 row_mask:0xf bank_mask:0xf bound_ctrl:1
	ds_bpermute_b32 v39, v4, v38
	s_waitcnt vmcnt(60)
	v_cvt_f32_f16_e32 v31, v7
	s_waitcnt lgkmcnt(0)
	v_add_f32_e32 v38, v38, v39
	ds_bpermute_b32 v39, v5, v38
	v_sub_f32_e32 v32, v32, v31
	v_fma_mixlo_f16 v7, v164, v32, v7 op_sel_hi:[0,0,1]
	s_waitcnt lgkmcnt(0)
	v_add_f32_e32 v38, v38, v39
	s_nop 0
	v_readlane_b32 s42, v38, 0
	v_readlane_b32 s28, v38, 1
	v_readlane_b32 s43, v38, 2
	v_sub_f32_e32 v38, 1.0, v28
	v_cvt_f16_f32_e32 v28, v28
	v_mul_f32_e32 v39, s28, v36
	v_fma_mixlo_f16 v22, v22, v38, -v39
	global_store_short v40, v22, s[66:67]
	global_store_short v40, v28, s[14:15]
	global_store_short v40, v7, s[18:19]
	v_fma_mixlo_f16 v7, v34, v35, 0
	global_store_short v40, v7, s[20:21]
	v_fma_mixlo_f16 v7, v30, v36, 0
	global_store_short v40, v7, s[22:23]
	v_add_u32_e32 v7, 0x5400, v2
	global_store_short v40, v15, s[16:17]
	global_store_short v7, v33, s[24:25]
	s_and_saveexec_b64 s[28:29], s[2:3]
	s_cbranch_execz .LBB0_572
	s_lshl_b64 s[44:45], s[26:27], 3
	s_add_u32 s44, s34, s44
	s_addc_u32 s45, s35, s45
	v_mov_b32_e32 v32, s42
	v_mov_b32_e32 v33, s43
	global_store_dwordx2 v139, v[32:33], s[44:45] offset:168
.LBB0_572:
	s_or_b64 exec, exec, s[28:29]
	v_add_u32_e32 v7, 0x18800, v229
	v_add_u32_e32 v15, 0x18c00, v229
	v_add_u32_e32 v28, 0x19000, v229
	global_load_ushort v22, v7, s[12:13]
	s_nop 0
	global_load_ushort v15, v15, s[12:13]
	s_nop 0
	global_load_ushort v7, v28, s[12:13]
	ds_read_u16 v32, v206
	s_waitcnt vmcnt(62)
	v_cvt_f32_f16_e32 v30, v23
	s_waitcnt vmcnt(61)
	v_cvt_f32_f16_e32 v28, v16
	v_mov_b32_e32 v35, 0
	v_sub_f32_e32 v29, v29, v30
	s_waitcnt lgkmcnt(0)
	v_fma_mix_f32 v32, v32, s31, v171 op_sel_hi:[1,0,0]
	v_fma_mix_f32 v23, v161, v29, v23 op_sel_hi:[0,0,1]
	ds_read_u16 v29, v176 offset:39776
	ds_read_u16 v33, v207
	v_exp_f32_e32 v32, v32
	v_sub_f32_e32 v27, v27, v28
	v_fma_mix_f32 v16, v160, v27, v16 op_sel_hi:[0,0,1]
	v_mul_f32_e32 v34, v1, v16
	s_waitcnt lgkmcnt(1)
; __device__ __forceinline__ bf16 f2bf(float f) { return (bf16)(pk2(f, 0.f) & 0xffffu); }
; __device__ __forceinline__ float wave_sum_d(float v) {
;     v = row16_sum(v);
;     v += __builtin_bit_cast(float, __builtin_amdgcn_update_dpp(0, __builtin_bit_cast(int, v), 0x142, 0xa, 0xf, false));
;     v += __builtin_bit_cast(float, __builtin_amdgcn_update_dpp(0, __builtin_bit_cast(int, v), 0x143, 0xc, 0xf, false));
;     return __builtin_bit_cast(float, __builtin_amdgcn_readlane(__builtin_bit_cast(int, v), 63));
; }
; __device__ __forceinline__ void prep_phase(const Ctx& F, const float* mu, const float* w0, const float* a0, const float* k_k, const float* k_a, const float* r_k) {
;     ...
;             if (t + 6 < 32) { rin[t + 7] = PRL((t + 6) * PRWW); kin[t + 7] = PRL((t + 6) * PRWW + 512); vin[t + 7] = PRL((t + 6) * PRWW + 1024); }
;             asm volatile("" ::: "memory");
;             const float rc = bf2f(rin[t + 1]), kc = bf2f(kin[t + 1]), vc = bf2f(vin[t + 1]), rp = bf2f(rin[t]), kp = bf2f(kin[t]), vp = bf2f(vin[t]);
;             const float r = rc + (rp - rc) * mur, kx = kc + (kp - kc) * muk, vx = vc + (vp - vc) * muv;
;             const float ld = bf2f(outs[t * OP + c]), la = bf2f(outs[32 * OP + t * OP + c]), g = bf2f(outs[64 * OP + t * OP + c]);
;             const float een = -0.87504979f * __builtin_amdgcn_rcpf(1.f + __builtin_amdgcn_exp2f(w0n - 1.44269504f * ld));
;             const float omw = 1.f - __builtin_amdgcn_exp2f(een);
;             const float a = __builtin_amdgcn_rcpf(1.f + __builtin_amdgcn_exp2f(a0n - 1.44269504f * la));
;             const float kkv = kx * kkc; const float n2 = wave_sum_d(kkv * kkv); const float kk = kkv * __builtin_amdgcn_rsqf(fmaxf(n2, 1e-24f));
;             const float kmod = kx * (1.f + (a - 1.f) * kac); const float bb = kk * a;
;             float s_kr = kmod * r, s_bs = s_kr * rkc, s_br = bb * r;
;             wave_sum3(s_kr, s_bs, s_br, lane);
;             const float wr = (1.f - omw) * r - s_br * kk;
;             const unsigned o = ob0 + t * 128u;
;             ST16(SWR, o, f2bf(wr)); ST16(SC, o, f2bf(omw)); ST16(SK, o, f2bf(kmod)); ST16(SV, o, f2bf(vx)); ST16(SKK, o, f2bf(kk)); ST16(SB, o, f2bf(bb));
;             ST16(GG, gb0 + t * 1024u, f2bf(g));
;             if (lane == 0) *(f32x2*)(SCAL + ((size_t)bh * SEQ + pos0 + t) * 2) = (f32x2){s_kr, s_bs};
	v_fma_mix_f32 v27, v29, s31, v170 op_sel_hi:[1,0,0]
	v_add_f32_e32 v29, 1.0, v32
	v_mul_f32_e32 v32, v34, v34
	v_rcp_f32_e32 v29, v29
	v_exp_f32_e32 v27, v27
	v_mov_b32_dpp v35, v32 quad_perm:[1,0,3,2] row_mask:0xf bank_mask:0xf
	v_fmac_f32_e32 v35, v34, v34
	v_add_f32_e32 v27, 1.0, v27
	s_nop 0
	v_add_f32_dpp v32, v35, v35 quad_perm:[2,3,0,1] row_mask:0xf bank_mask:0xf bound_ctrl:1
	v_rcp_f32_e32 v27, v27
	s_nop 0
	v_add_f32_dpp v32, v32, v32 row_half_mirror row_mask:0xf bank_mask:0xf bound_ctrl:1
	v_mul_f32_e32 v27, 0xbf600343, v27
	s_nop 0
	v_add_f32_dpp v32, v32, v32 row_mirror row_mask:0xf bank_mask:0xf bound_ctrl:1
	v_exp_f32_e32 v27, v27
	s_nop 0
	v_add_f32_dpp v32, v32, v32 row_bcast:15 row_mask:0xa bank_mask:0xf
	v_sub_f32_e32 v27, 1.0, v27
	s_nop 0
	v_add_f32_dpp v32, v32, v32 row_bcast:31 row_mask:0xc bank_mask:0xf
	s_nop 0
	v_readlane_b32 s28, v32, 63
	s_nop 1
	v_max_f32_e64 v32, s28, s28
	v_max_f32_e32 v32, 0x179abe15, v32
	v_rsq_f32_e32 v35, v32
	v_add_f32_e32 v32, -1.0, v29
	v_fma_f32 v37, v156, v32, 1.0
	v_mul_f32_e32 v32, v16, v37
	v_mul_f32_e32 v36, v34, v35
	v_mul_f32_e32 v38, v29, v36
	v_mul_f32_e32 v32, v23, v32
	v_mul_f32_e32 v39, v157, v32
	v_mul_f32_e32 v38, v23, v38
	v_cndmask_b32_e64 v40, v38, v32, s[6:7]
	v_cndmask_b32_e64 v32, v32, v38, s[6:7]
	v_cndmask_b32_e64 v38, 0, v39, s[6:7]
	v_cndmask_b32_e64 v39, v39, 0, s[6:7]
	v_add_f32_dpp v32, v32, v40 quad_perm:[1,0,3,2] row_mask:0xf bank_mask:0xf bound_ctrl:1
	v_or_b32_e32 v40, 0xb00, v3
	v_add_f32_dpp v38, v39, v38 quad_perm:[1,0,3,2] row_mask:0xf bank_mask:0xf bound_ctrl:1
	v_cndmask_b32_e64 v39, v38, v32, s[8:9]
	v_cndmask_b32_e64 v32, v32, v38, s[8:9]
	v_fma_mixlo_f16 v16, v16, v37, 0
	s_nop 0
	v_add_f32_dpp v32, v32, v39 quad_perm:[2,3,0,1] row_mask:0xf bank_mask:0xf bound_ctrl:1
	s_nop 1
	v_add_f32_dpp v32, v32, v32 row_ror:4 row_mask:0xf bank_mask:0xf bound_ctrl:1
	s_nop 1
	v_add_f32_dpp v38, v32, v32 row_ror:8 row_mask:0xf bank_mask:0xf bound_ctrl:1
	ds_bpermute_b32 v39, v4, v38
	s_waitcnt vmcnt(60)
	v_cvt_f32_f16_e32 v32, v8
	s_waitcnt lgkmcnt(0)
	v_add_f32_e32 v38, v38, v39
	ds_bpermute_b32 v39, v5, v38
	v_sub_f32_e32 v31, v31, v32
	v_fma_mixlo_f16 v8, v164, v31, v8 op_sel_hi:[0,0,1]
	s_waitcnt lgkmcnt(0)
	v_add_f32_e32 v38, v38, v39
	s_nop 0
	v_readlane_b32 s42, v38, 0
	v_readlane_b32 s28, v38, 1
	v_readlane_b32 s43, v38, 2
	v_sub_f32_e32 v38, 1.0, v27
	v_cvt_f16_f32_e32 v27, v27
	v_mul_f32_e32 v39, s28, v36
	v_fma_mixlo_f16 v23, v23, v38, -v39
	global_store_short v40, v23, s[66:67]
	global_store_short v40, v27, s[14:15]
	global_store_short v40, v8, s[18:19]
	v_fma_mixlo_f16 v8, v34, v35, 0
	global_store_short v40, v8, s[20:21]
	v_fma_mixlo_f16 v8, v29, v36, 0
	global_store_short v40, v8, s[22:23]
	v_add_u32_e32 v8, 0x5800, v2
	global_store_short v40, v16, s[16:17]
	global_store_short v8, v33, s[24:25]
	s_and_saveexec_b64 s[28:29], s[2:3]
	s_cbranch_execz .LBB0_574
	s_lshl_b64 s[44:45], s[26:27], 3
	s_add_u32 s44, s34, s44
	s_addc_u32 s45, s35, s45
	v_mov_b32_e32 v34, s42
	v_mov_b32_e32 v35, s43
	global_store_dwordx2 v139, v[34:35], s[44:45] offset:176
.LBB0_574:
	s_or_b64 exec, exec, s[28:29]
	v_add_u32_e32 v8, 0x19600, v229
	v_add_u32_e32 v16, 0x19a00, v229
	v_add_u32_e32 v27, 0x19e00, v229
	global_load_ushort v23, v8, s[12:13]
	s_nop 0
	global_load_ushort v16, v16, s[12:13]
	s_nop 0
	global_load_ushort v8, v27, s[12:13]
	ds_read_u16 v31, v208
	s_waitcnt vmcnt(62)
	v_cvt_f32_f16_e32 v29, v24
	s_waitcnt vmcnt(61)
	v_cvt_f32_f16_e32 v27, v17
	v_mov_b32_e32 v35, 0
	v_sub_f32_e32 v30, v30, v29
	s_waitcnt lgkmcnt(0)
	v_fma_mix_f32 v31, v31, s31, v171 op_sel_hi:[1,0,0]
	v_fma_mix_f32 v24, v161, v30, v24 op_sel_hi:[0,0,1]
	ds_read_u16 v30, v176 offset:40816
	ds_read_u16 v33, v209
	v_exp_f32_e32 v31, v31
	v_sub_f32_e32 v28, v28, v27
	v_fma_mix_f32 v17, v160, v28, v17 op_sel_hi:[0,0,1]
	v_mul_f32_e32 v34, v1, v17
	s_waitcnt lgkmcnt(1)
	v_fma_mix_f32 v28, v30, s31, v170 op_sel_hi:[1,0,0]
	v_add_f32_e32 v30, 1.0, v31
	v_mul_f32_e32 v31, v34, v34
	v_rcp_f32_e32 v30, v30
	v_exp_f32_e32 v28, v28
	v_mov_b32_dpp v35, v31 quad_perm:[1,0,3,2] row_mask:0xf bank_mask:0xf
	v_fmac_f32_e32 v35, v34, v34
	v_add_f32_e32 v28, 1.0, v28
	s_nop 0
	v_add_f32_dpp v31, v35, v35 quad_perm:[2,3,0,1] row_mask:0xf bank_mask:0xf bound_ctrl:1
	v_rcp_f32_e32 v28, v28
	s_nop 0
	v_add_f32_dpp v31, v31, v31 row_half_mirror row_mask:0xf bank_mask:0xf bound_ctrl:1
	v_mul_f32_e32 v28, 0xbf600343, v28
	s_nop 0
	v_add_f32_dpp v31, v31, v31 row_mirror row_mask:0xf bank_mask:0xf bound_ctrl:1
	v_exp_f32_e32 v28, v28
	s_nop 0
	v_add_f32_dpp v31, v31, v31 row_bcast:15 row_mask:0xa bank_mask:0xf
	v_sub_f32_e32 v28, 1.0, v28
	s_nop 0
	v_add_f32_dpp v31, v31, v31 row_bcast:31 row_mask:0xc bank_mask:0xf
	s_nop 0
	v_readlane_b32 s28, v31, 63
	s_nop 1
	v_max_f32_e64 v31, s28, s28
	v_max_f32_e32 v31, 0x179abe15, v31
	v_rsq_f32_e32 v35, v31
	v_add_f32_e32 v31, -1.0, v30
	v_fma_f32 v37, v156, v31, 1.0
	v_mul_f32_e32 v31, v17, v37
	v_mul_f32_e32 v36, v34, v35
	v_mul_f32_e32 v38, v30, v36
	v_mul_f32_e32 v31, v24, v31
	v_mul_f32_e32 v39, v157, v31
	v_mul_f32_e32 v38, v24, v38
	v_cndmask_b32_e64 v40, v38, v31, s[6:7]
	v_cndmask_b32_e64 v31, v31, v38, s[6:7]
	v_cndmask_b32_e64 v38, 0, v39, s[6:7]
	v_cndmask_b32_e64 v39, v39, 0, s[6:7]
	v_add_f32_dpp v31, v31, v40 quad_perm:[1,0,3,2] row_mask:0xf bank_mask:0xf bound_ctrl:1
	v_or_b32_e32 v40, 0xb80, v3
	v_add_f32_dpp v38, v39, v38 quad_perm:[1,0,3,2] row_mask:0xf bank_mask:0xf bound_ctrl:1
	v_cndmask_b32_e64 v39, v38, v31, s[8:9]
	v_cndmask_b32_e64 v31, v31, v38, s[8:9]
	v_fma_mixlo_f16 v17, v17, v37, 0
	s_nop 0
	v_add_f32_dpp v31, v31, v39 quad_perm:[2,3,0,1] row_mask:0xf bank_mask:0xf bound_ctrl:1
	s_nop 1
	v_add_f32_dpp v31, v31, v31 row_ror:4 row_mask:0xf bank_mask:0xf bound_ctrl:1
	s_nop 1
	v_add_f32_dpp v38, v31, v31 row_ror:8 row_mask:0xf bank_mask:0xf bound_ctrl:1
	ds_bpermute_b32 v39, v4, v38
	s_waitcnt vmcnt(60)
	v_cvt_f32_f16_e32 v31, v9
	s_waitcnt lgkmcnt(0)
	v_add_f32_e32 v38, v38, v39
	ds_bpermute_b32 v39, v5, v38
	v_sub_f32_e32 v32, v32, v31
	v_fma_mixlo_f16 v9, v164, v32, v9 op_sel_hi:[0,0,1]
	s_waitcnt lgkmcnt(0)
	v_add_f32_e32 v38, v38, v39
	s_nop 0
	v_readlane_b32 s42, v38, 0
	v_readlane_b32 s28, v38, 1
	v_readlane_b32 s43, v38, 2
	v_sub_f32_e32 v38, 1.0, v28
	v_cvt_f16_f32_e32 v28, v28
	v_mul_f32_e32 v39, s28, v36
	v_fma_mixlo_f16 v24, v24, v38, -v39
	global_store_short v40, v24, s[66:67]
	global_store_short v40, v28, s[14:15]
	global_store_short v40, v9, s[18:19]
	v_fma_mixlo_f16 v9, v34, v35, 0
	global_store_short v40, v9, s[20:21]
	v_fma_mixlo_f16 v9, v30, v36, 0
	global_store_short v40, v9, s[22:23]
	v_add_u32_e32 v9, 0x5c00, v2
	global_store_short v40, v17, s[16:17]
	global_store_short v9, v33, s[24:25]
	s_and_saveexec_b64 s[28:29], s[2:3]
	s_cbranch_execz .LBB0_576
	s_lshl_b64 s[44:45], s[26:27], 3
	s_add_u32 s44, s34, s44
	s_addc_u32 s45, s35, s45
	v_mov_b32_e32 v32, s42
	v_mov_b32_e32 v33, s43
	global_store_dwordx2 v139, v[32:33], s[44:45] offset:184
; __device__ __forceinline__ bf16 f2bf(float f) { return (bf16)(pk2(f, 0.f) & 0xffffu); }
; __device__ __forceinline__ float wave_sum_d(float v) {
;     v = row16_sum(v);
;     v += __builtin_bit_cast(float, __builtin_amdgcn_update_dpp(0, __builtin_bit_cast(int, v), 0x142, 0xa, 0xf, false));
;     v += __builtin_bit_cast(float, __builtin_amdgcn_update_dpp(0, __builtin_bit_cast(int, v), 0x143, 0xc, 0xf, false));
;     return __builtin_bit_cast(float, __builtin_amdgcn_readlane(__builtin_bit_cast(int, v), 63));
; }
; __device__ __forceinline__ void prep_phase(const Ctx& F, const float* mu, const float* w0, const float* a0, const float* k_k, const float* k_a, const float* r_k) {
;     ...
;             if (t + 6 < 32) { rin[t + 7] = PRL((t + 6) * PRWW); kin[t + 7] = PRL((t + 6) * PRWW + 512); vin[t + 7] = PRL((t + 6) * PRWW + 1024); }
;             asm volatile("" ::: "memory");
;             const float rc = bf2f(rin[t + 1]), kc = bf2f(kin[t + 1]), vc = bf2f(vin[t + 1]), rp = bf2f(rin[t]), kp = bf2f(kin[t]), vp = bf2f(vin[t]);
;             const float r = rc + (rp - rc) * mur, kx = kc + (kp - kc) * muk, vx = vc + (vp - vc) * muv;
;             const float ld = bf2f(outs[t * OP + c]), la = bf2f(outs[32 * OP + t * OP + c]), g = bf2f(outs[64 * OP + t * OP + c]);
;             const float een = -0.87504979f * __builtin_amdgcn_rcpf(1.f + __builtin_amdgcn_exp2f(w0n - 1.44269504f * ld));
;             const float omw = 1.f - __builtin_amdgcn_exp2f(een);
;             const float a = __builtin_amdgcn_rcpf(1.f + __builtin_amdgcn_exp2f(a0n - 1.44269504f * la));
;             const float kkv = kx * kkc; const float n2 = wave_sum_d(kkv * kkv); const float kk = kkv * __builtin_amdgcn_rsqf(fmaxf(n2, 1e-24f));
;             const float kmod = kx * (1.f + (a - 1.f) * kac); const float bb = kk * a;
;             float s_kr = kmod * r, s_bs = s_kr * rkc, s_br = bb * r;
;             wave_sum3(s_kr, s_bs, s_br, lane);
;             const float wr = (1.f - omw) * r - s_br * kk;
;             const unsigned o = ob0 + t * 128u;
;             ST16(SWR, o, f2bf(wr)); ST16(SC, o, f2bf(omw)); ST16(SK, o, f2bf(kmod)); ST16(SV, o, f2bf(vx)); ST16(SKK, o, f2bf(kk)); ST16(SB, o, f2bf(bb));
;             ST16(GG, gb0 + t * 1024u, f2bf(g));
;             if (lane == 0) *(f32x2*)(SCAL + ((size_t)bh * SEQ + pos0 + t) * 2) = (f32x2){s_kr, s_bs};
.LBB0_576:
	s_or_b64 exec, exec, s[28:29]
	v_add_u32_e32 v9, 0x1a400, v229
	v_add_u32_e32 v17, 0x1a800, v229
	v_add_u32_e32 v28, 0x1ac00, v229
	global_load_ushort v24, v9, s[12:13]
	s_nop 0
	global_load_ushort v17, v17, s[12:13]
	s_nop 0
	global_load_ushort v9, v28, s[12:13]
	ds_read_u16 v32, v210
	s_waitcnt vmcnt(62)
	v_cvt_f32_f16_e32 v30, v25
	s_waitcnt vmcnt(61)
	v_cvt_f32_f16_e32 v28, v18
	v_mov_b32_e32 v35, 0
	v_sub_f32_e32 v29, v29, v30
	s_waitcnt lgkmcnt(0)
	v_fma_mix_f32 v32, v32, s31, v171 op_sel_hi:[1,0,0]
	v_fma_mix_f32 v25, v161, v29, v25 op_sel_hi:[0,0,1]
	ds_read_u16 v29, v176 offset:41856
	ds_read_u16 v33, v211
	v_exp_f32_e32 v32, v32
	v_sub_f32_e32 v27, v27, v28
	v_fma_mix_f32 v18, v160, v27, v18 op_sel_hi:[0,0,1]
	s_waitcnt lgkmcnt(1)
	v_fma_mix_f32 v27, v29, s31, v170 op_sel_hi:[1,0,0]
	v_add_f32_e32 v29, 1.0, v32
	v_mul_f32_e32 v32, v1, v18
	v_mul_f32_e32 v34, v32, v32
	v_exp_f32_e32 v27, v27
	v_rcp_f32_e32 v29, v29
	v_mov_b32_dpp v35, v34 quad_perm:[1,0,3,2] row_mask:0xf bank_mask:0xf
	v_fmac_f32_e32 v35, v32, v32
	v_add_f32_e32 v27, 1.0, v27
	s_nop 0
	v_add_f32_dpp v34, v35, v35 quad_perm:[2,3,0,1] row_mask:0xf bank_mask:0xf bound_ctrl:1
	s_nop 0
	s_nop 0
	v_add_f32_dpp v34, v34, v34 row_half_mirror row_mask:0xf bank_mask:0xf bound_ctrl:1
	s_nop 1
	v_add_f32_dpp v34, v34, v34 row_mirror row_mask:0xf bank_mask:0xf bound_ctrl:1
	s_nop 1
	v_add_f32_dpp v34, v34, v34 row_bcast:15 row_mask:0xa bank_mask:0xf
	s_nop 1
	v_add_f32_dpp v34, v34, v34 row_bcast:31 row_mask:0xc bank_mask:0xf
	v_rcp_f32_e32 v35, v27
	v_readlane_b32 s28, v34, 63
	v_add_f32_e32 v27, -1.0, v29
	v_fma_f32 v37, v156, v27, 1.0
	v_max_f32_e64 v34, s28, s28
	v_max_f32_e32 v34, 0x179abe15, v34
	v_rsq_f32_e32 v34, v34
	v_mul_f32_e32 v27, v18, v37
	v_mul_f32_e32 v27, v25, v27
	v_mul_f32_e32 v39, v157, v27
	v_mul_f32_e32 v36, v32, v34
	v_mul_f32_e32 v38, v29, v36
	v_mul_f32_e32 v38, v25, v38
	v_cndmask_b32_e64 v40, v38, v27, s[6:7]
	v_cndmask_b32_e64 v27, v27, v38, s[6:7]
	v_cndmask_b32_e64 v38, 0, v39, s[6:7]
	v_cndmask_b32_e64 v39, v39, 0, s[6:7]
	v_add_f32_dpp v27, v27, v40 quad_perm:[1,0,3,2] row_mask:0xf bank_mask:0xf bound_ctrl:1
	v_mul_f32_e32 v35, 0xbf600343, v35
	v_add_f32_dpp v38, v39, v38 quad_perm:[1,0,3,2] row_mask:0xf bank_mask:0xf bound_ctrl:1
	v_cndmask_b32_e64 v39, v38, v27, s[8:9]
	v_cndmask_b32_e64 v27, v27, v38, s[8:9]
	v_exp_f32_e32 v35, v35
	v_or_b32_e32 v40, 0xc00, v3
	v_add_f32_dpp v27, v27, v39 quad_perm:[2,3,0,1] row_mask:0xf bank_mask:0xf bound_ctrl:1
	v_fma_mixlo_f16 v18, v18, v37, 0
	v_sub_f32_e32 v35, 1.0, v35
	v_add_f32_dpp v27, v27, v27 row_ror:4 row_mask:0xf bank_mask:0xf bound_ctrl:1
	s_nop 1
	v_add_f32_dpp v38, v27, v27 row_ror:8 row_mask:0xf bank_mask:0xf bound_ctrl:1
	ds_bpermute_b32 v39, v4, v38
	s_waitcnt vmcnt(60)
	v_cvt_f32_f16_e32 v27, v10
	s_waitcnt lgkmcnt(0)
	v_add_f32_e32 v38, v38, v39
	ds_bpermute_b32 v39, v5, v38
	v_sub_f32_e32 v31, v31, v27
	v_fma_mixlo_f16 v10, v164, v31, v10 op_sel_hi:[0,0,1]
	s_waitcnt lgkmcnt(0)
	v_add_f32_e32 v38, v38, v39
	s_nop 0
	v_readlane_b32 s42, v38, 0
	v_readlane_b32 s28, v38, 1
	v_readlane_b32 s43, v38, 2
	v_sub_f32_e32 v38, 1.0, v35
	v_cvt_f16_f32_e32 v35, v35
	v_mul_f32_e32 v39, s28, v36
	v_fma_mixlo_f16 v25, v25, v38, -v39
	global_store_short v40, v25, s[66:67]
	global_store_short v40, v35, s[14:15]
	global_store_short v40, v10, s[18:19]
	v_fma_mixlo_f16 v10, v32, v34, 0
	global_store_short v40, v10, s[20:21]
	v_fma_mixlo_f16 v10, v29, v36, 0
	global_store_short v40, v10, s[22:23]
	v_add_u32_e32 v10, 0x6000, v2
	global_store_short v40, v18, s[16:17]
	global_store_short v10, v33, s[24:25]
	s_and_saveexec_b64 s[28:29], s[2:3]
	s_cbranch_execz .LBB0_578
	s_lshl_b64 s[44:45], s[26:27], 3
	s_add_u32 s44, s34, s44
	s_addc_u32 s45, s35, s45
	v_mov_b32_e32 v32, s42
	v_mov_b32_e32 v33, s43
	global_store_dwordx2 v139, v[32:33], s[44:45] offset:192
.LBB0_578:
	s_or_b64 exec, exec, s[28:29]
	v_add_u32_e32 v10, 0x1b200, v229
	v_add_u32_e32 v18, 0x1b600, v229
	v_add_u32_e32 v31, 0x1ba00, v229
	global_load_ushort v25, v10, s[12:13]
	s_nop 0
	global_load_ushort v18, v18, s[12:13]
	s_nop 0
	global_load_ushort v10, v31, s[12:13]
	ds_read_u16 v32, v212
	s_waitcnt vmcnt(62)
	v_cvt_f32_f16_e32 v29, v26
	s_waitcnt vmcnt(61)
	v_cvt_f32_f16_e32 v31, v13
	v_mov_b32_e32 v35, 0
	v_sub_f32_e32 v30, v30, v29
	s_waitcnt lgkmcnt(0)
	v_fma_mix_f32 v32, v32, s31, v171 op_sel_hi:[1,0,0]
	v_fma_mix_f32 v30, v161, v30, v26 op_sel_hi:[0,0,1]
	v_sub_f32_e32 v26, v28, v31
	ds_read_u16 v28, v176 offset:42896
	ds_read_u16 v33, v213
	v_exp_f32_e32 v32, v32
	v_fma_mix_f32 v13, v160, v26, v13 op_sel_hi:[0,0,1]
	s_waitcnt lgkmcnt(1)
; __device__ __forceinline__ bf16 f2bf(float f) { return (bf16)(pk2(f, 0.f) & 0xffffu); }
; __device__ __forceinline__ float wave_sum_d(float v) {
;     v = row16_sum(v);
;     v += __builtin_bit_cast(float, __builtin_amdgcn_update_dpp(0, __builtin_bit_cast(int, v), 0x142, 0xa, 0xf, false));
;     v += __builtin_bit_cast(float, __builtin_amdgcn_update_dpp(0, __builtin_bit_cast(int, v), 0x143, 0xc, 0xf, false));
;     return __builtin_bit_cast(float, __builtin_amdgcn_readlane(__builtin_bit_cast(int, v), 63));
; }
; __device__ __forceinline__ void prep_phase(const Ctx& F, const float* mu, const float* w0, const float* a0, const float* k_k, const float* k_a, const float* r_k) {
;     ...
;             if (t + 6 < 32) { rin[t + 7] = PRL((t + 6) * PRWW); kin[t + 7] = PRL((t + 6) * PRWW + 512); vin[t + 7] = PRL((t + 6) * PRWW + 1024); }
;             asm volatile("" ::: "memory");
;             const float rc = bf2f(rin[t + 1]), kc = bf2f(kin[t + 1]), vc = bf2f(vin[t + 1]), rp = bf2f(rin[t]), kp = bf2f(kin[t]), vp = bf2f(vin[t]);
;             const float r = rc + (rp - rc) * mur, kx = kc + (kp - kc) * muk, vx = vc + (vp - vc) * muv;
;             const float ld = bf2f(outs[t * OP + c]), la = bf2f(outs[32 * OP + t * OP + c]), g = bf2f(outs[64 * OP + t * OP + c]);
;             const float een = -0.87504979f * __builtin_amdgcn_rcpf(1.f + __builtin_amdgcn_exp2f(w0n - 1.44269504f * ld));
;             const float omw = 1.f - __builtin_amdgcn_exp2f(een);
;             const float a = __builtin_amdgcn_rcpf(1.f + __builtin_amdgcn_exp2f(a0n - 1.44269504f * la));
;             const float kkv = kx * kkc; const float n2 = wave_sum_d(kkv * kkv); const float kk = kkv * __builtin_amdgcn_rsqf(fmaxf(n2, 1e-24f));
;             const float kmod = kx * (1.f + (a - 1.f) * kac); const float bb = kk * a;
;             float s_kr = kmod * r, s_bs = s_kr * rkc, s_br = bb * r;
;             wave_sum3(s_kr, s_bs, s_br, lane);
;             const float wr = (1.f - omw) * r - s_br * kk;
;             const unsigned o = ob0 + t * 128u;
;             ST16(SWR, o, f2bf(wr)); ST16(SC, o, f2bf(omw)); ST16(SK, o, f2bf(kmod)); ST16(SV, o, f2bf(vx)); ST16(SKK, o, f2bf(kk)); ST16(SB, o, f2bf(bb));
;             ST16(GG, gb0 + t * 1024u, f2bf(g));
;             if (lane == 0) *(f32x2*)(SCAL + ((size_t)bh * SEQ + pos0 + t) * 2) = (f32x2){s_kr, s_bs};
	v_fma_mix_f32 v26, v28, s31, v170 op_sel_hi:[1,0,0]
	v_add_f32_e32 v28, 1.0, v32
	v_mul_f32_e32 v32, v1, v13
	v_mul_f32_e32 v34, v32, v32
	v_exp_f32_e32 v26, v26
	v_rcp_f32_e32 v28, v28
	v_mov_b32_dpp v35, v34 quad_perm:[1,0,3,2] row_mask:0xf bank_mask:0xf
	v_fmac_f32_e32 v35, v32, v32
	v_add_f32_e32 v26, 1.0, v26
	s_nop 0
	v_add_f32_dpp v34, v35, v35 quad_perm:[2,3,0,1] row_mask:0xf bank_mask:0xf bound_ctrl:1
	s_nop 0
	s_nop 0
	v_add_f32_dpp v34, v34, v34 row_half_mirror row_mask:0xf bank_mask:0xf bound_ctrl:1
	s_nop 1
	v_add_f32_dpp v34, v34, v34 row_mirror row_mask:0xf bank_mask:0xf bound_ctrl:1
	s_nop 1
	v_add_f32_dpp v34, v34, v34 row_bcast:15 row_mask:0xa bank_mask:0xf
	s_nop 1
	v_add_f32_dpp v34, v34, v34 row_bcast:31 row_mask:0xc bank_mask:0xf
	v_rcp_f32_e32 v35, v26
	v_readlane_b32 s28, v34, 63
	v_add_f32_e32 v26, -1.0, v28
	v_fma_f32 v37, v156, v26, 1.0
	v_max_f32_e64 v34, s28, s28
	v_max_f32_e32 v34, 0x179abe15, v34
	v_rsq_f32_e32 v34, v34
	v_mul_f32_e32 v26, v13, v37
	v_mul_f32_e32 v26, v30, v26
	v_mul_f32_e32 v39, v157, v26
	v_mul_f32_e32 v36, v32, v34
	v_mul_f32_e32 v38, v28, v36
	v_mul_f32_e32 v38, v30, v38
	v_cndmask_b32_e64 v40, v38, v26, s[6:7]
	v_cndmask_b32_e64 v26, v26, v38, s[6:7]
	v_cndmask_b32_e64 v38, 0, v39, s[6:7]
	v_cndmask_b32_e64 v39, v39, 0, s[6:7]
	v_add_f32_dpp v26, v26, v40 quad_perm:[1,0,3,2] row_mask:0xf bank_mask:0xf bound_ctrl:1
	v_mul_f32_e32 v35, 0xbf600343, v35
	v_add_f32_dpp v38, v39, v38 quad_perm:[1,0,3,2] row_mask:0xf bank_mask:0xf bound_ctrl:1
	v_cndmask_b32_e64 v39, v38, v26, s[8:9]
	v_cndmask_b32_e64 v26, v26, v38, s[8:9]
	v_exp_f32_e32 v35, v35
	v_or_b32_e32 v40, 0xc80, v3
	v_add_f32_dpp v26, v26, v39 quad_perm:[2,3,0,1] row_mask:0xf bank_mask:0xf bound_ctrl:1
	v_fma_mixlo_f16 v13, v13, v37, 0
	v_sub_f32_e32 v35, 1.0, v35
	v_add_f32_dpp v26, v26, v26 row_ror:4 row_mask:0xf bank_mask:0xf bound_ctrl:1
	s_nop 1
	v_add_f32_dpp v38, v26, v26 row_ror:8 row_mask:0xf bank_mask:0xf bound_ctrl:1
	ds_bpermute_b32 v39, v4, v38
	s_waitcnt vmcnt(60)
	v_cvt_f32_f16_e32 v26, v11
	s_waitcnt lgkmcnt(0)
	v_add_f32_e32 v38, v38, v39
	ds_bpermute_b32 v39, v5, v38
	v_sub_f32_e32 v27, v27, v26
	v_fma_mixlo_f16 v11, v164, v27, v11 op_sel_hi:[0,0,1]
	s_waitcnt lgkmcnt(0)
	v_add_f32_e32 v38, v38, v39
	s_nop 0
	v_readlane_b32 s42, v38, 0
	v_readlane_b32 s28, v38, 1
	v_readlane_b32 s43, v38, 2
	v_sub_f32_e32 v38, 1.0, v35
	v_cvt_f16_f32_e32 v35, v35
	v_mul_f32_e32 v39, s28, v36
	v_fma_mixlo_f16 v30, v30, v38, -v39
	global_store_short v40, v30, s[66:67]
	global_store_short v40, v35, s[14:15]
	global_store_short v40, v11, s[18:19]
	v_fma_mixlo_f16 v11, v32, v34, 0
	global_store_short v40, v11, s[20:21]
	v_fma_mixlo_f16 v11, v28, v36, 0
	global_store_short v40, v11, s[22:23]
	v_add_u32_e32 v11, 0x6400, v2
	global_store_short v40, v13, s[16:17]
	global_store_short v11, v33, s[24:25]
	s_and_saveexec_b64 s[28:29], s[2:3]
	s_cbranch_execz .LBB0_580
	s_lshl_b64 s[44:45], s[26:27], 3
	s_add_u32 s44, s34, s44
	s_addc_u32 s45, s35, s45
	v_mov_b32_e32 v32, s42
	v_mov_b32_e32 v33, s43
	global_store_dwordx2 v139, v[32:33], s[44:45] offset:200
.LBB0_580:
	s_or_b64 exec, exec, s[28:29]
	s_waitcnt vmcnt(59)
	v_cvt_f32_f16_e32 v11, v20
	s_waitcnt vmcnt(58)
	v_cvt_f32_f16_e32 v13, v14
	ds_read_u16 v27, v214
	v_sub_f32_e32 v28, v29, v11
	ds_read_u16 v29, v176 offset:43936
	ds_read_u16 v30, v215
	v_fma_mix_f32 v28, v161, v28, v20 op_sel_hi:[0,0,1]
	v_sub_f32_e32 v20, v31, v13
	v_fma_mix_f32 v14, v160, v20, v14 op_sel_hi:[0,0,1]
	s_waitcnt lgkmcnt(1)
	v_fma_mix_f32 v20, v29, s31, v170 op_sel_hi:[1,0,0]
	v_mul_f32_e32 v29, v1, v14
	v_mul_f32_e32 v31, v29, v29
	v_mov_b32_e32 v32, 0
	v_fma_mix_f32 v27, v27, s31, v171 op_sel_hi:[1,0,0]
	v_exp_f32_e32 v20, v20
	v_mov_b32_dpp v32, v31 quad_perm:[1,0,3,2] row_mask:0xf bank_mask:0xf
	v_fmac_f32_e32 v32, v29, v29
	v_exp_f32_e32 v27, v27
	v_add_f32_e32 v20, 1.0, v20
	v_add_f32_dpp v31, v32, v32 quad_perm:[2,3,0,1] row_mask:0xf bank_mask:0xf bound_ctrl:1
	v_add_f32_e32 v27, 1.0, v27
	s_nop 0
	v_add_f32_dpp v31, v31, v31 row_half_mirror row_mask:0xf bank_mask:0xf bound_ctrl:1
	v_rcp_f32_e32 v27, v27
	s_nop 0
	v_add_f32_dpp v31, v31, v31 row_mirror row_mask:0xf bank_mask:0xf bound_ctrl:1
	s_nop 1
	v_add_f32_dpp v31, v31, v31 row_bcast:15 row_mask:0xa bank_mask:0xf
	s_nop 1
	v_add_f32_dpp v31, v31, v31 row_bcast:31 row_mask:0xc bank_mask:0xf
	v_rcp_f32_e32 v32, v20
	v_readlane_b32 s28, v31, 63
	v_add_f32_e32 v20, -1.0, v27
	v_fma_f32 v34, v156, v20, 1.0
	v_max_f32_e64 v31, s28, s28
	v_max_f32_e32 v31, 0x179abe15, v31
	v_rsq_f32_e32 v31, v31
	v_mul_f32_e32 v20, v14, v34
	v_mul_f32_e32 v20, v28, v20
	v_mul_f32_e32 v36, v157, v20
	v_mul_f32_e32 v33, v29, v31
	v_mul_f32_e32 v35, v27, v33
	v_mul_f32_e32 v35, v28, v35
	v_cndmask_b32_e64 v37, v35, v20, s[6:7]
	v_cndmask_b32_e64 v20, v20, v35, s[6:7]
	v_cndmask_b32_e64 v35, 0, v36, s[6:7]
	v_cndmask_b32_e64 v36, v36, 0, s[6:7]
	v_add_f32_dpp v20, v20, v37 quad_perm:[1,0,3,2] row_mask:0xf bank_mask:0xf bound_ctrl:1
	v_mul_f32_e32 v32, 0xbf600343, v32
	v_add_f32_dpp v35, v36, v35 quad_perm:[1,0,3,2] row_mask:0xf bank_mask:0xf bound_ctrl:1
	v_cndmask_b32_e64 v36, v35, v20, s[8:9]
	v_cndmask_b32_e64 v20, v20, v35, s[8:9]
	v_exp_f32_e32 v32, v32
	v_or_b32_e32 v37, 0xd00, v3
	v_add_f32_dpp v20, v20, v36 quad_perm:[2,3,0,1] row_mask:0xf bank_mask:0xf bound_ctrl:1
	v_fma_mixlo_f16 v14, v14, v34, 0
	v_sub_f32_e32 v32, 1.0, v32
	v_add_f32_dpp v20, v20, v20 row_ror:4 row_mask:0xf bank_mask:0xf bound_ctrl:1
	s_nop 1
	v_add_f32_dpp v35, v20, v20 row_ror:8 row_mask:0xf bank_mask:0xf bound_ctrl:1
	ds_bpermute_b32 v36, v4, v35
	s_waitcnt vmcnt(57)
	v_cvt_f32_f16_e32 v20, v12
	s_waitcnt lgkmcnt(0)
	v_add_f32_e32 v35, v35, v36
	ds_bpermute_b32 v36, v5, v35
	v_sub_f32_e32 v26, v26, v20
	v_fma_mixlo_f16 v12, v164, v26, v12 op_sel_hi:[0,0,1]
	s_waitcnt lgkmcnt(0)
	v_add_f32_e32 v35, v35, v36
	s_nop 0
	v_readlane_b32 s42, v35, 0
	v_readlane_b32 s28, v35, 1
	v_readlane_b32 s43, v35, 2
	v_sub_f32_e32 v35, 1.0, v32
	v_cvt_f16_f32_e32 v32, v32
	v_mul_f32_e32 v36, s28, v33
	v_fma_mixlo_f16 v28, v28, v35, -v36
	global_store_short v37, v28, s[66:67]
	global_store_short v37, v32, s[14:15]
	global_store_short v37, v12, s[18:19]
	v_fma_mixlo_f16 v12, v29, v31, 0
	global_store_short v37, v12, s[20:21]
	v_fma_mixlo_f16 v12, v27, v33, 0
	global_store_short v37, v12, s[22:23]
	v_add_u32_e32 v12, 0x6800, v2
	global_store_short v37, v14, s[16:17]
	global_store_short v12, v30, s[24:25]
	s_and_saveexec_b64 s[28:29], s[2:3]
	s_cbranch_execz .LBB0_582
	s_lshl_b64 s[44:45], s[26:27], 3
	s_add_u32 s44, s34, s44
	s_addc_u32 s45, s35, s45
	v_mov_b32_e32 v26, s42
	v_mov_b32_e32 v27, s43
	global_store_dwordx2 v139, v[26:27], s[44:45] offset:208
; __device__ __forceinline__ bf16 f2bf(float f) { return (bf16)(pk2(f, 0.f) & 0xffffu); }
; __device__ __forceinline__ float wave_sum_d(float v) {
;     v = row16_sum(v);
;     v += __builtin_bit_cast(float, __builtin_amdgcn_update_dpp(0, __builtin_bit_cast(int, v), 0x142, 0xa, 0xf, false));
;     v += __builtin_bit_cast(float, __builtin_amdgcn_update_dpp(0, __builtin_bit_cast(int, v), 0x143, 0xc, 0xf, false));
;     return __builtin_bit_cast(float, __builtin_amdgcn_readlane(__builtin_bit_cast(int, v), 63));
; }
; __device__ __forceinline__ void prep_phase(const Ctx& F, const float* mu, const float* w0, const float* a0, const float* k_k, const float* k_a, const float* r_k) {
;     ...
;             if (t + 6 < 32) { rin[t + 7] = PRL((t + 6) * PRWW); kin[t + 7] = PRL((t + 6) * PRWW + 512); vin[t + 7] = PRL((t + 6) * PRWW + 1024); }
;             asm volatile("" ::: "memory");
;             const float rc = bf2f(rin[t + 1]), kc = bf2f(kin[t + 1]), vc = bf2f(vin[t + 1]), rp = bf2f(rin[t]), kp = bf2f(kin[t]), vp = bf2f(vin[t]);
;             const float r = rc + (rp - rc) * mur, kx = kc + (kp - kc) * muk, vx = vc + (vp - vc) * muv;
;             const float ld = bf2f(outs[t * OP + c]), la = bf2f(outs[32 * OP + t * OP + c]), g = bf2f(outs[64 * OP + t * OP + c]);
;             const float een = -0.87504979f * __builtin_amdgcn_rcpf(1.f + __builtin_amdgcn_exp2f(w0n - 1.44269504f * ld));
;             const float omw = 1.f - __builtin_amdgcn_exp2f(een);
;             const float a = __builtin_amdgcn_rcpf(1.f + __builtin_amdgcn_exp2f(a0n - 1.44269504f * la));
;             const float kkv = kx * kkc; const float n2 = wave_sum_d(kkv * kkv); const float kk = kkv * __builtin_amdgcn_rsqf(fmaxf(n2, 1e-24f));
;             const float kmod = kx * (1.f + (a - 1.f) * kac); const float bb = kk * a;
;             float s_kr = kmod * r, s_bs = s_kr * rkc, s_br = bb * r;
;             wave_sum3(s_kr, s_bs, s_br, lane);
;             const float wr = (1.f - omw) * r - s_br * kk;
;             const unsigned o = ob0 + t * 128u;
;             ST16(SWR, o, f2bf(wr)); ST16(SC, o, f2bf(omw)); ST16(SK, o, f2bf(kmod)); ST16(SV, o, f2bf(vx)); ST16(SKK, o, f2bf(kk)); ST16(SB, o, f2bf(bb));
;             ST16(GG, gb0 + t * 1024u, f2bf(g));
;             if (lane == 0) *(f32x2*)(SCAL + ((size_t)bh * SEQ + pos0 + t) * 2) = (f32x2){s_kr, s_bs};
.LBB0_582:
	s_or_b64 exec, exec, s[28:29]
	ds_read_u16 v26, v216
	s_waitcnt vmcnt(56)
	v_cvt_f32_f16_e32 v12, v21
	s_waitcnt vmcnt(55)
	v_cvt_f32_f16_e32 v14, v19
	v_mov_b32_e32 v29, 0
	v_sub_f32_e32 v11, v11, v12
	s_waitcnt lgkmcnt(0)
	v_fma_mix_f32 v26, v26, s31, v171 op_sel_hi:[1,0,0]
	v_fma_mix_f32 v11, v161, v11, v21 op_sel_hi:[0,0,1]
	ds_read_u16 v21, v176 offset:44976
	ds_read_u16 v27, v217
	v_exp_f32_e32 v26, v26
	v_sub_f32_e32 v13, v13, v14
	v_fma_mix_f32 v19, v160, v13, v19 op_sel_hi:[0,0,1]
	s_waitcnt lgkmcnt(1)
	v_fma_mix_f32 v13, v21, s31, v170 op_sel_hi:[1,0,0]
	v_add_f32_e32 v21, 1.0, v26
	v_mul_f32_e32 v26, v1, v19
	v_mul_f32_e32 v28, v26, v26
	v_exp_f32_e32 v13, v13
	v_rcp_f32_e32 v21, v21
	v_mov_b32_dpp v29, v28 quad_perm:[1,0,3,2] row_mask:0xf bank_mask:0xf
	v_fmac_f32_e32 v29, v26, v26
	v_add_f32_e32 v13, 1.0, v13
	s_nop 0
	v_add_f32_dpp v28, v29, v29 quad_perm:[2,3,0,1] row_mask:0xf bank_mask:0xf bound_ctrl:1
	s_nop 0
	s_nop 0
	v_add_f32_dpp v28, v28, v28 row_half_mirror row_mask:0xf bank_mask:0xf bound_ctrl:1
	s_nop 1
	v_add_f32_dpp v28, v28, v28 row_mirror row_mask:0xf bank_mask:0xf bound_ctrl:1
	s_nop 1
	v_add_f32_dpp v28, v28, v28 row_bcast:15 row_mask:0xa bank_mask:0xf
	s_nop 1
	v_add_f32_dpp v28, v28, v28 row_bcast:31 row_mask:0xc bank_mask:0xf
	v_rcp_f32_e32 v29, v13
	v_readlane_b32 s28, v28, 63
	v_add_f32_e32 v13, -1.0, v21
	v_fma_f32 v31, v156, v13, 1.0
	v_max_f32_e64 v28, s28, s28
	v_max_f32_e32 v28, 0x179abe15, v28
	v_rsq_f32_e32 v28, v28
	v_mul_f32_e32 v13, v19, v31
	v_mul_f32_e32 v13, v11, v13
	v_mul_f32_e32 v33, v157, v13
	v_mul_f32_e32 v30, v26, v28
	v_mul_f32_e32 v32, v21, v30
	v_mul_f32_e32 v32, v11, v32
	v_cndmask_b32_e64 v34, v32, v13, s[6:7]
	v_cndmask_b32_e64 v13, v13, v32, s[6:7]
	v_cndmask_b32_e64 v32, 0, v33, s[6:7]
	v_cndmask_b32_e64 v33, v33, 0, s[6:7]
	v_add_f32_dpp v13, v13, v34 quad_perm:[1,0,3,2] row_mask:0xf bank_mask:0xf bound_ctrl:1
	v_mul_f32_e32 v29, 0xbf600343, v29
	v_add_f32_dpp v32, v33, v32 quad_perm:[1,0,3,2] row_mask:0xf bank_mask:0xf bound_ctrl:1
	v_cndmask_b32_e64 v33, v32, v13, s[8:9]
	v_cndmask_b32_e64 v13, v13, v32, s[8:9]
	v_exp_f32_e32 v29, v29
	v_or_b32_e32 v34, 0xd80, v3
	v_add_f32_dpp v13, v13, v33 quad_perm:[2,3,0,1] row_mask:0xf bank_mask:0xf bound_ctrl:1
	v_sub_f32_e32 v29, 1.0, v29
	s_nop 0
	v_add_f32_dpp v13, v13, v13 row_ror:4 row_mask:0xf bank_mask:0xf bound_ctrl:1
	s_nop 1
	v_add_f32_dpp v32, v13, v13 row_ror:8 row_mask:0xf bank_mask:0xf bound_ctrl:1
	ds_bpermute_b32 v33, v4, v32
	s_waitcnt vmcnt(54)
	v_cvt_f32_f16_e32 v13, v6
	s_waitcnt lgkmcnt(0)
	v_add_f32_e32 v32, v32, v33
	ds_bpermute_b32 v33, v5, v32
	v_sub_f32_e32 v20, v20, v13
	v_fma_mixlo_f16 v6, v164, v20, v6 op_sel_hi:[0,0,1]
	s_waitcnt lgkmcnt(0)
	v_add_f32_e32 v32, v32, v33
	s_nop 0
	v_readlane_b32 s42, v32, 0
	v_readlane_b32 s28, v32, 1
	v_readlane_b32 s43, v32, 2
	v_sub_f32_e32 v32, 1.0, v29
	v_cvt_f16_f32_e32 v29, v29
	v_mul_f32_e32 v33, s28, v30
	v_fma_mixlo_f16 v11, v11, v32, -v33
	global_store_short v34, v11, s[66:67]
	global_store_short v34, v29, s[14:15]
	global_store_short v34, v6, s[18:19]
	v_fma_mixlo_f16 v6, v26, v28, 0
	global_store_short v34, v6, s[20:21]
	v_fma_mixlo_f16 v6, v21, v30, 0
	v_fma_mixlo_f16 v11, v19, v31, 0
	global_store_short v34, v6, s[22:23]
	v_add_u32_e32 v6, 0x6c00, v2
	global_store_short v34, v11, s[16:17]
	global_store_short v6, v27, s[24:25]
	s_and_saveexec_b64 s[28:29], s[2:3]
	s_cbranch_execz .LBB0_584
	s_lshl_b64 s[44:45], s[26:27], 3
	s_add_u32 s44, s34, s44
	s_addc_u32 s45, s35, s45
	v_mov_b32_e32 v20, s42
	v_mov_b32_e32 v21, s43
	global_store_dwordx2 v139, v[20:21], s[44:45] offset:216
.LBB0_584:
	s_or_b64 exec, exec, s[28:29]
	s_waitcnt vmcnt(52)
	v_cvt_f32_f16_e32 v11, v15
	v_cvt_f32_f16_e32 v6, v22
	ds_read_u16 v19, v218
	ds_read_u16 v20, v176 offset:46016
	ds_read_u16 v21, v219
	v_sub_f32_e32 v14, v14, v11
	v_fma_mix_f32 v15, v160, v14, v15 op_sel_hi:[0,0,1]
	v_sub_f32_e32 v12, v12, v6
	s_waitcnt lgkmcnt(1)
	v_fma_mix_f32 v14, v20, s31, v170 op_sel_hi:[1,0,0]
	v_mul_f32_e32 v20, v1, v15
	v_fma_mix_f32 v12, v161, v12, v22 op_sel_hi:[0,0,1]
	v_mul_f32_e32 v22, v20, v20
	v_mov_b32_e32 v26, 0
	v_fma_mix_f32 v19, v19, s31, v171 op_sel_hi:[1,0,0]
	v_exp_f32_e32 v14, v14
	v_mov_b32_dpp v26, v22 quad_perm:[1,0,3,2] row_mask:0xf bank_mask:0xf
	v_fmac_f32_e32 v26, v20, v20
	v_exp_f32_e32 v19, v19
	v_add_f32_e32 v14, 1.0, v14
	v_add_f32_dpp v22, v26, v26 quad_perm:[2,3,0,1] row_mask:0xf bank_mask:0xf bound_ctrl:1
	v_add_f32_e32 v19, 1.0, v19
	s_nop 0
	v_add_f32_dpp v22, v22, v22 row_half_mirror row_mask:0xf bank_mask:0xf bound_ctrl:1
	v_rcp_f32_e32 v19, v19
	s_nop 0
	v_add_f32_dpp v22, v22, v22 row_mirror row_mask:0xf bank_mask:0xf bound_ctrl:1
	s_nop 1
	v_add_f32_dpp v22, v22, v22 row_bcast:15 row_mask:0xa bank_mask:0xf
	s_nop 1
	v_add_f32_dpp v22, v22, v22 row_bcast:31 row_mask:0xc bank_mask:0xf
	v_rcp_f32_e32 v26, v14
	v_readlane_b32 s28, v22, 63
	v_add_f32_e32 v14, -1.0, v19
	v_fma_f32 v28, v156, v14, 1.0
	v_max_f32_e64 v22, s28, s28
	v_max_f32_e32 v22, 0x179abe15, v22
	v_rsq_f32_e32 v22, v22
	v_mul_f32_e32 v14, v15, v28
	v_mul_f32_e32 v14, v12, v14
	v_mul_f32_e32 v30, v157, v14
	v_mul_f32_e32 v27, v20, v22
	v_mul_f32_e32 v29, v19, v27
	v_mul_f32_e32 v29, v12, v29
	v_cndmask_b32_e64 v31, v29, v14, s[6:7]
	v_cndmask_b32_e64 v14, v14, v29, s[6:7]
	v_cndmask_b32_e64 v29, 0, v30, s[6:7]
	v_cndmask_b32_e64 v30, v30, 0, s[6:7]
	v_add_f32_dpp v14, v14, v31 quad_perm:[1,0,3,2] row_mask:0xf bank_mask:0xf bound_ctrl:1
	v_mul_f32_e32 v26, 0xbf600343, v26
	v_add_f32_dpp v29, v30, v29 quad_perm:[1,0,3,2] row_mask:0xf bank_mask:0xf bound_ctrl:1
	v_cndmask_b32_e64 v30, v29, v14, s[8:9]
	v_cndmask_b32_e64 v14, v14, v29, s[8:9]
	v_exp_f32_e32 v26, v26
	v_or_b32_e32 v31, 0xe00, v3
	v_add_f32_dpp v14, v14, v30 quad_perm:[2,3,0,1] row_mask:0xf bank_mask:0xf bound_ctrl:1
	v_sub_f32_e32 v26, 1.0, v26
	s_nop 0
	v_add_f32_dpp v14, v14, v14 row_ror:4 row_mask:0xf bank_mask:0xf bound_ctrl:1
	s_nop 1
	v_add_f32_dpp v29, v14, v14 row_ror:8 row_mask:0xf bank_mask:0xf bound_ctrl:1
	ds_bpermute_b32 v30, v4, v29
	s_waitcnt vmcnt(51)
	v_cvt_f32_f16_e32 v14, v7
	s_waitcnt lgkmcnt(0)
	v_add_f32_e32 v29, v29, v30
	ds_bpermute_b32 v30, v5, v29
	v_sub_f32_e32 v13, v13, v14
	v_fma_mixlo_f16 v7, v164, v13, v7 op_sel_hi:[0,0,1]
	s_waitcnt lgkmcnt(0)
	v_add_f32_e32 v29, v29, v30
	s_nop 0
	v_readlane_b32 s42, v29, 0
	v_readlane_b32 s28, v29, 1
	v_readlane_b32 s43, v29, 2
	v_sub_f32_e32 v29, 1.0, v26
	v_cvt_f16_f32_e32 v26, v26
	v_mul_f32_e32 v30, s28, v27
	v_fma_mixlo_f16 v12, v12, v29, -v30
	global_store_short v31, v12, s[66:67]
	global_store_short v31, v26, s[14:15]
	global_store_short v31, v7, s[18:19]
	v_fma_mixlo_f16 v7, v20, v22, 0
	global_store_short v31, v7, s[20:21]
	v_fma_mixlo_f16 v7, v19, v27, 0
	v_fma_mixlo_f16 v12, v15, v28, 0
	global_store_short v31, v7, s[22:23]
	v_add_u32_e32 v7, 0x7000, v2
	global_store_short v31, v12, s[16:17]
	global_store_short v7, v21, s[24:25]
	s_and_saveexec_b64 s[28:29], s[2:3]
	s_cbranch_execz .LBB0_586
; __device__ __forceinline__ bf16 f2bf(float f) { return (bf16)(pk2(f, 0.f) & 0xffffu); }
; __device__ __forceinline__ float wave_sum_d(float v) {
;     v = row16_sum(v);
;     v += __builtin_bit_cast(float, __builtin_amdgcn_update_dpp(0, __builtin_bit_cast(int, v), 0x142, 0xa, 0xf, false));
;     v += __builtin_bit_cast(float, __builtin_amdgcn_update_dpp(0, __builtin_bit_cast(int, v), 0x143, 0xc, 0xf, false));
;     return __builtin_bit_cast(float, __builtin_amdgcn_readlane(__builtin_bit_cast(int, v), 63));
; }
; __device__ __forceinline__ void prep_phase(const Ctx& F, const float* mu, const float* w0, const float* a0, const float* k_k, const float* k_a, const float* r_k) {
;     ...
;             if (t + 6 < 32) { rin[t + 7] = PRL((t + 6) * PRWW); kin[t + 7] = PRL((t + 6) * PRWW + 512); vin[t + 7] = PRL((t + 6) * PRWW + 1024); }
;             asm volatile("" ::: "memory");
;             const float rc = bf2f(rin[t + 1]), kc = bf2f(kin[t + 1]), vc = bf2f(vin[t + 1]), rp = bf2f(rin[t]), kp = bf2f(kin[t]), vp = bf2f(vin[t]);
;             const float r = rc + (rp - rc) * mur, kx = kc + (kp - kc) * muk, vx = vc + (vp - vc) * muv;
;             const float ld = bf2f(outs[t * OP + c]), la = bf2f(outs[32 * OP + t * OP + c]), g = bf2f(outs[64 * OP + t * OP + c]);
;             const float een = -0.87504979f * __builtin_amdgcn_rcpf(1.f + __builtin_amdgcn_exp2f(w0n - 1.44269504f * ld));
;             const float omw = 1.f - __builtin_amdgcn_exp2f(een);
;             const float a = __builtin_amdgcn_rcpf(1.f + __builtin_amdgcn_exp2f(a0n - 1.44269504f * la));
;             const float kkv = kx * kkc; const float n2 = wave_sum_d(kkv * kkv); const float kk = kkv * __builtin_amdgcn_rsqf(fmaxf(n2, 1e-24f));
;             const float kmod = kx * (1.f + (a - 1.f) * kac); const float bb = kk * a;
;             float s_kr = kmod * r, s_bs = s_kr * rkc, s_br = bb * r;
;             wave_sum3(s_kr, s_bs, s_br, lane);
;             const float wr = (1.f - omw) * r - s_br * kk;
;             const unsigned o = ob0 + t * 128u;
;             ST16(SWR, o, f2bf(wr)); ST16(SC, o, f2bf(omw)); ST16(SK, o, f2bf(kmod)); ST16(SV, o, f2bf(vx)); ST16(SKK, o, f2bf(kk)); ST16(SB, o, f2bf(bb));
;             ST16(GG, gb0 + t * 1024u, f2bf(g));
;             if (lane == 0) *(f32x2*)(SCAL + ((size_t)bh * SEQ + pos0 + t) * 2) = (f32x2){s_kr, s_bs};
	s_lshl_b64 s[44:45], s[26:27], 3
	s_add_u32 s44, s34, s44
	s_addc_u32 s45, s35, s45
	v_mov_b32_e32 v12, s42
	v_mov_b32_e32 v13, s43
	global_store_dwordx2 v139, v[12:13], s[44:45] offset:224
.LBB0_586:
	s_or_b64 exec, exec, s[28:29]
	s_waitcnt vmcnt(49)
	v_cvt_f32_f16_e32 v12, v16
	ds_read_u16 v13, v220
	ds_read_u16 v15, v176 offset:47056
	ds_read_u16 v19, v221
	v_sub_f32_e32 v11, v11, v12
	v_fma_mix_f32 v16, v160, v11, v16 op_sel_hi:[0,0,1]
	v_mov_b32_e32 v21, 0
	s_waitcnt lgkmcnt(1)
	v_fma_mix_f32 v11, v15, s31, v170 op_sel_hi:[1,0,0]
	v_mul_f32_e32 v15, v1, v16
	v_mul_f32_e32 v20, v15, v15
	v_fma_mix_f32 v13, v13, s31, v171 op_sel_hi:[1,0,0]
	v_exp_f32_e32 v11, v11
	v_mov_b32_dpp v21, v20 quad_perm:[1,0,3,2] row_mask:0xf bank_mask:0xf
	v_fmac_f32_e32 v21, v15, v15
	v_exp_f32_e32 v13, v13
	v_cvt_f32_f16_e32 v7, v23
	v_add_f32_dpp v20, v21, v21 quad_perm:[2,3,0,1] row_mask:0xf bank_mask:0xf bound_ctrl:1
	v_add_f32_e32 v13, 1.0, v13
	s_nop 0
	v_add_f32_dpp v20, v20, v20 row_half_mirror row_mask:0xf bank_mask:0xf bound_ctrl:1
	v_rcp_f32_e32 v13, v13
	v_add_f32_e32 v11, 1.0, v11
	v_add_f32_dpp v20, v20, v20 row_mirror row_mask:0xf bank_mask:0xf bound_ctrl:1
	v_sub_f32_e32 v6, v6, v7
	v_fma_mix_f32 v6, v161, v6, v23 op_sel_hi:[0,0,1]
	v_add_f32_dpp v20, v20, v20 row_bcast:15 row_mask:0xa bank_mask:0xf
	s_nop 1
	v_add_f32_dpp v20, v20, v20 row_bcast:31 row_mask:0xc bank_mask:0xf
	v_rcp_f32_e32 v21, v11
	v_readlane_b32 s28, v20, 63
	v_add_f32_e32 v11, -1.0, v13
	v_fma_f32 v23, v156, v11, 1.0
	v_max_f32_e64 v20, s28, s28
	v_max_f32_e32 v20, 0x179abe15, v20
	v_rsq_f32_e32 v20, v20
	v_mul_f32_e32 v11, v16, v23
	v_mul_f32_e32 v11, v6, v11
	v_mul_f32_e32 v27, v157, v11
	v_mul_f32_e32 v22, v15, v20
	v_mul_f32_e32 v26, v13, v22
	v_mul_f32_e32 v26, v6, v26
	v_cndmask_b32_e64 v28, v26, v11, s[6:7]
	v_cndmask_b32_e64 v11, v11, v26, s[6:7]
	v_cndmask_b32_e64 v26, 0, v27, s[6:7]
	v_cndmask_b32_e64 v27, v27, 0, s[6:7]
	v_add_f32_dpp v11, v11, v28 quad_perm:[1,0,3,2] row_mask:0xf bank_mask:0xf bound_ctrl:1
	v_mul_f32_e32 v21, 0xbf600343, v21
	v_add_f32_dpp v26, v27, v26 quad_perm:[1,0,3,2] row_mask:0xf bank_mask:0xf bound_ctrl:1
	v_cndmask_b32_e64 v27, v26, v11, s[8:9]
	v_cndmask_b32_e64 v11, v11, v26, s[8:9]
	v_exp_f32_e32 v21, v21
	v_or_b32_e32 v28, 0xe80, v3
	v_add_f32_dpp v11, v11, v27 quad_perm:[2,3,0,1] row_mask:0xf bank_mask:0xf bound_ctrl:1
	v_sub_f32_e32 v21, 1.0, v21
	s_nop 0
	v_add_f32_dpp v11, v11, v11 row_ror:4 row_mask:0xf bank_mask:0xf bound_ctrl:1
	s_nop 1
	v_add_f32_dpp v26, v11, v11 row_ror:8 row_mask:0xf bank_mask:0xf bound_ctrl:1
	ds_bpermute_b32 v27, v4, v26
	s_waitcnt vmcnt(48)
	v_cvt_f32_f16_e32 v11, v8
	s_waitcnt lgkmcnt(0)
	v_add_f32_e32 v26, v26, v27
	ds_bpermute_b32 v27, v5, v26
	v_sub_f32_e32 v14, v14, v11
	s_waitcnt lgkmcnt(0)
	v_add_f32_e32 v26, v26, v27
	s_nop 0
	v_readlane_b32 s42, v26, 0
	v_readlane_b32 s28, v26, 1
	v_readlane_b32 s43, v26, 2
	v_sub_f32_e32 v26, 1.0, v21
	v_cvt_f16_f32_e32 v21, v21
	v_mul_f32_e32 v27, s28, v22
	v_fma_mixlo_f16 v6, v6, v26, -v27
	global_store_short v28, v6, s[66:67]
	global_store_short v28, v21, s[14:15]
	v_fma_mixlo_f16 v6, v16, v23, 0
	global_store_short v28, v6, s[16:17]
	v_fma_mixlo_f16 v6, v164, v14, v8 op_sel_hi:[0,0,1]
	global_store_short v28, v6, s[18:19]
	v_fma_mixlo_f16 v6, v15, v20, 0
	global_store_short v28, v6, s[20:21]
	v_fma_mixlo_f16 v6, v13, v22, 0
	global_store_short v28, v6, s[22:23]
	v_add_u32_e32 v6, 0x7400, v2
	global_store_short v6, v19, s[24:25]
	s_and_saveexec_b64 s[28:29], s[2:3]
	s_cbranch_execz .LBB0_588
	s_lshl_b64 s[44:45], s[26:27], 3
	s_add_u32 s44, s34, s44
	s_addc_u32 s45, s35, s45
	v_mov_b32_e32 v14, s42
	v_mov_b32_e32 v15, s43
	global_store_dwordx2 v139, v[14:15], s[44:45] offset:232
.LBB0_588:
	s_or_b64 exec, exec, s[28:29]
	ds_read_u16 v13, v222
	s_waitcnt vmcnt(47)
	v_cvt_f32_f16_e32 v6, v24
	s_waitcnt vmcnt(46)
	v_cvt_f32_f16_e32 v8, v17
	v_mov_b32_e32 v19, 0
	v_sub_f32_e32 v7, v7, v6
	s_waitcnt lgkmcnt(0)
	v_fma_mix_f32 v13, v13, s31, v171 op_sel_hi:[1,0,0]
	v_fma_mix_f32 v14, v161, v7, v24 op_sel_hi:[0,0,1]
	v_sub_f32_e32 v7, v12, v8
	ds_read_u16 v12, v176 offset:48096
	ds_read_u16 v15, v223
	v_exp_f32_e32 v13, v13
	v_fma_mix_f32 v16, v160, v7, v17 op_sel_hi:[0,0,1]
	s_waitcnt lgkmcnt(1)
	v_fma_mix_f32 v7, v12, s31, v170 op_sel_hi:[1,0,0]
	v_add_f32_e32 v12, 1.0, v13
	v_mul_f32_e32 v13, v1, v16
	v_mul_f32_e32 v17, v13, v13
	v_exp_f32_e32 v7, v7
	v_rcp_f32_e32 v12, v12
	v_mov_b32_dpp v19, v17 quad_perm:[1,0,3,2] row_mask:0xf bank_mask:0xf
	v_fmac_f32_e32 v19, v13, v13
	v_add_f32_e32 v7, 1.0, v7
	s_nop 0
	v_add_f32_dpp v17, v19, v19 quad_perm:[2,3,0,1] row_mask:0xf bank_mask:0xf bound_ctrl:1
	s_nop 0
	s_nop 0
	v_add_f32_dpp v17, v17, v17 row_half_mirror row_mask:0xf bank_mask:0xf bound_ctrl:1
	s_nop 1
	v_add_f32_dpp v17, v17, v17 row_mirror row_mask:0xf bank_mask:0xf bound_ctrl:1
	s_nop 1
	v_add_f32_dpp v17, v17, v17 row_bcast:15 row_mask:0xa bank_mask:0xf
	s_nop 1
	v_add_f32_dpp v17, v17, v17 row_bcast:31 row_mask:0xc bank_mask:0xf
	v_rcp_f32_e32 v19, v7
	v_readlane_b32 s28, v17, 63
	v_add_f32_e32 v7, -1.0, v12
	v_fma_f32 v21, v156, v7, 1.0
	v_max_f32_e64 v17, s28, s28
	v_max_f32_e32 v17, 0x179abe15, v17
	v_rsq_f32_e32 v17, v17
	v_mul_f32_e32 v7, v16, v21
	v_mul_f32_e32 v7, v14, v7
	v_mul_f32_e32 v23, v157, v7
	v_mul_f32_e32 v20, v13, v17
	v_mul_f32_e32 v22, v12, v20
	v_mul_f32_e32 v22, v14, v22
	v_cndmask_b32_e64 v24, v22, v7, s[6:7]
	v_cndmask_b32_e64 v7, v7, v22, s[6:7]
	v_cndmask_b32_e64 v22, 0, v23, s[6:7]
	v_cndmask_b32_e64 v23, v23, 0, s[6:7]
	v_add_f32_dpp v7, v7, v24 quad_perm:[1,0,3,2] row_mask:0xf bank_mask:0xf bound_ctrl:1
	v_mul_f32_e32 v19, 0xbf600343, v19
	v_add_f32_dpp v22, v23, v22 quad_perm:[1,0,3,2] row_mask:0xf bank_mask:0xf bound_ctrl:1
	v_cndmask_b32_e64 v23, v22, v7, s[8:9]
	v_cndmask_b32_e64 v7, v7, v22, s[8:9]
	v_exp_f32_e32 v19, v19
	v_or_b32_e32 v24, 0xf00, v3
	v_add_f32_dpp v7, v7, v23 quad_perm:[2,3,0,1] row_mask:0xf bank_mask:0xf bound_ctrl:1
	v_sub_f32_e32 v19, 1.0, v19
	s_nop 0
	v_add_f32_dpp v7, v7, v7 row_ror:4 row_mask:0xf bank_mask:0xf bound_ctrl:1
	s_nop 1
	v_add_f32_dpp v22, v7, v7 row_ror:8 row_mask:0xf bank_mask:0xf bound_ctrl:1
	ds_bpermute_b32 v23, v4, v22
	s_waitcnt vmcnt(45)
; __device__ __forceinline__ bf16 f2bf(float f) { return (bf16)(pk2(f, 0.f) & 0xffffu); }
; __device__ __forceinline__ float wave_sum_d(float v) {
;     v = row16_sum(v);
;     v += __builtin_bit_cast(float, __builtin_amdgcn_update_dpp(0, __builtin_bit_cast(int, v), 0x142, 0xa, 0xf, false));
;     v += __builtin_bit_cast(float, __builtin_amdgcn_update_dpp(0, __builtin_bit_cast(int, v), 0x143, 0xc, 0xf, false));
;     return __builtin_bit_cast(float, __builtin_amdgcn_readlane(__builtin_bit_cast(int, v), 63));
; }
; __device__ __forceinline__ void prep_phase(const Ctx& F, const float* mu, const float* w0, const float* a0, const float* k_k, const float* k_a, const float* r_k) {
;     ...
;             if (t + 6 < 32) { rin[t + 7] = PRL((t + 6) * PRWW); kin[t + 7] = PRL((t + 6) * PRWW + 512); vin[t + 7] = PRL((t + 6) * PRWW + 1024); }
;             asm volatile("" ::: "memory");
;             const float rc = bf2f(rin[t + 1]), kc = bf2f(kin[t + 1]), vc = bf2f(vin[t + 1]), rp = bf2f(rin[t]), kp = bf2f(kin[t]), vp = bf2f(vin[t]);
;             const float r = rc + (rp - rc) * mur, kx = kc + (kp - kc) * muk, vx = vc + (vp - vc) * muv;
;             const float ld = bf2f(outs[t * OP + c]), la = bf2f(outs[32 * OP + t * OP + c]), g = bf2f(outs[64 * OP + t * OP + c]);
;             const float een = -0.87504979f * __builtin_amdgcn_rcpf(1.f + __builtin_amdgcn_exp2f(w0n - 1.44269504f * ld));
;             const float omw = 1.f - __builtin_amdgcn_exp2f(een);
;             const float a = __builtin_amdgcn_rcpf(1.f + __builtin_amdgcn_exp2f(a0n - 1.44269504f * la));
;             const float kkv = kx * kkc; const float n2 = wave_sum_d(kkv * kkv); const float kk = kkv * __builtin_amdgcn_rsqf(fmaxf(n2, 1e-24f));
;             const float kmod = kx * (1.f + (a - 1.f) * kac); const float bb = kk * a;
;             float s_kr = kmod * r, s_bs = s_kr * rkc, s_br = bb * r;
;             wave_sum3(s_kr, s_bs, s_br, lane);
;             const float wr = (1.f - omw) * r - s_br * kk;
;             const unsigned o = ob0 + t * 128u;
;             ST16(SWR, o, f2bf(wr)); ST16(SC, o, f2bf(omw)); ST16(SK, o, f2bf(kmod)); ST16(SV, o, f2bf(vx)); ST16(SKK, o, f2bf(kk)); ST16(SB, o, f2bf(bb));
;             ST16(GG, gb0 + t * 1024u, f2bf(g));
;             if (lane == 0) *(f32x2*)(SCAL + ((size_t)bh * SEQ + pos0 + t) * 2) = (f32x2){s_kr, s_bs};
	v_cvt_f32_f16_e32 v7, v9
	s_waitcnt lgkmcnt(0)
	v_add_f32_e32 v22, v22, v23
	ds_bpermute_b32 v23, v5, v22
	v_sub_f32_e32 v11, v11, v7
	v_fma_mixlo_f16 v9, v164, v11, v9 op_sel_hi:[0,0,1]
	s_waitcnt lgkmcnt(0)
	v_add_f32_e32 v22, v22, v23
	s_nop 0
	v_readlane_b32 s42, v22, 0
	v_readlane_b32 s28, v22, 1
	v_readlane_b32 s43, v22, 2
	v_sub_f32_e32 v22, 1.0, v19
	v_cvt_f16_f32_e32 v19, v19
	v_mul_f32_e32 v23, s28, v20
	v_fma_mixlo_f16 v14, v14, v22, -v23
	global_store_short v24, v14, s[66:67]
	global_store_short v24, v19, s[14:15]
	global_store_short v24, v9, s[18:19]
	v_fma_mixlo_f16 v9, v13, v17, 0
	global_store_short v24, v9, s[20:21]
	v_fma_mixlo_f16 v9, v12, v20, 0
	v_fma_mixlo_f16 v14, v16, v21, 0
	global_store_short v24, v9, s[22:23]
	v_add_u32_e32 v9, 0x7800, v2
	global_store_short v24, v14, s[16:17]
	global_store_short v9, v15, s[24:25]
	s_and_saveexec_b64 s[28:29], s[2:3]
	s_cbranch_execz .LBB0_590
	s_lshl_b64 s[44:45], s[26:27], 3
	s_add_u32 s44, s34, s44
	s_addc_u32 s45, s35, s45
	v_mov_b32_e32 v12, s42
	v_mov_b32_e32 v13, s43
	global_store_dwordx2 v139, v[12:13], s[44:45] offset:240
.LBB0_590:
	s_or_b64 exec, exec, s[28:29]
	s_waitcnt vmcnt(43)
	v_cvt_f32_f16_e32 v11, v18
	ds_read_u16 v12, v224
	v_mov_b32_e32 v15, 0
	v_sub_f32_e32 v8, v8, v11
	v_fma_mix_f32 v8, v160, v8, v18 op_sel_hi:[0,0,1]
	v_mul_f32_e32 v13, v1, v8
	v_mul_f32_e32 v14, v13, v13
	s_waitcnt lgkmcnt(0)
	v_fma_mix_f32 v12, v12, s31, v171 op_sel_hi:[1,0,0]
	v_cvt_f32_f16_e32 v9, v25
	v_mov_b32_dpp v15, v14 quad_perm:[1,0,3,2] row_mask:0xf bank_mask:0xf
	v_fmac_f32_e32 v15, v13, v13
	v_exp_f32_e32 v12, v12
	v_sub_f32_e32 v6, v6, v9
	v_add_f32_dpp v14, v15, v15 quad_perm:[2,3,0,1] row_mask:0xf bank_mask:0xf bound_ctrl:1
	v_add_f32_e32 v12, 1.0, v12
	s_nop 0
	v_add_f32_dpp v14, v14, v14 row_half_mirror row_mask:0xf bank_mask:0xf bound_ctrl:1
	v_rcp_f32_e32 v12, v12
	v_fma_mix_f32 v6, v161, v6, v25 op_sel_hi:[0,0,1]
	v_add_f32_dpp v14, v14, v14 row_mirror row_mask:0xf bank_mask:0xf bound_ctrl:1
	ds_read_u16 v9, v176 offset:49136
	ds_read_u16 v11, v225
	v_add_f32_dpp v14, v14, v14 row_bcast:15 row_mask:0xa bank_mask:0xf
	v_add_f32_e32 v16, -1.0, v12
	v_fma_f32 v16, v156, v16, 1.0
	v_add_f32_dpp v14, v14, v14 row_bcast:31 row_mask:0xc bank_mask:0xf
	v_mul_f32_e32 v17, v8, v16
	v_readlane_b32 s28, v14, 63
	v_mul_f32_e32 v17, v6, v17
	v_mul_f32_e32 v19, v157, v17
	v_max_f32_e64 v14, s28, s28
	v_max_f32_e32 v14, 0x179abe15, v14
	v_rsq_f32_e32 v14, v14
	s_waitcnt lgkmcnt(1)
	v_fma_mix_f32 v9, v9, s31, v170 op_sel_hi:[1,0,0]
	v_or_b32_e32 v3, 0xf80, v3
	v_exp_f32_e32 v9, v9
	v_mul_f32_e32 v15, v13, v14
	v_mul_f32_e32 v18, v12, v15
	v_mul_f32_e32 v18, v6, v18
	v_cndmask_b32_e64 v20, v18, v17, s[6:7]
	v_cndmask_b32_e64 v17, v17, v18, s[6:7]
	v_cndmask_b32_e64 v18, 0, v19, s[6:7]
	v_cndmask_b32_e64 v19, v19, 0, s[6:7]
	v_add_f32_dpp v17, v17, v20 quad_perm:[1,0,3,2] row_mask:0xf bank_mask:0xf bound_ctrl:1
	v_add_f32_e32 v9, 1.0, v9
	v_add_f32_dpp v18, v19, v18 quad_perm:[1,0,3,2] row_mask:0xf bank_mask:0xf bound_ctrl:1
	v_cndmask_b32_e64 v19, v18, v17, s[8:9]
	v_cndmask_b32_e64 v17, v17, v18, s[8:9]
	v_rcp_f32_e32 v9, v9
	s_waitcnt vmcnt(42)
	v_cvt_f32_f16_e32 v18, v10
	v_add_f32_dpp v17, v17, v19 quad_perm:[2,3,0,1] row_mask:0xf bank_mask:0xf bound_ctrl:1
	v_add_u32_e32 v2, 0x7c00, v2
	v_mul_f32_e32 v9, 0xbf600343, v9
	v_add_f32_dpp v17, v17, v17 row_ror:4 row_mask:0xf bank_mask:0xf bound_ctrl:1
	v_exp_f32_e32 v9, v9
	v_sub_f32_e32 v7, v7, v18
	v_add_f32_dpp v17, v17, v17 row_ror:8 row_mask:0xf bank_mask:0xf bound_ctrl:1
	ds_bpermute_b32 v4, v4, v17
	v_sub_f32_e32 v9, 1.0, v9
	s_waitcnt lgkmcnt(0)
	v_add_f32_e32 v4, v17, v4
	ds_bpermute_b32 v5, v5, v4
	s_waitcnt lgkmcnt(0)
	v_add_f32_e32 v4, v4, v5
	s_nop 0
	v_readlane_b32 s42, v4, 0
	v_readlane_b32 s28, v4, 1
	v_readlane_b32 s43, v4, 2
	v_sub_f32_e32 v4, 1.0, v9
	v_cvt_f16_f32_e32 v9, v9
	v_mul_f32_e32 v5, s28, v15
	v_fma_mixlo_f16 v4, v6, v4, -v5
	global_store_short v3, v4, s[66:67]
	global_store_short v3, v9, s[14:15]
	v_fma_mixlo_f16 v4, v8, v16, 0
	global_store_short v3, v4, s[16:17]
	v_fma_mixlo_f16 v4, v164, v7, v10 op_sel_hi:[0,0,1]
	global_store_short v3, v4, s[18:19]
	v_fma_mixlo_f16 v4, v13, v14, 0
	global_store_short v3, v4, s[20:21]
	v_fma_mixlo_f16 v4, v12, v15, 0
	global_store_short v3, v4, s[22:23]
	global_store_short v2, v11, s[24:25]
	s_and_saveexec_b64 s[28:29], s[2:3]
	s_cbranch_execz .LBB0_518
	s_lshl_b64 s[26:27], s[26:27], 3
	s_add_u32 s26, s34, s26
	s_addc_u32 s27, s35, s27
	v_mov_b32_e32 v2, s42
	v_mov_b32_e32 v3, s43
	global_store_dwordx2 v139, v[2:3], s[26:27] offset:248
	s_branch .LBB0_518
